# vm10: K-loop DMA waits moved to just before each reading phase (vmcnt(10) in 6 load segments instead of vmcnt(6) in 2), all main GEMM loops; on top of lorak
# baseline (speedup 1.0000x reference)
.LBB0_162:
	ds_read_b128 v[150:153], v147
	ds_read_b128 v[154:157], v147 offset:1024
	ds_read_b128 v[158:161], v147 offset:2048
	ds_read_b128 v[162:165], v147 offset:3072
	s_add_u32 s18, s16, 0xfff80080
	s_addc_u32 s19, s17, -1
	s_cmp_eq_u32 s43, 28
	s_cselect_b32 s21, s11, s19
	s_cselect_b32 s20, s39, s18
	s_cselect_b32 s19, s9, s42
	s_cselect_b32 s18, s40, s41
	v_lshl_add_u64 v[200:201], s[16:17], 0, v[136:137]
	s_add_i32 m0, s7, 0xc000
	ds_read_b128 v[166:169], v148
	ds_read_b128 v[172:175], v148 offset:1024
	ds_read_b128 v[176:179], v148 offset:2048
	ds_read_b128 v[180:183], v148 offset:3072
	ds_read_b128 v[184:187], v148 offset:4096
	ds_read_b128 v[188:191], v148 offset:5120
	ds_read_b128 v[192:195], v148 offset:6144
	ds_read_b128 v[196:199], v148 offset:7168
	global_load_lds_dwordx4 v[200:201], off
	v_lshl_add_u64 v[200:201], s[16:17], 0, v[138:139]
	s_add_i32 m0, s7, 0xe000
	s_nop 0
	global_load_lds_dwordx4 v[200:201], off
	s_waitcnt vmcnt(10)
	s_waitcnt lgkmcnt(8)
	s_barrier
	s_waitcnt lgkmcnt(0)
	s_setprio 1
	s_waitcnt lgkmcnt(0)
	v_mfma_f32_16x16x32_bf16 v[124:127], v[150:153], v[166:169], v[124:127]
	v_mfma_f32_16x16x32_bf16 v[120:123], v[158:161], v[166:169], v[120:123]
	v_mfma_f32_16x16x32_bf16 v[116:119], v[150:153], v[176:179], v[116:119]
	v_mfma_f32_16x16x32_bf16 v[112:115], v[158:161], v[176:179], v[112:115]
	v_mfma_f32_16x16x32_bf16 v[100:103], v[150:153], v[184:187], v[100:103]
	v_mfma_f32_16x16x32_bf16 v[96:99], v[158:161], v[184:187], v[96:99]
	v_mfma_f32_16x16x32_bf16 v[84:87], v[150:153], v[192:195], v[84:87]
	v_mfma_f32_16x16x32_bf16 v[80:83], v[158:161], v[192:195], v[80:83]
	v_mfma_f32_16x16x32_bf16 v[124:127], v[154:157], v[172:175], v[124:127]
	v_mfma_f32_16x16x32_bf16 v[120:123], v[162:165], v[172:175], v[120:123]
	v_mfma_f32_16x16x32_bf16 v[116:119], v[154:157], v[180:183], v[116:119]
	v_mfma_f32_16x16x32_bf16 v[112:115], v[162:165], v[180:183], v[112:115]
	v_mfma_f32_16x16x32_bf16 v[100:103], v[154:157], v[188:191], v[100:103]
	v_mfma_f32_16x16x32_bf16 v[96:99], v[162:165], v[188:191], v[96:99]
	v_mfma_f32_16x16x32_bf16 v[84:87], v[154:157], v[196:199], v[84:87]
	v_mfma_f32_16x16x32_bf16 v[80:83], v[162:165], v[196:199], v[80:83]
	s_setprio 0
	s_barrier
	s_add_i32 s44, s35, s23
	v_lshl_add_u64 v[216:217], s[18:19], 0, v[130:131]
	s_mov_b32 m0, s44
	ds_read_b128 v[200:203], v149
	ds_read_b128 v[204:207], v149 offset:1024
	ds_read_b128 v[208:211], v149 offset:2048
	ds_read_b128 v[212:215], v149 offset:3072
	global_load_lds_dwordx4 v[216:217], off
	v_lshl_add_u64 v[218:219], s[18:19], 0, v[134:135]
	s_add_i32 m0, s44, 0x2000
	s_nop 0
	global_load_lds_dwordx4 v[218:219], off
	s_waitcnt vmcnt(10)
	s_barrier
	s_waitcnt lgkmcnt(0)
	s_setprio 1
	s_waitcnt lgkmcnt(0)
	v_mfma_f32_16x16x32_bf16 v[108:111], v[200:203], v[166:169], v[108:111]
	v_mfma_f32_16x16x32_bf16 v[104:107], v[208:211], v[166:169], v[104:107]
	v_mfma_f32_16x16x32_bf16 v[92:95], v[200:203], v[176:179], v[92:95]
	v_mfma_f32_16x16x32_bf16 v[88:91], v[208:211], v[176:179], v[88:91]
	v_mfma_f32_16x16x32_bf16 v[76:79], v[200:203], v[184:187], v[76:79]
	v_mfma_f32_16x16x32_bf16 v[72:75], v[208:211], v[184:187], v[72:75]
	v_mfma_f32_16x16x32_bf16 v[68:71], v[200:203], v[192:195], v[68:71]
	v_mfma_f32_16x16x32_bf16 v[64:67], v[208:211], v[192:195], v[64:67]
	v_mfma_f32_16x16x32_bf16 v[108:111], v[204:207], v[172:175], v[108:111]
	v_mfma_f32_16x16x32_bf16 v[104:107], v[212:215], v[172:175], v[104:107]
	v_mfma_f32_16x16x32_bf16 v[92:95], v[204:207], v[180:183], v[92:95]
	v_mfma_f32_16x16x32_bf16 v[88:91], v[212:215], v[180:183], v[88:91]
	v_mfma_f32_16x16x32_bf16 v[76:79], v[204:207], v[188:191], v[76:79]
	v_mfma_f32_16x16x32_bf16 v[72:75], v[212:215], v[188:191], v[72:75]
	v_mfma_f32_16x16x32_bf16 v[68:71], v[204:207], v[196:199], v[68:71]
	v_mfma_f32_16x16x32_bf16 v[64:67], v[212:215], v[196:199], v[64:67]
	s_setprio 0
	s_mov_b32 m0, s7
	v_lshl_add_u64 v[220:221], s[20:21], 0, v[128:129]
	s_barrier
	ds_read_b128 v[166:169], v148 offset:16384
	ds_read_b128 v[172:175], v148 offset:17408
	ds_read_b128 v[176:179], v148 offset:18432
	ds_read_b128 v[180:183], v148 offset:19456
	ds_read_b128 v[184:187], v148 offset:20480
	ds_read_b128 v[188:191], v148 offset:21504
	ds_read_b128 v[192:195], v148 offset:22528
	ds_read_b128 v[196:199], v148 offset:23552
	global_load_lds_dwordx4 v[220:221], off
	v_lshl_add_u64 v[222:223], s[20:21], 0, v[132:133]
	s_mov_b32 m0, s26
	s_nop 0
	global_load_lds_dwordx4 v[222:223], off
	s_barrier
	s_waitcnt lgkmcnt(0)
	s_setprio 1
	s_waitcnt lgkmcnt(0)
	v_mfma_f32_16x16x32_bf16 v[60:63], v[150:153], v[166:169], v[60:63]
	v_mfma_f32_16x16x32_bf16 v[56:59], v[158:161], v[166:169], v[56:59]
	v_mfma_f32_16x16x32_bf16 v[52:55], v[150:153], v[176:179], v[52:55]
	v_mfma_f32_16x16x32_bf16 v[48:51], v[158:161], v[176:179], v[48:51]
	v_mfma_f32_16x16x32_bf16 v[36:39], v[150:153], v[184:187], v[36:39]
	v_mfma_f32_16x16x32_bf16 v[32:35], v[158:161], v[184:187], v[32:35]
	v_mfma_f32_16x16x32_bf16 v[20:23], v[150:153], v[192:195], v[20:23]
	v_mfma_f32_16x16x32_bf16 v[16:19], v[158:161], v[192:195], v[16:19]
	v_mfma_f32_16x16x32_bf16 v[60:63], v[154:157], v[172:175], v[60:63]
	v_mfma_f32_16x16x32_bf16 v[56:59], v[162:165], v[172:175], v[56:59]
	v_mfma_f32_16x16x32_bf16 v[52:55], v[154:157], v[180:183], v[52:55]
	v_mfma_f32_16x16x32_bf16 v[48:51], v[162:165], v[180:183], v[48:51]
	v_mfma_f32_16x16x32_bf16 v[36:39], v[154:157], v[188:191], v[36:39]
	v_mfma_f32_16x16x32_bf16 v[32:35], v[162:165], v[188:191], v[32:35]
	v_mfma_f32_16x16x32_bf16 v[20:23], v[154:157], v[196:199], v[20:23]
	v_mfma_f32_16x16x32_bf16 v[16:19], v[162:165], v[196:199], v[16:19]
	s_setprio 0
	s_barrier
	s_add_u32 s44, s18, 0x80000
	s_addc_u32 s45, s19, 0
	s_add_i32 s46, s36, s23
	v_lshl_add_u64 v[150:151], s[44:45], 0, v[130:131]
	s_mov_b32 m0, s46
	s_nop 0
	global_load_lds_dwordx4 v[150:151], off
	v_lshl_add_u64 v[150:151], s[44:45], 0, v[134:135]
	s_add_i32 m0, s46, 0x2000
	s_nop 0
	global_load_lds_dwordx4 v[150:151], off
	s_waitcnt vmcnt(10)
	s_barrier
	s_setprio 1
	v_mfma_f32_16x16x32_bf16 v[44:47], v[200:203], v[166:169], v[44:47]
	v_mfma_f32_16x16x32_bf16 v[40:43], v[208:211], v[166:169], v[40:43]
	v_mfma_f32_16x16x32_bf16 v[28:31], v[200:203], v[176:179], v[28:31]
	v_mfma_f32_16x16x32_bf16 v[24:27], v[208:211], v[176:179], v[24:27]
	v_mfma_f32_16x16x32_bf16 v[12:15], v[200:203], v[184:187], v[12:15]
	v_mfma_f32_16x16x32_bf16 v[8:11], v[208:211], v[184:187], v[8:11]
	v_mfma_f32_16x16x32_bf16 v[4:7], v[200:203], v[192:195], v[4:7]
	v_mfma_f32_16x16x32_bf16 v[0:3], v[208:211], v[192:195], v[0:3]
	v_mfma_f32_16x16x32_bf16 v[44:47], v[204:207], v[172:175], v[44:47]
	v_mfma_f32_16x16x32_bf16 v[40:43], v[212:215], v[172:175], v[40:43]
	v_mfma_f32_16x16x32_bf16 v[28:31], v[204:207], v[180:183], v[28:31]
	v_mfma_f32_16x16x32_bf16 v[24:27], v[212:215], v[180:183], v[24:27]
	v_mfma_f32_16x16x32_bf16 v[12:15], v[204:207], v[188:191], v[12:15]
	v_mfma_f32_16x16x32_bf16 v[8:11], v[212:215], v[188:191], v[8:11]
	v_mfma_f32_16x16x32_bf16 v[4:7], v[204:207], v[196:199], v[4:7]
	v_mfma_f32_16x16x32_bf16 v[0:3], v[212:215], v[196:199], v[0:3]
	s_setprio 0
	s_add_i32 s44, 0, 0x18000
	v_add_u32_e32 v162, s44, v145
	s_barrier
	ds_read_b128 v[150:153], v162
	ds_read_b128 v[154:157], v162 offset:1024
	ds_read_b128 v[158:161], v162 offset:2048
	ds_read_b128 v[162:165], v162 offset:3072
	s_add_u32 s20, s20, 0x80000
	s_addc_u32 s21, s21, 0
	s_mov_b32 m0, s27
	v_lshl_add_u64 v[200:201], s[20:21], 0, v[128:129]
	ds_read_b128 v[166:169], v148 offset:32768
	ds_read_b128 v[172:175], v148 offset:33792
	ds_read_b128 v[176:179], v148 offset:34816
	ds_read_b128 v[180:183], v148 offset:35840
	ds_read_b128 v[184:187], v148 offset:36864
	ds_read_b128 v[188:191], v148 offset:37888
	ds_read_b128 v[192:195], v148 offset:38912
	ds_read_b128 v[196:199], v148 offset:39936
	global_load_lds_dwordx4 v[200:201], off
	v_lshl_add_u64 v[200:201], s[20:21], 0, v[132:133]
	s_mov_b32 m0, s28
	s_nop 0
	global_load_lds_dwordx4 v[200:201], off
	s_waitcnt vmcnt(10)
	s_waitcnt lgkmcnt(8)
	s_barrier
	s_waitcnt lgkmcnt(0)
	s_setprio 1
	s_waitcnt lgkmcnt(0)
	v_mfma_f32_16x16x32_bf16 v[124:127], v[150:153], v[166:169], v[124:127]
	v_mfma_f32_16x16x32_bf16 v[120:123], v[158:161], v[166:169], v[120:123]
	v_mfma_f32_16x16x32_bf16 v[116:119], v[150:153], v[176:179], v[116:119]
	v_mfma_f32_16x16x32_bf16 v[112:115], v[158:161], v[176:179], v[112:115]
	v_mfma_f32_16x16x32_bf16 v[100:103], v[150:153], v[184:187], v[100:103]
	v_mfma_f32_16x16x32_bf16 v[96:99], v[158:161], v[184:187], v[96:99]
	v_mfma_f32_16x16x32_bf16 v[84:87], v[150:153], v[192:195], v[84:87]
	v_mfma_f32_16x16x32_bf16 v[80:83], v[158:161], v[192:195], v[80:83]
	v_mfma_f32_16x16x32_bf16 v[124:127], v[154:157], v[172:175], v[124:127]
	v_mfma_f32_16x16x32_bf16 v[120:123], v[162:165], v[172:175], v[120:123]
	v_mfma_f32_16x16x32_bf16 v[116:119], v[154:157], v[180:183], v[116:119]
	v_mfma_f32_16x16x32_bf16 v[112:115], v[162:165], v[180:183], v[112:115]
	v_mfma_f32_16x16x32_bf16 v[100:103], v[154:157], v[188:191], v[100:103]
	v_mfma_f32_16x16x32_bf16 v[96:99], v[162:165], v[188:191], v[96:99]
	v_mfma_f32_16x16x32_bf16 v[84:87], v[154:157], v[196:199], v[84:87]
	v_mfma_f32_16x16x32_bf16 v[80:83], v[162:165], v[196:199], v[80:83]
	s_setprio 0
	s_barrier
	s_add_i32 s20, 0, 0x1c000
	s_add_i32 s21, s44, s23
	v_add_u32_e32 v171, s20, v145
	v_lshl_add_u64 v[216:217], v[216:217], 0, s[4:5]
	s_mov_b32 m0, s21
	ds_read_b128 v[200:203], v171
	ds_read_b128 v[204:207], v171 offset:1024
	ds_read_b128 v[208:211], v171 offset:2048
	ds_read_b128 v[212:215], v171 offset:3072
	global_load_lds_dwordx4 v[216:217], off
	v_lshl_add_u64 v[216:217], v[218:219], 0, s[4:5]
	s_add_i32 m0, s21, 0x2000
	s_nop 0
	global_load_lds_dwordx4 v[216:217], off
	s_waitcnt vmcnt(10)
	s_barrier
	s_waitcnt lgkmcnt(0)
	s_setprio 1
	s_waitcnt lgkmcnt(0)
	v_mfma_f32_16x16x32_bf16 v[108:111], v[200:203], v[166:169], v[108:111]
	v_mfma_f32_16x16x32_bf16 v[104:107], v[208:211], v[166:169], v[104:107]
	v_mfma_f32_16x16x32_bf16 v[92:95], v[200:203], v[176:179], v[92:95]
	v_mfma_f32_16x16x32_bf16 v[88:91], v[208:211], v[176:179], v[88:91]
	v_mfma_f32_16x16x32_bf16 v[76:79], v[200:203], v[184:187], v[76:79]
	v_mfma_f32_16x16x32_bf16 v[72:75], v[208:211], v[184:187], v[72:75]
	v_mfma_f32_16x16x32_bf16 v[68:71], v[200:203], v[192:195], v[68:71]
	v_mfma_f32_16x16x32_bf16 v[64:67], v[208:211], v[192:195], v[64:67]
	v_mfma_f32_16x16x32_bf16 v[108:111], v[204:207], v[172:175], v[108:111]
	v_mfma_f32_16x16x32_bf16 v[104:107], v[212:215], v[172:175], v[104:107]
	v_mfma_f32_16x16x32_bf16 v[92:95], v[204:207], v[180:183], v[92:95]
	v_mfma_f32_16x16x32_bf16 v[88:91], v[212:215], v[180:183], v[88:91]
	v_mfma_f32_16x16x32_bf16 v[76:79], v[204:207], v[188:191], v[76:79]
	v_mfma_f32_16x16x32_bf16 v[72:75], v[212:215], v[188:191], v[72:75]
	v_mfma_f32_16x16x32_bf16 v[68:71], v[204:207], v[196:199], v[68:71]
	v_mfma_f32_16x16x32_bf16 v[64:67], v[212:215], v[196:199], v[64:67]
	s_setprio 0
	s_mov_b32 m0, s31
	v_lshl_add_u64 v[216:217], v[220:221], 0, s[4:5]
	s_barrier
	ds_read_b128 v[166:169], v148 offset:49152
	ds_read_b128 v[172:175], v148 offset:50176
	ds_read_b128 v[176:179], v148 offset:51200
	ds_read_b128 v[180:183], v148 offset:52224
	ds_read_b128 v[184:187], v148 offset:53248
	ds_read_b128 v[188:191], v148 offset:54272
	ds_read_b128 v[192:195], v148 offset:55296
	ds_read_b128 v[196:199], v148 offset:56320
	global_load_lds_dwordx4 v[216:217], off
	v_lshl_add_u64 v[216:217], v[222:223], 0, s[4:5]
	s_mov_b32 m0, s33
	s_nop 0
	global_load_lds_dwordx4 v[216:217], off
	s_barrier
	s_waitcnt lgkmcnt(0)
	s_setprio 1
	s_waitcnt lgkmcnt(0)
	v_mfma_f32_16x16x32_bf16 v[60:63], v[150:153], v[166:169], v[60:63]
	v_mfma_f32_16x16x32_bf16 v[56:59], v[158:161], v[166:169], v[56:59]
	v_mfma_f32_16x16x32_bf16 v[52:55], v[150:153], v[176:179], v[52:55]
	v_mfma_f32_16x16x32_bf16 v[48:51], v[158:161], v[176:179], v[48:51]
	v_mfma_f32_16x16x32_bf16 v[36:39], v[150:153], v[184:187], v[36:39]
	v_mfma_f32_16x16x32_bf16 v[32:35], v[158:161], v[184:187], v[32:35]
	v_mfma_f32_16x16x32_bf16 v[20:23], v[150:153], v[192:195], v[20:23]
	v_mfma_f32_16x16x32_bf16 v[16:19], v[158:161], v[192:195], v[16:19]
	v_mfma_f32_16x16x32_bf16 v[60:63], v[154:157], v[172:175], v[60:63]
	v_mfma_f32_16x16x32_bf16 v[56:59], v[162:165], v[172:175], v[56:59]
	v_mfma_f32_16x16x32_bf16 v[52:55], v[154:157], v[180:183], v[52:55]
	v_mfma_f32_16x16x32_bf16 v[48:51], v[162:165], v[180:183], v[48:51]
	v_mfma_f32_16x16x32_bf16 v[36:39], v[154:157], v[188:191], v[36:39]
	v_mfma_f32_16x16x32_bf16 v[32:35], v[162:165], v[188:191], v[32:35]
	v_mfma_f32_16x16x32_bf16 v[20:23], v[154:157], v[196:199], v[20:23]
	v_mfma_f32_16x16x32_bf16 v[16:19], v[162:165], v[196:199], v[16:19]
	s_setprio 0
	s_barrier
	s_add_u32 s18, s18, 0x80080
	s_addc_u32 s19, s19, 0
	s_add_i32 s20, s20, s23
	v_lshl_add_u64 v[150:151], s[18:19], 0, v[130:131]
	s_mov_b32 m0, s20
	s_nop 0
	global_load_lds_dwordx4 v[150:151], off
	v_lshl_add_u64 v[150:151], s[18:19], 0, v[134:135]
	s_add_i32 m0, s20, 0x2000
	s_nop 0
	global_load_lds_dwordx4 v[150:151], off
	s_waitcnt vmcnt(10)
	s_barrier
	s_setprio 1
	v_mfma_f32_16x16x32_bf16 v[44:47], v[200:203], v[166:169], v[44:47]
	v_mfma_f32_16x16x32_bf16 v[40:43], v[208:211], v[166:169], v[40:43]
	v_mfma_f32_16x16x32_bf16 v[28:31], v[200:203], v[176:179], v[28:31]
	v_mfma_f32_16x16x32_bf16 v[24:27], v[208:211], v[176:179], v[24:27]
	v_mfma_f32_16x16x32_bf16 v[12:15], v[200:203], v[184:187], v[12:15]
	v_mfma_f32_16x16x32_bf16 v[8:11], v[208:211], v[184:187], v[8:11]
	v_mfma_f32_16x16x32_bf16 v[4:7], v[200:203], v[192:195], v[4:7]
	v_mfma_f32_16x16x32_bf16 v[0:3], v[208:211], v[192:195], v[0:3]
	v_mfma_f32_16x16x32_bf16 v[44:47], v[204:207], v[172:175], v[44:47]
	v_mfma_f32_16x16x32_bf16 v[40:43], v[212:215], v[172:175], v[40:43]
	v_mfma_f32_16x16x32_bf16 v[28:31], v[204:207], v[180:183], v[28:31]
	v_mfma_f32_16x16x32_bf16 v[24:27], v[212:215], v[180:183], v[24:27]
	v_mfma_f32_16x16x32_bf16 v[12:15], v[204:207], v[188:191], v[12:15]
	v_mfma_f32_16x16x32_bf16 v[8:11], v[212:215], v[188:191], v[8:11]
	v_mfma_f32_16x16x32_bf16 v[4:7], v[204:207], v[196:199], v[4:7]
	v_mfma_f32_16x16x32_bf16 v[0:3], v[212:215], v[196:199], v[0:3]
	s_setprio 0
	s_add_i32 s43, s43, 2
	s_add_u32 s16, s16, 0x100
	s_addc_u32 s17, s17, 0
	s_add_u32 s41, s41, 0x100
	s_addc_u32 s42, s42, 0
	s_cmp_gt_u32 s43, 29
	s_barrier
	s_cbranch_scc0 .LBB0_162
	v_readlane_b32 s16, v234, 9
	v_lshl_add_u32 v156, s6, 8, v144
	v_lshl_or_b32 v150, s38, 8, v146
	v_readlane_b32 s17, v234, 10
	v_ashrrev_i32_e32 v151, 31, v150
	v_cvt_pk_bf16_f32 v68, v68, v69
	v_mov_b64_e32 v[152:153], s[16:17]
	v_cvt_pk_bf16_f32 v69, v70, v71
	v_cvt_pk_bf16_f32 v70, v64, v65
	v_add_u32_e32 v64, 0x80, v156
	v_mad_i64_i32 v[154:155], s[16:17], v156, s37, v[152:153]
	v_lshlrev_b64 v[150:151], 1, v[150:151]
	v_cvt_pk_bf16_f32 v108, v108, v109
	v_cvt_pk_bf16_f32 v109, v110, v111
	v_cvt_pk_bf16_f32 v110, v104, v105
	v_or_b32_e32 v104, 16, v156
	v_mad_i64_i32 v[64:65], s[16:17], v64, s37, v[152:153]
	v_cvt_pk_bf16_f32 v44, v44, v45
	v_cvt_pk_bf16_f32 v45, v46, v47
	v_cvt_pk_bf16_f32 v46, v40, v41
	v_add_u32_e32 v40, 0x90, v156
	v_lshl_add_u64 v[154:155], v[154:155], 0, v[150:151]
	v_cvt_pk_bf16_f32 v111, v106, v107
	v_mad_i64_i32 v[104:105], s[16:17], v104, s37, v[152:153]
	v_cvt_pk_bf16_f32 v92, v92, v93
	v_cvt_pk_bf16_f32 v93, v94, v95
	v_cvt_pk_bf16_f32 v94, v88, v89
	v_or_b32_e32 v88, 32, v156
	v_lshl_add_u64 v[64:65], v[64:65], 0, v[150:151]
	v_cvt_pk_bf16_f32 v47, v42, v43
	v_mad_i64_i32 v[40:41], s[16:17], v40, s37, v[152:153]
	v_cvt_pk_bf16_f32 v28, v28, v29
	v_cvt_pk_bf16_f32 v29, v30, v31
	v_cvt_pk_bf16_f32 v30, v24, v25
	v_add_u32_e32 v24, 0xa0, v156
	global_store_dwordx4 v[154:155], v[108:111], off offset:256
	v_cvt_pk_bf16_f32 v95, v90, v91
	v_mad_i64_i32 v[88:89], s[16:17], v88, s37, v[152:153]
	v_lshl_add_u64 v[108:109], v[104:105], 0, v[150:151]
	v_cvt_pk_bf16_f32 v76, v76, v77
	v_cvt_pk_bf16_f32 v77, v78, v79
	v_cvt_pk_bf16_f32 v78, v72, v73
	v_or_b32_e32 v72, 48, v156
	global_store_dwordx4 v[64:65], v[44:47], off offset:256
	v_cvt_pk_bf16_f32 v31, v26, v27
	v_mad_i64_i32 v[24:25], s[16:17], v24, s37, v[152:153]
	v_lshl_add_u64 v[44:45], v[40:41], 0, v[150:151]
	v_cvt_pk_bf16_f32 v12, v12, v13
	v_cvt_pk_bf16_f32 v13, v14, v15
	v_cvt_pk_bf16_f32 v14, v8, v9
	v_add_u32_e32 v8, 0xb0, v156
	global_store_dwordx4 v[108:109], v[92:95], off offset:256
	v_cvt_pk_bf16_f32 v79, v74, v75
	v_mad_i64_i32 v[72:73], s[16:17], v72, s37, v[152:153]
	v_lshl_add_u64 v[92:93], v[88:89], 0, v[150:151]
	global_store_dwordx4 v[44:45], v[28:31], off offset:256
	v_cvt_pk_bf16_f32 v15, v10, v11
	v_mad_i64_i32 v[8:9], s[16:17], v8, s37, v[152:153]
	v_lshl_add_u64 v[28:29], v[24:25], 0, v[150:151]
	v_cvt_pk_bf16_f32 v124, v124, v125
	v_cvt_pk_bf16_f32 v125, v126, v127
	v_cvt_pk_bf16_f32 v126, v120, v121
	v_cvt_pk_bf16_f32 v127, v122, v123
	v_cvt_pk_bf16_f32 v104, v116, v117
	v_cvt_pk_bf16_f32 v105, v118, v119
	v_cvt_pk_bf16_f32 v106, v112, v113
	v_cvt_pk_bf16_f32 v107, v114, v115
	v_cvt_pk_bf16_f32 v88, v100, v101
	v_cvt_pk_bf16_f32 v89, v102, v103
	v_cvt_pk_bf16_f32 v90, v96, v97
	v_cvt_pk_bf16_f32 v91, v98, v99
	global_store_dwordx4 v[92:93], v[76:79], off offset:256
	v_cvt_pk_bf16_f32 v74, v80, v81
	v_cvt_pk_bf16_f32 v75, v82, v83
	v_lshl_add_u64 v[76:77], v[72:73], 0, v[150:151]
	v_cvt_pk_bf16_f32 v72, v84, v85
	v_cvt_pk_bf16_f32 v73, v86, v87
	v_cvt_pk_bf16_f32 v71, v66, v67
	v_cvt_pk_bf16_f32 v60, v60, v61
	v_cvt_pk_bf16_f32 v61, v62, v63
	v_cvt_pk_bf16_f32 v62, v56, v57
	v_cvt_pk_bf16_f32 v63, v58, v59
	v_cvt_pk_bf16_f32 v40, v52, v53
	v_cvt_pk_bf16_f32 v41, v54, v55
	v_cvt_pk_bf16_f32 v42, v48, v49
	v_cvt_pk_bf16_f32 v43, v50, v51
	v_cvt_pk_bf16_f32 v24, v36, v37
	v_cvt_pk_bf16_f32 v25, v38, v39
	v_cvt_pk_bf16_f32 v26, v32, v33
	v_cvt_pk_bf16_f32 v27, v34, v35
	global_store_dwordx4 v[28:29], v[12:15], off offset:256
	v_cvt_pk_bf16_f32 v10, v16, v17
	v_cvt_pk_bf16_f32 v11, v18, v19
	v_lshl_add_u64 v[12:13], v[8:9], 0, v[150:151]
	v_cvt_pk_bf16_f32 v8, v20, v21
	v_cvt_pk_bf16_f32 v9, v22, v23
	v_cvt_pk_bf16_f32 v4, v4, v5
	v_cvt_pk_bf16_f32 v5, v6, v7
	v_cvt_pk_bf16_f32 v6, v0, v1
	v_cvt_pk_bf16_f32 v7, v2, v3
	s_and_b64 vcc, exec, s[2:3]
	s_mov_b32 s38, s8
	s_mov_b32 s6, s10
	s_mov_b64 s[18:19], s[14:15]
	s_mov_b64 s[16:17], s[12:13]
	global_store_dwordx4 v[154:155], v[124:127], off
	global_store_dwordx4 v[108:109], v[104:107], off
	global_store_dwordx4 v[92:93], v[88:91], off
	global_store_dwordx4 v[76:77], v[72:75], off
	global_store_dwordx4 v[76:77], v[68:71], off offset:256
	global_store_dwordx4 v[64:65], v[60:63], off
	global_store_dwordx4 v[44:45], v[40:43], off
	global_store_dwordx4 v[28:29], v[24:27], off
	global_store_dwordx4 v[12:13], v[8:11], off
	global_store_dwordx4 v[12:13], v[4:7], off offset:256
	s_cbranch_vccz .LBB0_159
	s_waitcnt vmcnt(0)
	s_cmpk_gt_u32 s22, 0xff
	s_cbranch_scc1 .LBB0_166
	s_barrier

.LBB0_484:
	ds_read_b128 v[160:163], v153
	ds_read_b128 v[164:167], v153 offset:1024
	ds_read_b128 v[172:175], v153 offset:2048
	ds_read_b128 v[176:179], v153 offset:3072
	s_add_u32 s28, s26, 0xfff80080
	s_addc_u32 s29, s27, -1
	s_cmp_eq_u32 s57, 28
	s_cselect_b32 s31, s21, s29
	s_cselect_b32 s30, s53, s28
	s_cselect_b32 s29, s19, s56
	s_cselect_b32 s28, s54, s55
	v_lshl_add_u64 v[168:169], s[26:27], 0, v[136:137]
	s_add_i32 m0, s15, 0xc000
	ds_read_b128 v[180:183], v157
	ds_read_b128 v[184:187], v157 offset:1024
	ds_read_b128 v[188:191], v157 offset:2048
	ds_read_b128 v[192:195], v157 offset:3072
	ds_read_b128 v[196:199], v157 offset:4096
	ds_read_b128 v[200:203], v157 offset:5120
	ds_read_b128 v[204:207], v157 offset:6144
	ds_read_b128 v[208:211], v157 offset:7168
	global_load_lds_dwordx4 v[168:169], off
	v_lshl_add_u64 v[168:169], s[26:27], 0, v[138:139]
	s_add_i32 m0, s15, 0xe000
	s_nop 0
	global_load_lds_dwordx4 v[168:169], off
	s_waitcnt vmcnt(10)
	s_waitcnt lgkmcnt(8)
	s_barrier
	s_waitcnt lgkmcnt(0)
	s_setprio 1
	s_waitcnt lgkmcnt(0)
	v_mfma_f32_16x16x32_bf16 v[124:127], v[160:163], v[180:183], v[124:127]
	v_mfma_f32_16x16x32_bf16 v[120:123], v[172:175], v[180:183], v[120:123]
	v_mfma_f32_16x16x32_bf16 v[116:119], v[160:163], v[188:191], v[116:119]
	v_mfma_f32_16x16x32_bf16 v[112:115], v[172:175], v[188:191], v[112:115]
	v_mfma_f32_16x16x32_bf16 v[100:103], v[160:163], v[196:199], v[100:103]
	v_mfma_f32_16x16x32_bf16 v[96:99], v[172:175], v[196:199], v[96:99]
	v_mfma_f32_16x16x32_bf16 v[84:87], v[160:163], v[204:207], v[84:87]
	v_mfma_f32_16x16x32_bf16 v[80:83], v[172:175], v[204:207], v[80:83]
	v_mfma_f32_16x16x32_bf16 v[124:127], v[164:167], v[184:187], v[124:127]
	v_mfma_f32_16x16x32_bf16 v[120:123], v[176:179], v[184:187], v[120:123]
	v_mfma_f32_16x16x32_bf16 v[116:119], v[164:167], v[192:195], v[116:119]
	v_mfma_f32_16x16x32_bf16 v[112:115], v[176:179], v[192:195], v[112:115]
	v_mfma_f32_16x16x32_bf16 v[100:103], v[164:167], v[200:203], v[100:103]
	v_mfma_f32_16x16x32_bf16 v[96:99], v[176:179], v[200:203], v[96:99]
	v_mfma_f32_16x16x32_bf16 v[84:87], v[164:167], v[208:211], v[84:87]
	v_mfma_f32_16x16x32_bf16 v[80:83], v[176:179], v[208:211], v[80:83]
	s_setprio 0
	s_barrier
	s_add_i32 s58, s50, s41
	v_lshl_add_u64 v[168:169], s[28:29], 0, v[130:131]
	s_mov_b32 m0, s58
	ds_read_b128 v[212:215], v158
	ds_read_b128 v[216:219], v158 offset:1024
	ds_read_b128 v[220:223], v158 offset:2048
	ds_read_b128 v[224:227], v158 offset:3072
	global_load_lds_dwordx4 v[168:169], off
	v_lshl_add_u64 v[228:229], s[28:29], 0, v[134:135]
	s_add_i32 m0, s58, 0x2000
	s_nop 0
	global_load_lds_dwordx4 v[228:229], off
	s_waitcnt vmcnt(10)
	s_barrier
	s_waitcnt lgkmcnt(0)
	s_setprio 1
	s_waitcnt lgkmcnt(0)
	v_mfma_f32_16x16x32_bf16 v[108:111], v[212:215], v[180:183], v[108:111]
	v_mfma_f32_16x16x32_bf16 v[104:107], v[220:223], v[180:183], v[104:107]
	v_mfma_f32_16x16x32_bf16 v[92:95], v[212:215], v[188:191], v[92:95]
	v_mfma_f32_16x16x32_bf16 v[88:91], v[220:223], v[188:191], v[88:91]
	v_mfma_f32_16x16x32_bf16 v[76:79], v[212:215], v[196:199], v[76:79]
	v_mfma_f32_16x16x32_bf16 v[72:75], v[220:223], v[196:199], v[72:75]
	v_mfma_f32_16x16x32_bf16 v[68:71], v[212:215], v[204:207], v[68:71]
	v_mfma_f32_16x16x32_bf16 v[64:67], v[220:223], v[204:207], v[64:67]
	v_mfma_f32_16x16x32_bf16 v[108:111], v[216:219], v[184:187], v[108:111]
	v_mfma_f32_16x16x32_bf16 v[104:107], v[224:227], v[184:187], v[104:107]
	v_mfma_f32_16x16x32_bf16 v[92:95], v[216:219], v[192:195], v[92:95]
	v_mfma_f32_16x16x32_bf16 v[88:91], v[224:227], v[192:195], v[88:91]
	v_mfma_f32_16x16x32_bf16 v[76:79], v[216:219], v[200:203], v[76:79]
	v_mfma_f32_16x16x32_bf16 v[72:75], v[224:227], v[200:203], v[72:75]
	v_mfma_f32_16x16x32_bf16 v[68:71], v[216:219], v[208:211], v[68:71]
	v_mfma_f32_16x16x32_bf16 v[64:67], v[224:227], v[208:211], v[64:67]
	s_setprio 0
	s_mov_b32 m0, s15
	v_lshl_add_u64 v[230:231], s[30:31], 0, v[128:129]
	s_barrier
	ds_read_b128 v[180:183], v157 offset:16384
	ds_read_b128 v[184:187], v157 offset:17408
	ds_read_b128 v[188:191], v157 offset:18432
	ds_read_b128 v[192:195], v157 offset:19456
	ds_read_b128 v[196:199], v157 offset:20480
	ds_read_b128 v[200:203], v157 offset:21504
	ds_read_b128 v[204:207], v157 offset:22528
	ds_read_b128 v[208:211], v157 offset:23552
	global_load_lds_dwordx4 v[230:231], off
	v_lshl_add_u64 v[232:233], s[30:31], 0, v[132:133]
	s_mov_b32 m0, s42
	s_nop 0
	global_load_lds_dwordx4 v[232:233], off
	s_barrier
	s_waitcnt lgkmcnt(0)
	s_setprio 1
	s_waitcnt lgkmcnt(0)
	v_mfma_f32_16x16x32_bf16 v[60:63], v[160:163], v[180:183], v[60:63]
	v_mfma_f32_16x16x32_bf16 v[56:59], v[172:175], v[180:183], v[56:59]
	v_mfma_f32_16x16x32_bf16 v[52:55], v[160:163], v[188:191], v[52:55]
	v_mfma_f32_16x16x32_bf16 v[48:51], v[172:175], v[188:191], v[48:51]
	v_mfma_f32_16x16x32_bf16 v[36:39], v[160:163], v[196:199], v[36:39]
	v_mfma_f32_16x16x32_bf16 v[32:35], v[172:175], v[196:199], v[32:35]
	v_mfma_f32_16x16x32_bf16 v[20:23], v[160:163], v[204:207], v[20:23]
	v_mfma_f32_16x16x32_bf16 v[16:19], v[172:175], v[204:207], v[16:19]
	v_mfma_f32_16x16x32_bf16 v[60:63], v[164:167], v[184:187], v[60:63]
	v_mfma_f32_16x16x32_bf16 v[56:59], v[176:179], v[184:187], v[56:59]
	v_mfma_f32_16x16x32_bf16 v[52:55], v[164:167], v[192:195], v[52:55]
	v_mfma_f32_16x16x32_bf16 v[48:51], v[176:179], v[192:195], v[48:51]
	v_mfma_f32_16x16x32_bf16 v[36:39], v[164:167], v[200:203], v[36:39]
	v_mfma_f32_16x16x32_bf16 v[32:35], v[176:179], v[200:203], v[32:35]
	v_mfma_f32_16x16x32_bf16 v[20:23], v[164:167], v[208:211], v[20:23]
	v_mfma_f32_16x16x32_bf16 v[16:19], v[176:179], v[208:211], v[16:19]
	s_setprio 0
	s_barrier
	s_add_u32 s58, s28, 0x80000
	s_addc_u32 s59, s29, 0
	s_add_i32 s60, s51, s41
	v_lshl_add_u64 v[160:161], s[58:59], 0, v[130:131]
	s_mov_b32 m0, s60
	s_nop 0
	global_load_lds_dwordx4 v[160:161], off
	v_lshl_add_u64 v[160:161], s[58:59], 0, v[134:135]
	s_add_i32 m0, s60, 0x2000
	s_nop 0
	global_load_lds_dwordx4 v[160:161], off
	s_waitcnt vmcnt(10)
	s_barrier
	s_setprio 1
	v_mfma_f32_16x16x32_bf16 v[44:47], v[212:215], v[180:183], v[44:47]
	v_mfma_f32_16x16x32_bf16 v[40:43], v[220:223], v[180:183], v[40:43]
	v_mfma_f32_16x16x32_bf16 v[28:31], v[212:215], v[188:191], v[28:31]
	v_mfma_f32_16x16x32_bf16 v[24:27], v[220:223], v[188:191], v[24:27]
	v_mfma_f32_16x16x32_bf16 v[12:15], v[212:215], v[196:199], v[12:15]
	v_mfma_f32_16x16x32_bf16 v[8:11], v[220:223], v[196:199], v[8:11]
	v_mfma_f32_16x16x32_bf16 v[4:7], v[212:215], v[204:207], v[4:7]
	v_mfma_f32_16x16x32_bf16 v[0:3], v[220:223], v[204:207], v[0:3]
	v_mfma_f32_16x16x32_bf16 v[44:47], v[216:219], v[184:187], v[44:47]
	v_mfma_f32_16x16x32_bf16 v[40:43], v[224:227], v[184:187], v[40:43]
	v_mfma_f32_16x16x32_bf16 v[28:31], v[216:219], v[192:195], v[28:31]
	v_mfma_f32_16x16x32_bf16 v[24:27], v[224:227], v[192:195], v[24:27]
	v_mfma_f32_16x16x32_bf16 v[12:15], v[216:219], v[200:203], v[12:15]
	v_mfma_f32_16x16x32_bf16 v[8:11], v[224:227], v[200:203], v[8:11]
	v_mfma_f32_16x16x32_bf16 v[4:7], v[216:219], v[208:211], v[4:7]
	v_mfma_f32_16x16x32_bf16 v[0:3], v[224:227], v[208:211], v[0:3]
	s_setprio 0
	s_add_i32 s58, 0, 0x18000
	v_add_u32_e32 v159, s58, v150
	s_barrier
	ds_read_b128 v[160:163], v159
	ds_read_b128 v[164:167], v159 offset:1024
	ds_read_b128 v[172:175], v159 offset:2048
	ds_read_b128 v[176:179], v159 offset:3072
	s_add_u32 s30, s30, 0x80000
	s_addc_u32 s31, s31, 0
	s_mov_b32 m0, s43
	v_lshl_add_u64 v[212:213], s[30:31], 0, v[128:129]
	ds_read_b128 v[180:183], v157 offset:32768
	ds_read_b128 v[184:187], v157 offset:33792
	ds_read_b128 v[188:191], v157 offset:34816
	ds_read_b128 v[192:195], v157 offset:35840
	ds_read_b128 v[196:199], v157 offset:36864
	ds_read_b128 v[200:203], v157 offset:37888
	ds_read_b128 v[204:207], v157 offset:38912
	ds_read_b128 v[208:211], v157 offset:39936
	global_load_lds_dwordx4 v[212:213], off
	v_lshl_add_u64 v[212:213], s[30:31], 0, v[132:133]
	s_mov_b32 m0, s44
	s_nop 0
	global_load_lds_dwordx4 v[212:213], off
	s_waitcnt vmcnt(10)
	s_waitcnt lgkmcnt(8)
	s_barrier
	s_waitcnt lgkmcnt(0)
	s_setprio 1
	s_waitcnt lgkmcnt(0)
	v_mfma_f32_16x16x32_bf16 v[124:127], v[160:163], v[180:183], v[124:127]
	v_mfma_f32_16x16x32_bf16 v[120:123], v[172:175], v[180:183], v[120:123]
	v_mfma_f32_16x16x32_bf16 v[116:119], v[160:163], v[188:191], v[116:119]
	v_mfma_f32_16x16x32_bf16 v[112:115], v[172:175], v[188:191], v[112:115]
	v_mfma_f32_16x16x32_bf16 v[100:103], v[160:163], v[196:199], v[100:103]
	v_mfma_f32_16x16x32_bf16 v[96:99], v[172:175], v[196:199], v[96:99]
	v_mfma_f32_16x16x32_bf16 v[84:87], v[160:163], v[204:207], v[84:87]
	v_mfma_f32_16x16x32_bf16 v[80:83], v[172:175], v[204:207], v[80:83]
	v_mfma_f32_16x16x32_bf16 v[124:127], v[164:167], v[184:187], v[124:127]
	v_mfma_f32_16x16x32_bf16 v[120:123], v[176:179], v[184:187], v[120:123]
	v_mfma_f32_16x16x32_bf16 v[116:119], v[164:167], v[192:195], v[116:119]
	v_mfma_f32_16x16x32_bf16 v[112:115], v[176:179], v[192:195], v[112:115]
	v_mfma_f32_16x16x32_bf16 v[100:103], v[164:167], v[200:203], v[100:103]
	v_mfma_f32_16x16x32_bf16 v[96:99], v[176:179], v[200:203], v[96:99]
	v_mfma_f32_16x16x32_bf16 v[84:87], v[164:167], v[208:211], v[84:87]
	v_mfma_f32_16x16x32_bf16 v[80:83], v[176:179], v[208:211], v[80:83]
	s_setprio 0
	s_barrier
	s_add_i32 s30, 0, 0x1c000
	s_add_i32 s31, s58, s41
	v_add_u32_e32 v159, s30, v150
	v_lshl_add_u64 v[168:169], v[168:169], 0, s[12:13]
	s_mov_b32 m0, s31
	ds_read_b128 v[212:215], v159
	ds_read_b128 v[216:219], v159 offset:1024
	ds_read_b128 v[220:223], v159 offset:2048
	ds_read_b128 v[224:227], v159 offset:3072
	global_load_lds_dwordx4 v[168:169], off
	v_lshl_add_u64 v[168:169], v[228:229], 0, s[12:13]
	s_add_i32 m0, s31, 0x2000
	s_nop 0
	global_load_lds_dwordx4 v[168:169], off
	s_waitcnt vmcnt(10)
	s_barrier
	s_waitcnt lgkmcnt(0)
	s_setprio 1
	s_waitcnt lgkmcnt(0)
	v_mfma_f32_16x16x32_bf16 v[108:111], v[212:215], v[180:183], v[108:111]
	v_mfma_f32_16x16x32_bf16 v[104:107], v[220:223], v[180:183], v[104:107]
	v_mfma_f32_16x16x32_bf16 v[92:95], v[212:215], v[188:191], v[92:95]
	v_mfma_f32_16x16x32_bf16 v[88:91], v[220:223], v[188:191], v[88:91]
	v_mfma_f32_16x16x32_bf16 v[76:79], v[212:215], v[196:199], v[76:79]
	v_mfma_f32_16x16x32_bf16 v[72:75], v[220:223], v[196:199], v[72:75]
	v_mfma_f32_16x16x32_bf16 v[68:71], v[212:215], v[204:207], v[68:71]
	v_mfma_f32_16x16x32_bf16 v[64:67], v[220:223], v[204:207], v[64:67]
	v_mfma_f32_16x16x32_bf16 v[108:111], v[216:219], v[184:187], v[108:111]
	v_mfma_f32_16x16x32_bf16 v[104:107], v[224:227], v[184:187], v[104:107]
	v_mfma_f32_16x16x32_bf16 v[92:95], v[216:219], v[192:195], v[92:95]
	v_mfma_f32_16x16x32_bf16 v[88:91], v[224:227], v[192:195], v[88:91]
	v_mfma_f32_16x16x32_bf16 v[76:79], v[216:219], v[200:203], v[76:79]
	v_mfma_f32_16x16x32_bf16 v[72:75], v[224:227], v[200:203], v[72:75]
	v_mfma_f32_16x16x32_bf16 v[68:71], v[216:219], v[208:211], v[68:71]
	v_mfma_f32_16x16x32_bf16 v[64:67], v[224:227], v[208:211], v[64:67]
	s_setprio 0
	s_mov_b32 m0, s46
	v_lshl_add_u64 v[168:169], v[230:231], 0, s[12:13]
	s_barrier
	ds_read_b128 v[180:183], v157 offset:49152
	ds_read_b128 v[184:187], v157 offset:50176
	ds_read_b128 v[188:191], v157 offset:51200
	ds_read_b128 v[192:195], v157 offset:52224
	ds_read_b128 v[196:199], v157 offset:53248
	ds_read_b128 v[200:203], v157 offset:54272
	ds_read_b128 v[204:207], v157 offset:55296
	ds_read_b128 v[208:211], v157 offset:56320
	global_load_lds_dwordx4 v[168:169], off
	v_lshl_add_u64 v[168:169], v[232:233], 0, s[12:13]
	s_mov_b32 m0, s47
	s_nop 0
	global_load_lds_dwordx4 v[168:169], off
	s_barrier
	s_waitcnt lgkmcnt(0)
	s_setprio 1
	s_waitcnt lgkmcnt(0)
	v_mfma_f32_16x16x32_bf16 v[60:63], v[160:163], v[180:183], v[60:63]
	v_mfma_f32_16x16x32_bf16 v[56:59], v[172:175], v[180:183], v[56:59]
	v_mfma_f32_16x16x32_bf16 v[52:55], v[160:163], v[188:191], v[52:55]
	v_mfma_f32_16x16x32_bf16 v[48:51], v[172:175], v[188:191], v[48:51]
	v_mfma_f32_16x16x32_bf16 v[36:39], v[160:163], v[196:199], v[36:39]
	v_mfma_f32_16x16x32_bf16 v[32:35], v[172:175], v[196:199], v[32:35]
	v_mfma_f32_16x16x32_bf16 v[20:23], v[160:163], v[204:207], v[20:23]
	v_mfma_f32_16x16x32_bf16 v[16:19], v[172:175], v[204:207], v[16:19]
	v_mfma_f32_16x16x32_bf16 v[60:63], v[164:167], v[184:187], v[60:63]
	v_mfma_f32_16x16x32_bf16 v[56:59], v[176:179], v[184:187], v[56:59]
	v_mfma_f32_16x16x32_bf16 v[52:55], v[164:167], v[192:195], v[52:55]
	v_mfma_f32_16x16x32_bf16 v[48:51], v[176:179], v[192:195], v[48:51]
	v_mfma_f32_16x16x32_bf16 v[36:39], v[164:167], v[200:203], v[36:39]
	v_mfma_f32_16x16x32_bf16 v[32:35], v[176:179], v[200:203], v[32:35]
	v_mfma_f32_16x16x32_bf16 v[20:23], v[164:167], v[208:211], v[20:23]
	v_mfma_f32_16x16x32_bf16 v[16:19], v[176:179], v[208:211], v[16:19]
	s_setprio 0
	s_barrier
	s_add_u32 s28, s28, 0x80080
	s_addc_u32 s29, s29, 0
	s_add_i32 s30, s30, s41
	v_lshl_add_u64 v[160:161], s[28:29], 0, v[130:131]
	s_mov_b32 m0, s30
	s_nop 0
	global_load_lds_dwordx4 v[160:161], off
	v_lshl_add_u64 v[160:161], s[28:29], 0, v[134:135]
	s_add_i32 m0, s30, 0x2000
	s_nop 0
	global_load_lds_dwordx4 v[160:161], off
	s_waitcnt vmcnt(10)
	s_barrier
	s_setprio 1
	v_mfma_f32_16x16x32_bf16 v[44:47], v[212:215], v[180:183], v[44:47]
	v_mfma_f32_16x16x32_bf16 v[40:43], v[220:223], v[180:183], v[40:43]
	v_mfma_f32_16x16x32_bf16 v[28:31], v[212:215], v[188:191], v[28:31]
	v_mfma_f32_16x16x32_bf16 v[24:27], v[220:223], v[188:191], v[24:27]
	v_mfma_f32_16x16x32_bf16 v[12:15], v[212:215], v[196:199], v[12:15]
	v_mfma_f32_16x16x32_bf16 v[8:11], v[220:223], v[196:199], v[8:11]
	v_mfma_f32_16x16x32_bf16 v[4:7], v[212:215], v[204:207], v[4:7]
	v_mfma_f32_16x16x32_bf16 v[0:3], v[220:223], v[204:207], v[0:3]
	v_mfma_f32_16x16x32_bf16 v[44:47], v[216:219], v[184:187], v[44:47]
	v_mfma_f32_16x16x32_bf16 v[40:43], v[224:227], v[184:187], v[40:43]
	v_mfma_f32_16x16x32_bf16 v[28:31], v[216:219], v[192:195], v[28:31]
	v_mfma_f32_16x16x32_bf16 v[24:27], v[224:227], v[192:195], v[24:27]
	v_mfma_f32_16x16x32_bf16 v[12:15], v[216:219], v[200:203], v[12:15]
	v_mfma_f32_16x16x32_bf16 v[8:11], v[224:227], v[200:203], v[8:11]
	v_mfma_f32_16x16x32_bf16 v[4:7], v[216:219], v[208:211], v[4:7]
	v_mfma_f32_16x16x32_bf16 v[0:3], v[224:227], v[208:211], v[0:3]
	s_setprio 0
	s_add_i32 s57, s57, 2
	s_add_u32 s26, s26, 0x100
	s_addc_u32 s27, s27, 0
	s_add_u32 s55, s55, 0x100
	s_addc_u32 s56, s56, 0
	s_cmp_gt_u32 s57, 29
	s_barrier
	s_cbranch_scc0 .LBB0_484
	v_lshl_add_u32 v160, s14, 8, v149
	v_lshl_or_b32 v162, s52, 8, v151
	v_ashrrev_i32_e32 v161, 31, v160
	v_ashrrev_i32_e32 v163, 31, v162
	v_lshlrev_b64 v[164:165], 12, v[160:161]
	v_lshl_add_u64 v[164:165], s[2:3], 0, v[164:165]
	v_lshlrev_b64 v[162:163], 1, v[162:163]
	v_lshl_add_u64 v[164:165], v[164:165], 0, v[162:163]
	s_mov_b32 s14, 0x80000
	s_mov_b64 s[26:27], 0x80000
	v_cvt_pk_bf16_f32 v60, v60, v61
	v_cvt_pk_bf16_f32 v61, v62, v63
	v_cvt_pk_bf16_f32 v62, v56, v57
	v_add_co_u32_e32 v56, vcc, s14, v164
	v_cvt_pk_bf16_f32 v68, v68, v69
	v_cvt_pk_bf16_f32 v69, v70, v71
	v_cvt_pk_bf16_f32 v70, v64, v65
	v_lshl_add_u64 v[64:65], v[164:165], 0, s[26:27]
	v_addc_co_u32_e32 v57, vcc, 0, v165, vcc
	v_cvt_pk_bf16_f32 v44, v44, v45
	v_cvt_pk_bf16_f32 v45, v46, v47
	v_cvt_pk_bf16_f32 v46, v40, v41
	v_cvt_pk_bf16_f32 v47, v42, v43
	s_mov_b32 s14, 0x90000
	v_cvt_pk_bf16_f32 v108, v108, v109
	v_cvt_pk_bf16_f32 v109, v110, v111
	v_cvt_pk_bf16_f32 v110, v104, v105
	v_or_b32_e32 v104, 16, v160
	global_store_dwordx4 v[64:65], v[44:47], off offset:256
	s_mov_b64 s[26:27], 0x90000
	v_ashrrev_i32_e32 v105, 31, v104
	v_add_co_u32_e32 v46, vcc, s14, v164
	v_cvt_pk_bf16_f32 v92, v92, v93
	v_cvt_pk_bf16_f32 v93, v94, v95
	v_cvt_pk_bf16_f32 v94, v88, v89
	v_or_b32_e32 v88, 32, v160
	v_lshl_add_u64 v[44:45], v[164:165], 0, s[26:27]
	v_addc_co_u32_e32 v47, vcc, 0, v165, vcc
	v_cvt_pk_bf16_f32 v28, v28, v29
	v_cvt_pk_bf16_f32 v29, v30, v31
	v_cvt_pk_bf16_f32 v30, v24, v25
	v_cvt_pk_bf16_f32 v31, v26, v27
	s_mov_b32 s14, 0xa0000
	v_lshlrev_b64 v[104:105], 12, v[104:105]
	v_ashrrev_i32_e32 v89, 31, v88
	v_cvt_pk_bf16_f32 v76, v76, v77
	v_cvt_pk_bf16_f32 v77, v78, v79
	v_cvt_pk_bf16_f32 v78, v72, v73
	v_or_b32_e32 v72, 48, v160
	global_store_dwordx4 v[44:45], v[28:31], off offset:256
	s_mov_b64 s[26:27], 0xa0000
	v_cvt_pk_bf16_f32 v111, v106, v107
	v_add_co_u32_e32 v30, vcc, s14, v164
	v_lshl_add_u64 v[104:105], s[2:3], 0, v[104:105]
	v_lshlrev_b64 v[88:89], 12, v[88:89]
	v_ashrrev_i32_e32 v73, 31, v72
	v_lshl_add_u64 v[28:29], v[164:165], 0, s[26:27]
	v_addc_co_u32_e32 v31, vcc, 0, v165, vcc
	v_cvt_pk_bf16_f32 v12, v12, v13
	v_cvt_pk_bf16_f32 v13, v14, v15
	v_cvt_pk_bf16_f32 v14, v8, v9
	v_cvt_pk_bf16_f32 v15, v10, v11
	global_store_dwordx4 v[164:165], v[108:111], off offset:256
	v_cvt_pk_bf16_f32 v95, v90, v91
	v_lshl_add_u64 v[88:89], s[2:3], 0, v[88:89]
	v_lshl_add_u64 v[108:109], v[104:105], 0, v[162:163]
	v_lshlrev_b64 v[72:73], 12, v[72:73]
	global_store_dwordx4 v[28:29], v[12:15], off offset:256
	global_store_dwordx4 v[108:109], v[92:95], off offset:256
	v_cvt_pk_bf16_f32 v79, v74, v75
	v_add_co_u32_e32 v14, vcc, 0xb0000, v164
	v_lshl_add_u64 v[92:93], v[88:89], 0, v[162:163]
	v_lshl_add_u64 v[72:73], s[2:3], 0, v[72:73]
	s_mov_b64 s[26:27], 0xb0000
	v_addc_co_u32_e32 v15, vcc, 0, v165, vcc
	v_cvt_pk_bf16_f32 v124, v124, v125
	v_cvt_pk_bf16_f32 v125, v126, v127
	v_cvt_pk_bf16_f32 v126, v120, v121
	v_cvt_pk_bf16_f32 v127, v122, v123
	v_cvt_pk_bf16_f32 v104, v116, v117
	v_cvt_pk_bf16_f32 v105, v118, v119
	v_cvt_pk_bf16_f32 v106, v112, v113
	v_cvt_pk_bf16_f32 v107, v114, v115
	v_cvt_pk_bf16_f32 v88, v100, v101
	v_cvt_pk_bf16_f32 v89, v102, v103
	v_cvt_pk_bf16_f32 v90, v96, v97
	v_cvt_pk_bf16_f32 v91, v98, v99
	global_store_dwordx4 v[92:93], v[76:79], off offset:256
	v_cvt_pk_bf16_f32 v74, v80, v81
	v_cvt_pk_bf16_f32 v75, v82, v83
	v_lshl_add_u64 v[76:77], v[72:73], 0, v[162:163]
	v_cvt_pk_bf16_f32 v72, v84, v85
	v_cvt_pk_bf16_f32 v73, v86, v87
	v_cvt_pk_bf16_f32 v71, v66, v67
	v_cvt_pk_bf16_f32 v63, v58, v59
	v_cvt_pk_bf16_f32 v40, v52, v53
	v_cvt_pk_bf16_f32 v41, v54, v55
	v_cvt_pk_bf16_f32 v42, v48, v49
	v_cvt_pk_bf16_f32 v43, v50, v51
	v_cvt_pk_bf16_f32 v24, v36, v37
	v_cvt_pk_bf16_f32 v25, v38, v39
	v_cvt_pk_bf16_f32 v26, v32, v33
	v_cvt_pk_bf16_f32 v27, v34, v35
	v_lshl_add_u64 v[12:13], v[164:165], 0, s[26:27]
	v_cvt_pk_bf16_f32 v8, v20, v21
	v_cvt_pk_bf16_f32 v9, v22, v23
	v_cvt_pk_bf16_f32 v10, v16, v17
	v_cvt_pk_bf16_f32 v11, v18, v19
	v_cvt_pk_bf16_f32 v4, v4, v5
	v_cvt_pk_bf16_f32 v5, v6, v7
	v_cvt_pk_bf16_f32 v6, v0, v1
	v_cvt_pk_bf16_f32 v7, v2, v3
	s_and_b64 vcc, exec, s[16:17]
	s_mov_b32 s52, s18
	s_mov_b32 s14, s20
	s_mov_b64 s[28:29], s[24:25]
	s_mov_b64 s[26:27], s[22:23]
	global_store_dwordx4 v[164:165], v[124:127], off
	global_store_dwordx4 v[108:109], v[104:107], off
	global_store_dwordx4 v[92:93], v[88:91], off
	global_store_dwordx4 v[76:77], v[72:75], off
	global_store_dwordx4 v[76:77], v[68:71], off offset:256
	global_store_dwordx4 v[56:57], v[60:63], off
	global_store_dwordx4 v[46:47], v[40:43], off
	global_store_dwordx4 v[30:31], v[24:27], off
	global_store_dwordx4 v[14:15], v[8:11], off
	global_store_dwordx4 v[12:13], v[4:7], off offset:256
	s_cbranch_vccz .LBB0_477
	s_waitcnt vmcnt(0)
	s_cmpk_gt_u32 s35, 0xff
	s_cbranch_scc1 .LBB0_488
	s_barrier

.LBB0_504:
	ds_read_b128 v[160:163], v153
	ds_read_b128 v[164:167], v153 offset:1024
	ds_read_b128 v[172:175], v153 offset:2048
	ds_read_b128 v[176:179], v153 offset:3072
	s_add_u32 s26, s24, 0xfff80080
	s_addc_u32 s27, s25, -1
	s_cmp_eq_u32 s55, 28
	s_cselect_b32 s29, s19, s27
	s_cselect_b32 s28, s51, s26
	s_cselect_b32 s27, s17, s54
	s_cselect_b32 s26, s52, s53
	v_lshl_add_u64 v[168:169], s[24:25], 0, v[136:137]
	s_add_i32 m0, s13, 0xc000
	ds_read_b128 v[180:183], v157
	ds_read_b128 v[184:187], v157 offset:1024
	ds_read_b128 v[188:191], v157 offset:2048
	ds_read_b128 v[192:195], v157 offset:3072
	ds_read_b128 v[196:199], v157 offset:4096
	ds_read_b128 v[200:203], v157 offset:5120
	ds_read_b128 v[204:207], v157 offset:6144
	ds_read_b128 v[208:211], v157 offset:7168
	global_load_lds_dwordx4 v[168:169], off
	v_lshl_add_u64 v[168:169], s[24:25], 0, v[138:139]
	s_add_i32 m0, s13, 0xe000
	s_nop 0
	global_load_lds_dwordx4 v[168:169], off
	s_waitcnt vmcnt(10)
	s_waitcnt lgkmcnt(8)
	s_barrier
	s_waitcnt lgkmcnt(0)
	s_setprio 1
	s_waitcnt lgkmcnt(0)
	v_mfma_f32_16x16x32_bf16 v[124:127], v[160:163], v[180:183], v[124:127]
	v_mfma_f32_16x16x32_bf16 v[120:123], v[172:175], v[180:183], v[120:123]
	v_mfma_f32_16x16x32_bf16 v[116:119], v[160:163], v[188:191], v[116:119]
	v_mfma_f32_16x16x32_bf16 v[112:115], v[172:175], v[188:191], v[112:115]
	v_mfma_f32_16x16x32_bf16 v[100:103], v[160:163], v[196:199], v[100:103]
	v_mfma_f32_16x16x32_bf16 v[96:99], v[172:175], v[196:199], v[96:99]
	v_mfma_f32_16x16x32_bf16 v[84:87], v[160:163], v[204:207], v[84:87]
	v_mfma_f32_16x16x32_bf16 v[80:83], v[172:175], v[204:207], v[80:83]
	v_mfma_f32_16x16x32_bf16 v[124:127], v[164:167], v[184:187], v[124:127]
	v_mfma_f32_16x16x32_bf16 v[120:123], v[176:179], v[184:187], v[120:123]
	v_mfma_f32_16x16x32_bf16 v[116:119], v[164:167], v[192:195], v[116:119]
	v_mfma_f32_16x16x32_bf16 v[112:115], v[176:179], v[192:195], v[112:115]
	v_mfma_f32_16x16x32_bf16 v[100:103], v[164:167], v[200:203], v[100:103]
	v_mfma_f32_16x16x32_bf16 v[96:99], v[176:179], v[200:203], v[96:99]
	v_mfma_f32_16x16x32_bf16 v[84:87], v[164:167], v[208:211], v[84:87]
	v_mfma_f32_16x16x32_bf16 v[80:83], v[176:179], v[208:211], v[80:83]
	s_setprio 0
	s_barrier
	s_add_i32 s56, s48, s37
	v_lshl_add_u64 v[168:169], s[26:27], 0, v[130:131]
	s_mov_b32 m0, s56
	ds_read_b128 v[212:215], v158
	ds_read_b128 v[216:219], v158 offset:1024
	ds_read_b128 v[220:223], v158 offset:2048
	ds_read_b128 v[224:227], v158 offset:3072
	global_load_lds_dwordx4 v[168:169], off
	v_lshl_add_u64 v[228:229], s[26:27], 0, v[134:135]
	s_add_i32 m0, s56, 0x2000
	s_nop 0
	global_load_lds_dwordx4 v[228:229], off
	s_waitcnt vmcnt(10)
	s_barrier
	s_waitcnt lgkmcnt(0)
	s_setprio 1
	s_waitcnt lgkmcnt(0)
	v_mfma_f32_16x16x32_bf16 v[108:111], v[212:215], v[180:183], v[108:111]
	v_mfma_f32_16x16x32_bf16 v[104:107], v[220:223], v[180:183], v[104:107]
	v_mfma_f32_16x16x32_bf16 v[92:95], v[212:215], v[188:191], v[92:95]
	v_mfma_f32_16x16x32_bf16 v[88:91], v[220:223], v[188:191], v[88:91]
	v_mfma_f32_16x16x32_bf16 v[76:79], v[212:215], v[196:199], v[76:79]
	v_mfma_f32_16x16x32_bf16 v[72:75], v[220:223], v[196:199], v[72:75]
	v_mfma_f32_16x16x32_bf16 v[68:71], v[212:215], v[204:207], v[68:71]
	v_mfma_f32_16x16x32_bf16 v[64:67], v[220:223], v[204:207], v[64:67]
	v_mfma_f32_16x16x32_bf16 v[108:111], v[216:219], v[184:187], v[108:111]
	v_mfma_f32_16x16x32_bf16 v[104:107], v[224:227], v[184:187], v[104:107]
	v_mfma_f32_16x16x32_bf16 v[92:95], v[216:219], v[192:195], v[92:95]
	v_mfma_f32_16x16x32_bf16 v[88:91], v[224:227], v[192:195], v[88:91]
	v_mfma_f32_16x16x32_bf16 v[76:79], v[216:219], v[200:203], v[76:79]
	v_mfma_f32_16x16x32_bf16 v[72:75], v[224:227], v[200:203], v[72:75]
	v_mfma_f32_16x16x32_bf16 v[68:71], v[216:219], v[208:211], v[68:71]
	v_mfma_f32_16x16x32_bf16 v[64:67], v[224:227], v[208:211], v[64:67]
	s_setprio 0
	s_mov_b32 m0, s13
	v_lshl_add_u64 v[230:231], s[28:29], 0, v[128:129]
	s_barrier
	ds_read_b128 v[180:183], v157 offset:16384
	ds_read_b128 v[184:187], v157 offset:17408
	ds_read_b128 v[188:191], v157 offset:18432
	ds_read_b128 v[192:195], v157 offset:19456
	ds_read_b128 v[196:199], v157 offset:20480
	ds_read_b128 v[200:203], v157 offset:21504
	ds_read_b128 v[204:207], v157 offset:22528
	ds_read_b128 v[208:211], v157 offset:23552
	global_load_lds_dwordx4 v[230:231], off
	v_lshl_add_u64 v[232:233], s[28:29], 0, v[132:133]
	s_mov_b32 m0, s40
	s_nop 0
	global_load_lds_dwordx4 v[232:233], off
	s_barrier
	s_waitcnt lgkmcnt(0)
	s_setprio 1
	s_waitcnt lgkmcnt(0)
	v_mfma_f32_16x16x32_bf16 v[60:63], v[160:163], v[180:183], v[60:63]
	v_mfma_f32_16x16x32_bf16 v[56:59], v[172:175], v[180:183], v[56:59]
	v_mfma_f32_16x16x32_bf16 v[52:55], v[160:163], v[188:191], v[52:55]
	v_mfma_f32_16x16x32_bf16 v[48:51], v[172:175], v[188:191], v[48:51]
	v_mfma_f32_16x16x32_bf16 v[36:39], v[160:163], v[196:199], v[36:39]
	v_mfma_f32_16x16x32_bf16 v[32:35], v[172:175], v[196:199], v[32:35]
	v_mfma_f32_16x16x32_bf16 v[20:23], v[160:163], v[204:207], v[20:23]
	v_mfma_f32_16x16x32_bf16 v[16:19], v[172:175], v[204:207], v[16:19]
	v_mfma_f32_16x16x32_bf16 v[60:63], v[164:167], v[184:187], v[60:63]
	v_mfma_f32_16x16x32_bf16 v[56:59], v[176:179], v[184:187], v[56:59]
	v_mfma_f32_16x16x32_bf16 v[52:55], v[164:167], v[192:195], v[52:55]
	v_mfma_f32_16x16x32_bf16 v[48:51], v[176:179], v[192:195], v[48:51]
	v_mfma_f32_16x16x32_bf16 v[36:39], v[164:167], v[200:203], v[36:39]
	v_mfma_f32_16x16x32_bf16 v[32:35], v[176:179], v[200:203], v[32:35]
	v_mfma_f32_16x16x32_bf16 v[20:23], v[164:167], v[208:211], v[20:23]
	v_mfma_f32_16x16x32_bf16 v[16:19], v[176:179], v[208:211], v[16:19]
	s_setprio 0
	s_barrier
	s_add_u32 s56, s26, 0x80000
	s_addc_u32 s57, s27, 0
	s_add_i32 s58, s49, s37
	v_lshl_add_u64 v[160:161], s[56:57], 0, v[130:131]
	s_mov_b32 m0, s58
	s_nop 0
	global_load_lds_dwordx4 v[160:161], off
	v_lshl_add_u64 v[160:161], s[56:57], 0, v[134:135]
	s_add_i32 m0, s58, 0x2000
	s_nop 0
	global_load_lds_dwordx4 v[160:161], off
	s_waitcnt vmcnt(10)
	s_barrier
	s_setprio 1
	v_mfma_f32_16x16x32_bf16 v[44:47], v[212:215], v[180:183], v[44:47]
	v_mfma_f32_16x16x32_bf16 v[40:43], v[220:223], v[180:183], v[40:43]
	v_mfma_f32_16x16x32_bf16 v[28:31], v[212:215], v[188:191], v[28:31]
	v_mfma_f32_16x16x32_bf16 v[24:27], v[220:223], v[188:191], v[24:27]
	v_mfma_f32_16x16x32_bf16 v[12:15], v[212:215], v[196:199], v[12:15]
	v_mfma_f32_16x16x32_bf16 v[8:11], v[220:223], v[196:199], v[8:11]
	v_mfma_f32_16x16x32_bf16 v[4:7], v[212:215], v[204:207], v[4:7]
	v_mfma_f32_16x16x32_bf16 v[0:3], v[220:223], v[204:207], v[0:3]
	v_mfma_f32_16x16x32_bf16 v[44:47], v[216:219], v[184:187], v[44:47]
	v_mfma_f32_16x16x32_bf16 v[40:43], v[224:227], v[184:187], v[40:43]
	v_mfma_f32_16x16x32_bf16 v[28:31], v[216:219], v[192:195], v[28:31]
	v_mfma_f32_16x16x32_bf16 v[24:27], v[224:227], v[192:195], v[24:27]
	v_mfma_f32_16x16x32_bf16 v[12:15], v[216:219], v[200:203], v[12:15]
	v_mfma_f32_16x16x32_bf16 v[8:11], v[224:227], v[200:203], v[8:11]
	v_mfma_f32_16x16x32_bf16 v[4:7], v[216:219], v[208:211], v[4:7]
	v_mfma_f32_16x16x32_bf16 v[0:3], v[224:227], v[208:211], v[0:3]
	s_setprio 0
	s_add_i32 s56, 0, 0x18000
	v_add_u32_e32 v159, s56, v150
	s_barrier
	ds_read_b128 v[160:163], v159
	ds_read_b128 v[164:167], v159 offset:1024
	ds_read_b128 v[172:175], v159 offset:2048
	ds_read_b128 v[176:179], v159 offset:3072
	s_add_u32 s28, s28, 0x80000
	s_addc_u32 s29, s29, 0
	s_mov_b32 m0, s41
	v_lshl_add_u64 v[212:213], s[28:29], 0, v[128:129]
	ds_read_b128 v[180:183], v157 offset:32768
	ds_read_b128 v[184:187], v157 offset:33792
	ds_read_b128 v[188:191], v157 offset:34816
	ds_read_b128 v[192:195], v157 offset:35840
	ds_read_b128 v[196:199], v157 offset:36864
	ds_read_b128 v[200:203], v157 offset:37888
	ds_read_b128 v[204:207], v157 offset:38912
	ds_read_b128 v[208:211], v157 offset:39936
	global_load_lds_dwordx4 v[212:213], off
	v_lshl_add_u64 v[212:213], s[28:29], 0, v[132:133]
	s_mov_b32 m0, s42
	s_nop 0
	global_load_lds_dwordx4 v[212:213], off
	s_waitcnt vmcnt(10)
	s_waitcnt lgkmcnt(8)
	s_barrier
	s_waitcnt lgkmcnt(0)
	s_setprio 1
	s_waitcnt lgkmcnt(0)
	v_mfma_f32_16x16x32_bf16 v[124:127], v[160:163], v[180:183], v[124:127]
	v_mfma_f32_16x16x32_bf16 v[120:123], v[172:175], v[180:183], v[120:123]
	v_mfma_f32_16x16x32_bf16 v[116:119], v[160:163], v[188:191], v[116:119]
	v_mfma_f32_16x16x32_bf16 v[112:115], v[172:175], v[188:191], v[112:115]
	v_mfma_f32_16x16x32_bf16 v[100:103], v[160:163], v[196:199], v[100:103]
	v_mfma_f32_16x16x32_bf16 v[96:99], v[172:175], v[196:199], v[96:99]
	v_mfma_f32_16x16x32_bf16 v[84:87], v[160:163], v[204:207], v[84:87]
	v_mfma_f32_16x16x32_bf16 v[80:83], v[172:175], v[204:207], v[80:83]
	v_mfma_f32_16x16x32_bf16 v[124:127], v[164:167], v[184:187], v[124:127]
	v_mfma_f32_16x16x32_bf16 v[120:123], v[176:179], v[184:187], v[120:123]
	v_mfma_f32_16x16x32_bf16 v[116:119], v[164:167], v[192:195], v[116:119]
	v_mfma_f32_16x16x32_bf16 v[112:115], v[176:179], v[192:195], v[112:115]
	v_mfma_f32_16x16x32_bf16 v[100:103], v[164:167], v[200:203], v[100:103]
	v_mfma_f32_16x16x32_bf16 v[96:99], v[176:179], v[200:203], v[96:99]
	v_mfma_f32_16x16x32_bf16 v[84:87], v[164:167], v[208:211], v[84:87]
	v_mfma_f32_16x16x32_bf16 v[80:83], v[176:179], v[208:211], v[80:83]
	s_setprio 0
	s_barrier
	s_add_i32 s28, 0, 0x1c000
	s_add_i32 s29, s56, s37
	v_add_u32_e32 v159, s28, v150
	v_lshl_add_u64 v[168:169], v[168:169], 0, s[2:3]
	s_mov_b32 m0, s29
	ds_read_b128 v[212:215], v159
	ds_read_b128 v[216:219], v159 offset:1024
	ds_read_b128 v[220:223], v159 offset:2048
	ds_read_b128 v[224:227], v159 offset:3072
	global_load_lds_dwordx4 v[168:169], off
	v_lshl_add_u64 v[168:169], v[228:229], 0, s[2:3]
	s_add_i32 m0, s29, 0x2000
	s_nop 0
	global_load_lds_dwordx4 v[168:169], off
	s_waitcnt vmcnt(10)
	s_barrier
	s_waitcnt lgkmcnt(0)
	s_setprio 1
	s_waitcnt lgkmcnt(0)
	v_mfma_f32_16x16x32_bf16 v[108:111], v[212:215], v[180:183], v[108:111]
	v_mfma_f32_16x16x32_bf16 v[104:107], v[220:223], v[180:183], v[104:107]
	v_mfma_f32_16x16x32_bf16 v[92:95], v[212:215], v[188:191], v[92:95]
	v_mfma_f32_16x16x32_bf16 v[88:91], v[220:223], v[188:191], v[88:91]
	v_mfma_f32_16x16x32_bf16 v[76:79], v[212:215], v[196:199], v[76:79]
	v_mfma_f32_16x16x32_bf16 v[72:75], v[220:223], v[196:199], v[72:75]
	v_mfma_f32_16x16x32_bf16 v[68:71], v[212:215], v[204:207], v[68:71]
	v_mfma_f32_16x16x32_bf16 v[64:67], v[220:223], v[204:207], v[64:67]
	v_mfma_f32_16x16x32_bf16 v[108:111], v[216:219], v[184:187], v[108:111]
	v_mfma_f32_16x16x32_bf16 v[104:107], v[224:227], v[184:187], v[104:107]
	v_mfma_f32_16x16x32_bf16 v[92:95], v[216:219], v[192:195], v[92:95]
	v_mfma_f32_16x16x32_bf16 v[88:91], v[224:227], v[192:195], v[88:91]
	v_mfma_f32_16x16x32_bf16 v[76:79], v[216:219], v[200:203], v[76:79]
	v_mfma_f32_16x16x32_bf16 v[72:75], v[224:227], v[200:203], v[72:75]
	v_mfma_f32_16x16x32_bf16 v[68:71], v[216:219], v[208:211], v[68:71]
	v_mfma_f32_16x16x32_bf16 v[64:67], v[224:227], v[208:211], v[64:67]
	s_setprio 0
	s_mov_b32 m0, s44
	v_lshl_add_u64 v[168:169], v[230:231], 0, s[2:3]
	s_barrier
	ds_read_b128 v[180:183], v157 offset:49152
	ds_read_b128 v[184:187], v157 offset:50176
	ds_read_b128 v[188:191], v157 offset:51200
	ds_read_b128 v[192:195], v157 offset:52224
	ds_read_b128 v[196:199], v157 offset:53248
	ds_read_b128 v[200:203], v157 offset:54272
	ds_read_b128 v[204:207], v157 offset:55296
	ds_read_b128 v[208:211], v157 offset:56320
	global_load_lds_dwordx4 v[168:169], off
	v_lshl_add_u64 v[168:169], v[232:233], 0, s[2:3]
	s_mov_b32 m0, s45
	s_nop 0
	global_load_lds_dwordx4 v[168:169], off
	s_barrier
	s_waitcnt lgkmcnt(0)
	s_setprio 1
	s_waitcnt lgkmcnt(0)
	v_mfma_f32_16x16x32_bf16 v[60:63], v[160:163], v[180:183], v[60:63]
	v_mfma_f32_16x16x32_bf16 v[56:59], v[172:175], v[180:183], v[56:59]
	v_mfma_f32_16x16x32_bf16 v[52:55], v[160:163], v[188:191], v[52:55]
	v_mfma_f32_16x16x32_bf16 v[48:51], v[172:175], v[188:191], v[48:51]
	v_mfma_f32_16x16x32_bf16 v[36:39], v[160:163], v[196:199], v[36:39]
	v_mfma_f32_16x16x32_bf16 v[32:35], v[172:175], v[196:199], v[32:35]
	v_mfma_f32_16x16x32_bf16 v[20:23], v[160:163], v[204:207], v[20:23]
	v_mfma_f32_16x16x32_bf16 v[16:19], v[172:175], v[204:207], v[16:19]
	v_mfma_f32_16x16x32_bf16 v[60:63], v[164:167], v[184:187], v[60:63]
	v_mfma_f32_16x16x32_bf16 v[56:59], v[176:179], v[184:187], v[56:59]
	v_mfma_f32_16x16x32_bf16 v[52:55], v[164:167], v[192:195], v[52:55]
	v_mfma_f32_16x16x32_bf16 v[48:51], v[176:179], v[192:195], v[48:51]
	v_mfma_f32_16x16x32_bf16 v[36:39], v[164:167], v[200:203], v[36:39]
	v_mfma_f32_16x16x32_bf16 v[32:35], v[176:179], v[200:203], v[32:35]
	v_mfma_f32_16x16x32_bf16 v[20:23], v[164:167], v[208:211], v[20:23]
	v_mfma_f32_16x16x32_bf16 v[16:19], v[176:179], v[208:211], v[16:19]
	s_setprio 0
	s_barrier
	s_add_u32 s26, s26, 0x80080
	s_addc_u32 s27, s27, 0
	s_add_i32 s28, s28, s37
	v_lshl_add_u64 v[160:161], s[26:27], 0, v[130:131]
	s_mov_b32 m0, s28
	s_nop 0
	global_load_lds_dwordx4 v[160:161], off
	v_lshl_add_u64 v[160:161], s[26:27], 0, v[134:135]
	s_add_i32 m0, s28, 0x2000
	s_nop 0
	global_load_lds_dwordx4 v[160:161], off
	s_waitcnt vmcnt(10)
	s_barrier
	s_setprio 1
	v_mfma_f32_16x16x32_bf16 v[44:47], v[212:215], v[180:183], v[44:47]
	v_mfma_f32_16x16x32_bf16 v[40:43], v[220:223], v[180:183], v[40:43]
	v_mfma_f32_16x16x32_bf16 v[28:31], v[212:215], v[188:191], v[28:31]
	v_mfma_f32_16x16x32_bf16 v[24:27], v[220:223], v[188:191], v[24:27]
	v_mfma_f32_16x16x32_bf16 v[12:15], v[212:215], v[196:199], v[12:15]
	v_mfma_f32_16x16x32_bf16 v[8:11], v[220:223], v[196:199], v[8:11]
	v_mfma_f32_16x16x32_bf16 v[4:7], v[212:215], v[204:207], v[4:7]
	v_mfma_f32_16x16x32_bf16 v[0:3], v[220:223], v[204:207], v[0:3]
	v_mfma_f32_16x16x32_bf16 v[44:47], v[216:219], v[184:187], v[44:47]
	v_mfma_f32_16x16x32_bf16 v[40:43], v[224:227], v[184:187], v[40:43]
	v_mfma_f32_16x16x32_bf16 v[28:31], v[216:219], v[192:195], v[28:31]
	v_mfma_f32_16x16x32_bf16 v[24:27], v[224:227], v[192:195], v[24:27]
	v_mfma_f32_16x16x32_bf16 v[12:15], v[216:219], v[200:203], v[12:15]
	v_mfma_f32_16x16x32_bf16 v[8:11], v[224:227], v[200:203], v[8:11]
	v_mfma_f32_16x16x32_bf16 v[4:7], v[216:219], v[208:211], v[4:7]
	v_mfma_f32_16x16x32_bf16 v[0:3], v[224:227], v[208:211], v[0:3]
	s_setprio 0
	s_add_i32 s55, s55, 2
	s_add_u32 s24, s24, 0x100
	s_addc_u32 s25, s25, 0
	s_add_u32 s53, s53, 0x100
	s_addc_u32 s54, s54, 0
	s_cmp_gt_u32 s55, 29
	s_barrier
	s_cbranch_scc0 .LBB0_504
	v_lshl_add_u32 v160, s12, 8, v149
	v_lshl_or_b32 v162, s50, 8, v151
	v_ashrrev_i32_e32 v161, 31, v160
	v_ashrrev_i32_e32 v163, 31, v162
	v_lshlrev_b64 v[164:165], 11, v[160:161]
	v_lshl_add_u64 v[164:165], s[0:1], 0, v[164:165]
	v_lshlrev_b64 v[162:163], 1, v[162:163]
	v_lshl_add_u64 v[164:165], v[164:165], 0, v[162:163]
	s_mov_b32 s12, 0x40000
	s_mov_b64 s[24:25], 0x40000
	v_cvt_pk_bf16_f32 v60, v60, v61
	v_cvt_pk_bf16_f32 v61, v62, v63
	v_cvt_pk_bf16_f32 v62, v56, v57
	v_add_co_u32_e32 v56, vcc, s12, v164
	v_cvt_pk_bf16_f32 v68, v68, v69
	v_cvt_pk_bf16_f32 v69, v70, v71
	v_cvt_pk_bf16_f32 v70, v64, v65
	v_lshl_add_u64 v[64:65], v[164:165], 0, s[24:25]
	v_addc_co_u32_e32 v57, vcc, 0, v165, vcc
	v_cvt_pk_bf16_f32 v44, v44, v45
	v_cvt_pk_bf16_f32 v45, v46, v47
	v_cvt_pk_bf16_f32 v46, v40, v41
	v_cvt_pk_bf16_f32 v47, v42, v43
	s_mov_b32 s12, 0x48000
	v_cvt_pk_bf16_f32 v108, v108, v109
	v_cvt_pk_bf16_f32 v109, v110, v111
	v_cvt_pk_bf16_f32 v110, v104, v105
	v_or_b32_e32 v104, 16, v160
	global_store_dwordx4 v[64:65], v[44:47], off offset:256
	s_mov_b64 s[24:25], 0x48000
	v_ashrrev_i32_e32 v105, 31, v104
	v_add_co_u32_e32 v46, vcc, s12, v164
	v_cvt_pk_bf16_f32 v92, v92, v93
	v_cvt_pk_bf16_f32 v93, v94, v95
	v_cvt_pk_bf16_f32 v94, v88, v89
	v_or_b32_e32 v88, 32, v160
	v_lshl_add_u64 v[44:45], v[164:165], 0, s[24:25]
	v_addc_co_u32_e32 v47, vcc, 0, v165, vcc
	v_cvt_pk_bf16_f32 v28, v28, v29
	v_cvt_pk_bf16_f32 v29, v30, v31
	v_cvt_pk_bf16_f32 v30, v24, v25
	v_cvt_pk_bf16_f32 v31, v26, v27
	s_mov_b32 s12, 0x50000
	v_lshlrev_b64 v[104:105], 11, v[104:105]
	v_ashrrev_i32_e32 v89, 31, v88
	v_cvt_pk_bf16_f32 v76, v76, v77
	v_cvt_pk_bf16_f32 v77, v78, v79
	v_cvt_pk_bf16_f32 v78, v72, v73
	v_or_b32_e32 v72, 48, v160
	global_store_dwordx4 v[44:45], v[28:31], off offset:256
	s_mov_b64 s[24:25], 0x50000
	v_cvt_pk_bf16_f32 v111, v106, v107
	v_add_co_u32_e32 v30, vcc, s12, v164
	v_lshl_add_u64 v[104:105], s[0:1], 0, v[104:105]
	v_lshlrev_b64 v[88:89], 11, v[88:89]
	v_ashrrev_i32_e32 v73, 31, v72
	v_lshl_add_u64 v[28:29], v[164:165], 0, s[24:25]
	v_addc_co_u32_e32 v31, vcc, 0, v165, vcc
	v_cvt_pk_bf16_f32 v12, v12, v13
	v_cvt_pk_bf16_f32 v13, v14, v15
	v_cvt_pk_bf16_f32 v14, v8, v9
	v_cvt_pk_bf16_f32 v15, v10, v11
	global_store_dwordx4 v[164:165], v[108:111], off offset:256
	v_cvt_pk_bf16_f32 v95, v90, v91
	v_lshl_add_u64 v[88:89], s[0:1], 0, v[88:89]
	v_lshl_add_u64 v[108:109], v[104:105], 0, v[162:163]
	v_lshlrev_b64 v[72:73], 11, v[72:73]
	global_store_dwordx4 v[28:29], v[12:15], off offset:256
	global_store_dwordx4 v[108:109], v[92:95], off offset:256
	v_cvt_pk_bf16_f32 v79, v74, v75
	v_add_co_u32_e32 v14, vcc, 0x58000, v164
	v_lshl_add_u64 v[92:93], v[88:89], 0, v[162:163]
	v_lshl_add_u64 v[72:73], s[0:1], 0, v[72:73]
	s_mov_b64 s[24:25], 0x58000
	v_addc_co_u32_e32 v15, vcc, 0, v165, vcc
	v_cvt_pk_bf16_f32 v124, v124, v125
	v_cvt_pk_bf16_f32 v125, v126, v127
	v_cvt_pk_bf16_f32 v126, v120, v121
	v_cvt_pk_bf16_f32 v127, v122, v123
	v_cvt_pk_bf16_f32 v104, v116, v117
	v_cvt_pk_bf16_f32 v105, v118, v119
	v_cvt_pk_bf16_f32 v106, v112, v113
	v_cvt_pk_bf16_f32 v107, v114, v115
	v_cvt_pk_bf16_f32 v88, v100, v101
	v_cvt_pk_bf16_f32 v89, v102, v103
	v_cvt_pk_bf16_f32 v90, v96, v97
	v_cvt_pk_bf16_f32 v91, v98, v99
	global_store_dwordx4 v[92:93], v[76:79], off offset:256
	v_cvt_pk_bf16_f32 v74, v80, v81
	v_cvt_pk_bf16_f32 v75, v82, v83
	v_lshl_add_u64 v[76:77], v[72:73], 0, v[162:163]
	v_cvt_pk_bf16_f32 v72, v84, v85
	v_cvt_pk_bf16_f32 v73, v86, v87
	v_cvt_pk_bf16_f32 v71, v66, v67
	v_cvt_pk_bf16_f32 v63, v58, v59
	v_cvt_pk_bf16_f32 v40, v52, v53
	v_cvt_pk_bf16_f32 v41, v54, v55
	v_cvt_pk_bf16_f32 v42, v48, v49
	v_cvt_pk_bf16_f32 v43, v50, v51
	v_cvt_pk_bf16_f32 v24, v36, v37
	v_cvt_pk_bf16_f32 v25, v38, v39
	v_cvt_pk_bf16_f32 v26, v32, v33
	v_cvt_pk_bf16_f32 v27, v34, v35
	v_lshl_add_u64 v[12:13], v[164:165], 0, s[24:25]
	v_cvt_pk_bf16_f32 v8, v20, v21
	v_cvt_pk_bf16_f32 v9, v22, v23
	v_cvt_pk_bf16_f32 v10, v16, v17
	v_cvt_pk_bf16_f32 v11, v18, v19
	v_cvt_pk_bf16_f32 v4, v4, v5
	v_cvt_pk_bf16_f32 v5, v6, v7
	v_cvt_pk_bf16_f32 v6, v0, v1
	v_cvt_pk_bf16_f32 v7, v2, v3
	s_and_b64 vcc, exec, s[14:15]
	s_mov_b32 s50, s16
	s_mov_b32 s12, s18
	s_mov_b64 s[26:27], s[22:23]
	s_mov_b64 s[24:25], s[20:21]
	global_store_dwordx4 v[164:165], v[124:127], off
	global_store_dwordx4 v[108:109], v[104:107], off
	global_store_dwordx4 v[92:93], v[88:91], off
	global_store_dwordx4 v[76:77], v[72:75], off
	global_store_dwordx4 v[76:77], v[68:71], off offset:256
	global_store_dwordx4 v[56:57], v[60:63], off
	global_store_dwordx4 v[46:47], v[40:43], off
	global_store_dwordx4 v[30:31], v[24:27], off
	global_store_dwordx4 v[14:15], v[8:11], off
	global_store_dwordx4 v[12:13], v[4:7], off offset:256
	s_cbranch_vccz .LBB0_497
	s_waitcnt vmcnt(0)
	s_cmpk_gt_u32 s30, 0xff
	s_cbranch_scc1 .LBB0_508
	s_barrier

.LBB0_517:
	ds_read_b128 v[64:67], v175
	ds_read_b128 v[68:71], v175 offset:1024
	ds_read_b128 v[80:83], v175 offset:2048
	ds_read_b128 v[84:87], v175 offset:3072
	s_add_u32 s34, s30, 0xfffe0080
	s_addc_u32 s35, s31, -1
	s_cmp_eq_u32 s80, 0
	s_cselect_b32 s37, s1, s35
	s_cselect_b32 s36, s25, s34
	s_cselect_b32 s35, s23, s67
	s_cselect_b32 s34, s65, s66
	v_lshl_add_u64 v[204:205], s[30:31], 0, v[154:155]
	s_add_i32 m0, s46, 0xc000
	ds_read_b128 v[162:165], v176
	ds_read_b128 v[166:169], v176 offset:1024
	ds_read_b128 v[180:183], v176 offset:2048
	ds_read_b128 v[184:187], v176 offset:3072
	ds_read_b128 v[188:191], v176 offset:4096
	ds_read_b128 v[192:195], v176 offset:5120
	ds_read_b128 v[196:199], v176 offset:6144
	ds_read_b128 v[200:203], v176 offset:7168
	global_load_lds_dwordx4 v[204:205], off
	v_lshl_add_u64 v[204:205], s[30:31], 0, v[156:157]
	s_add_i32 m0, s46, 0xe000
	s_nop 0
	global_load_lds_dwordx4 v[204:205], off
	s_waitcnt vmcnt(10)
	s_waitcnt lgkmcnt(8)
	s_barrier
	s_waitcnt lgkmcnt(0)
	s_setprio 1
	s_waitcnt lgkmcnt(0)
	v_mfma_f32_16x16x32_bf16 v[140:143], v[64:67], v[162:165], v[140:143]
	v_mfma_f32_16x16x32_bf16 v[136:139], v[80:83], v[162:165], v[136:139]
	v_mfma_f32_16x16x32_bf16 v[124:127], v[64:67], v[180:183], v[124:127]
	v_mfma_f32_16x16x32_bf16 v[120:123], v[80:83], v[180:183], v[120:123]
	v_mfma_f32_16x16x32_bf16 v[108:111], v[64:67], v[188:191], v[108:111]
	v_mfma_f32_16x16x32_bf16 v[104:107], v[80:83], v[188:191], v[104:107]
	v_mfma_f32_16x16x32_bf16 v[92:95], v[64:67], v[196:199], v[92:95]
	v_mfma_f32_16x16x32_bf16 v[88:91], v[80:83], v[196:199], v[88:91]
	v_mfma_f32_16x16x32_bf16 v[140:143], v[68:71], v[166:169], v[140:143]
	v_mfma_f32_16x16x32_bf16 v[136:139], v[84:87], v[166:169], v[136:139]
	v_mfma_f32_16x16x32_bf16 v[124:127], v[68:71], v[184:187], v[124:127]
	v_mfma_f32_16x16x32_bf16 v[120:123], v[84:87], v[184:187], v[120:123]
	v_mfma_f32_16x16x32_bf16 v[108:111], v[68:71], v[192:195], v[108:111]
	v_mfma_f32_16x16x32_bf16 v[104:107], v[84:87], v[192:195], v[104:107]
	v_mfma_f32_16x16x32_bf16 v[92:95], v[68:71], v[200:203], v[92:95]
	v_mfma_f32_16x16x32_bf16 v[88:91], v[84:87], v[200:203], v[88:91]
	s_setprio 0
	s_barrier
	s_add_i32 s81, s55, s43
	v_lshl_add_u64 v[220:221], s[34:35], 0, v[148:149]
	s_mov_b32 m0, s81
	ds_read_b128 v[204:207], v177
	ds_read_b128 v[208:211], v177 offset:1024
	ds_read_b128 v[212:215], v177 offset:2048
	ds_read_b128 v[216:219], v177 offset:3072
	global_load_lds_dwordx4 v[220:221], off
	v_lshl_add_u64 v[222:223], s[34:35], 0, v[144:145]
	s_add_i32 m0, s81, 0x2000
	s_nop 0
	global_load_lds_dwordx4 v[222:223], off
	s_waitcnt vmcnt(10)
	s_barrier
	s_waitcnt lgkmcnt(0)
	s_setprio 1
	s_waitcnt lgkmcnt(0)
	v_mfma_f32_16x16x32_bf16 v[132:135], v[204:207], v[162:165], v[132:135]
	v_mfma_f32_16x16x32_bf16 v[128:131], v[212:215], v[162:165], v[128:131]
	v_mfma_f32_16x16x32_bf16 v[116:119], v[204:207], v[180:183], v[116:119]
	v_mfma_f32_16x16x32_bf16 v[112:115], v[212:215], v[180:183], v[112:115]
	v_mfma_f32_16x16x32_bf16 v[100:103], v[204:207], v[188:191], v[100:103]
	v_mfma_f32_16x16x32_bf16 v[96:99], v[212:215], v[188:191], v[96:99]
	v_mfma_f32_16x16x32_bf16 v[76:79], v[204:207], v[196:199], v[76:79]
	v_mfma_f32_16x16x32_bf16 v[72:75], v[212:215], v[196:199], v[72:75]
	v_mfma_f32_16x16x32_bf16 v[132:135], v[208:211], v[166:169], v[132:135]
	v_mfma_f32_16x16x32_bf16 v[128:131], v[216:219], v[166:169], v[128:131]
	v_mfma_f32_16x16x32_bf16 v[116:119], v[208:211], v[184:187], v[116:119]
	v_mfma_f32_16x16x32_bf16 v[112:115], v[216:219], v[184:187], v[112:115]
	v_mfma_f32_16x16x32_bf16 v[100:103], v[208:211], v[192:195], v[100:103]
	v_mfma_f32_16x16x32_bf16 v[96:99], v[216:219], v[192:195], v[96:99]
	v_mfma_f32_16x16x32_bf16 v[76:79], v[208:211], v[200:203], v[76:79]
	v_mfma_f32_16x16x32_bf16 v[72:75], v[216:219], v[200:203], v[72:75]
	s_setprio 0
	s_mov_b32 m0, s46
	v_lshl_add_u64 v[224:225], s[36:37], 0, v[150:151]
	s_barrier
	ds_read_b128 v[162:165], v176 offset:16384
	ds_read_b128 v[166:169], v176 offset:17408
	ds_read_b128 v[180:183], v176 offset:18432
	ds_read_b128 v[184:187], v176 offset:19456
	ds_read_b128 v[188:191], v176 offset:20480
	ds_read_b128 v[192:195], v176 offset:21504
	ds_read_b128 v[196:199], v176 offset:22528
	ds_read_b128 v[200:203], v176 offset:23552
	global_load_lds_dwordx4 v[224:225], off
	v_lshl_add_u64 v[226:227], s[36:37], 0, v[146:147]
	s_mov_b32 m0, s47
	s_nop 0
	global_load_lds_dwordx4 v[226:227], off
	s_barrier
	s_waitcnt lgkmcnt(0)
	s_setprio 1
	s_waitcnt lgkmcnt(0)
	v_mfma_f32_16x16x32_bf16 v[60:63], v[64:67], v[162:165], v[60:63]
	v_mfma_f32_16x16x32_bf16 v[56:59], v[80:83], v[162:165], v[56:59]
	v_mfma_f32_16x16x32_bf16 v[44:47], v[64:67], v[180:183], v[44:47]
	v_mfma_f32_16x16x32_bf16 v[40:43], v[80:83], v[180:183], v[40:43]
	v_mfma_f32_16x16x32_bf16 v[28:31], v[64:67], v[188:191], v[28:31]
	v_mfma_f32_16x16x32_bf16 v[24:27], v[80:83], v[188:191], v[24:27]
	v_mfma_f32_16x16x32_bf16 v[12:15], v[64:67], v[196:199], v[12:15]
	v_mfma_f32_16x16x32_bf16 v[8:11], v[80:83], v[196:199], v[8:11]
	v_mfma_f32_16x16x32_bf16 v[60:63], v[68:71], v[166:169], v[60:63]
	v_mfma_f32_16x16x32_bf16 v[56:59], v[84:87], v[166:169], v[56:59]
	v_mfma_f32_16x16x32_bf16 v[44:47], v[68:71], v[184:187], v[44:47]
	v_mfma_f32_16x16x32_bf16 v[40:43], v[84:87], v[184:187], v[40:43]
	v_mfma_f32_16x16x32_bf16 v[28:31], v[68:71], v[192:195], v[28:31]
	v_mfma_f32_16x16x32_bf16 v[24:27], v[84:87], v[192:195], v[24:27]
	v_mfma_f32_16x16x32_bf16 v[12:15], v[68:71], v[200:203], v[12:15]
	v_mfma_f32_16x16x32_bf16 v[8:11], v[84:87], v[200:203], v[8:11]
	s_setprio 0
	s_barrier
	s_add_u32 s82, s34, 0x20000
	s_addc_u32 s83, s35, 0
	s_add_i32 s81, s56, s43
	v_lshl_add_u64 v[64:65], s[82:83], 0, v[148:149]
	s_mov_b32 m0, s81
	s_nop 0
	global_load_lds_dwordx4 v[64:65], off
	v_lshl_add_u64 v[64:65], s[82:83], 0, v[144:145]
	s_add_i32 m0, s81, 0x2000
	s_nop 0
	global_load_lds_dwordx4 v[64:65], off
	s_waitcnt vmcnt(10)
	s_barrier
	s_setprio 1
	v_mfma_f32_16x16x32_bf16 v[52:55], v[204:207], v[162:165], v[52:55]
	v_mfma_f32_16x16x32_bf16 v[48:51], v[212:215], v[162:165], v[48:51]
	v_mfma_f32_16x16x32_bf16 v[36:39], v[204:207], v[180:183], v[36:39]
	v_mfma_f32_16x16x32_bf16 v[32:35], v[212:215], v[180:183], v[32:35]
	v_mfma_f32_16x16x32_bf16 v[20:23], v[204:207], v[188:191], v[20:23]
	v_mfma_f32_16x16x32_bf16 v[16:19], v[212:215], v[188:191], v[16:19]
	v_mfma_f32_16x16x32_bf16 v[4:7], v[204:207], v[196:199], v[4:7]
	v_mfma_f32_16x16x32_bf16 v[0:3], v[212:215], v[196:199], v[0:3]
	v_mfma_f32_16x16x32_bf16 v[52:55], v[208:211], v[166:169], v[52:55]
	v_mfma_f32_16x16x32_bf16 v[48:51], v[216:219], v[166:169], v[48:51]
	v_mfma_f32_16x16x32_bf16 v[36:39], v[208:211], v[184:187], v[36:39]
	v_mfma_f32_16x16x32_bf16 v[32:35], v[216:219], v[184:187], v[32:35]
	v_mfma_f32_16x16x32_bf16 v[20:23], v[208:211], v[192:195], v[20:23]
	v_mfma_f32_16x16x32_bf16 v[16:19], v[216:219], v[192:195], v[16:19]
	v_mfma_f32_16x16x32_bf16 v[4:7], v[208:211], v[200:203], v[4:7]
	v_mfma_f32_16x16x32_bf16 v[0:3], v[216:219], v[200:203], v[0:3]
	s_setprio 0
	s_add_i32 s81, 0, 0x18000
	v_add_u32_e32 v84, s81, v173
	s_barrier
	ds_read_b128 v[64:67], v84
	ds_read_b128 v[68:71], v84 offset:1024
	ds_read_b128 v[80:83], v84 offset:2048
	ds_read_b128 v[84:87], v84 offset:3072
	s_add_u32 s36, s36, 0x20000
	s_addc_u32 s37, s37, 0
	s_mov_b32 m0, s48
	v_lshl_add_u64 v[204:205], s[36:37], 0, v[150:151]
	ds_read_b128 v[162:165], v176 offset:32768
	ds_read_b128 v[166:169], v176 offset:33792
	ds_read_b128 v[180:183], v176 offset:34816
	ds_read_b128 v[184:187], v176 offset:35840
	ds_read_b128 v[188:191], v176 offset:36864
	ds_read_b128 v[192:195], v176 offset:37888
	ds_read_b128 v[196:199], v176 offset:38912
	ds_read_b128 v[200:203], v176 offset:39936
	global_load_lds_dwordx4 v[204:205], off
	v_lshl_add_u64 v[204:205], s[36:37], 0, v[146:147]
	s_mov_b32 m0, s49
	s_nop 0
	global_load_lds_dwordx4 v[204:205], off
	s_waitcnt vmcnt(10)
	s_waitcnt lgkmcnt(8)
	s_barrier
	s_waitcnt lgkmcnt(0)
	s_setprio 1
	s_waitcnt lgkmcnt(0)
	v_mfma_f32_16x16x32_bf16 v[140:143], v[64:67], v[162:165], v[140:143]
	v_mfma_f32_16x16x32_bf16 v[136:139], v[80:83], v[162:165], v[136:139]
	v_mfma_f32_16x16x32_bf16 v[124:127], v[64:67], v[180:183], v[124:127]
	v_mfma_f32_16x16x32_bf16 v[120:123], v[80:83], v[180:183], v[120:123]
	v_mfma_f32_16x16x32_bf16 v[108:111], v[64:67], v[188:191], v[108:111]
	v_mfma_f32_16x16x32_bf16 v[104:107], v[80:83], v[188:191], v[104:107]
	v_mfma_f32_16x16x32_bf16 v[92:95], v[64:67], v[196:199], v[92:95]
	v_mfma_f32_16x16x32_bf16 v[88:91], v[80:83], v[196:199], v[88:91]
	v_mfma_f32_16x16x32_bf16 v[140:143], v[68:71], v[166:169], v[140:143]
	v_mfma_f32_16x16x32_bf16 v[136:139], v[84:87], v[166:169], v[136:139]
	v_mfma_f32_16x16x32_bf16 v[124:127], v[68:71], v[184:187], v[124:127]
	v_mfma_f32_16x16x32_bf16 v[120:123], v[84:87], v[184:187], v[120:123]
	v_mfma_f32_16x16x32_bf16 v[108:111], v[68:71], v[192:195], v[108:111]
	v_mfma_f32_16x16x32_bf16 v[104:107], v[84:87], v[192:195], v[104:107]
	v_mfma_f32_16x16x32_bf16 v[92:95], v[68:71], v[200:203], v[92:95]
	v_mfma_f32_16x16x32_bf16 v[88:91], v[84:87], v[200:203], v[88:91]
	s_setprio 0
	s_barrier
	s_add_i32 s36, 0, 0x1c000
	s_add_i32 s37, s81, s43
	v_add_u32_e32 v152, s36, v173
	v_lshl_add_u64 v[220:221], v[220:221], 0, s[12:13]
	s_mov_b32 m0, s37
	ds_read_b128 v[204:207], v152
	ds_read_b128 v[208:211], v152 offset:1024
	ds_read_b128 v[212:215], v152 offset:2048
	ds_read_b128 v[216:219], v152 offset:3072
	global_load_lds_dwordx4 v[220:221], off
	v_lshl_add_u64 v[220:221], v[222:223], 0, s[12:13]
	s_add_i32 m0, s37, 0x2000
	s_nop 0
	global_load_lds_dwordx4 v[220:221], off
	s_waitcnt vmcnt(10)
	s_barrier
	s_waitcnt lgkmcnt(0)
	s_setprio 1
	s_waitcnt lgkmcnt(0)
	v_mfma_f32_16x16x32_bf16 v[132:135], v[204:207], v[162:165], v[132:135]
	v_mfma_f32_16x16x32_bf16 v[128:131], v[212:215], v[162:165], v[128:131]
	v_mfma_f32_16x16x32_bf16 v[116:119], v[204:207], v[180:183], v[116:119]
	v_mfma_f32_16x16x32_bf16 v[112:115], v[212:215], v[180:183], v[112:115]
	v_mfma_f32_16x16x32_bf16 v[100:103], v[204:207], v[188:191], v[100:103]
	v_mfma_f32_16x16x32_bf16 v[96:99], v[212:215], v[188:191], v[96:99]
	v_mfma_f32_16x16x32_bf16 v[76:79], v[204:207], v[196:199], v[76:79]
	v_mfma_f32_16x16x32_bf16 v[72:75], v[212:215], v[196:199], v[72:75]
	v_mfma_f32_16x16x32_bf16 v[132:135], v[208:211], v[166:169], v[132:135]
	v_mfma_f32_16x16x32_bf16 v[128:131], v[216:219], v[166:169], v[128:131]
	v_mfma_f32_16x16x32_bf16 v[116:119], v[208:211], v[184:187], v[116:119]
	v_mfma_f32_16x16x32_bf16 v[112:115], v[216:219], v[184:187], v[112:115]
	v_mfma_f32_16x16x32_bf16 v[100:103], v[208:211], v[192:195], v[100:103]
	v_mfma_f32_16x16x32_bf16 v[96:99], v[216:219], v[192:195], v[96:99]
	v_mfma_f32_16x16x32_bf16 v[76:79], v[208:211], v[200:203], v[76:79]
	v_mfma_f32_16x16x32_bf16 v[72:75], v[216:219], v[200:203], v[72:75]
	s_setprio 0
	s_mov_b32 m0, s51
	v_lshl_add_u64 v[220:221], v[224:225], 0, s[12:13]
	s_barrier
	ds_read_b128 v[162:165], v176 offset:49152
	ds_read_b128 v[166:169], v176 offset:50176
	ds_read_b128 v[180:183], v176 offset:51200
	ds_read_b128 v[184:187], v176 offset:52224
	ds_read_b128 v[188:191], v176 offset:53248
	ds_read_b128 v[192:195], v176 offset:54272
	ds_read_b128 v[196:199], v176 offset:55296
	ds_read_b128 v[200:203], v176 offset:56320
	global_load_lds_dwordx4 v[220:221], off
	v_lshl_add_u64 v[220:221], v[226:227], 0, s[12:13]
	s_mov_b32 m0, s52
	s_nop 0
	global_load_lds_dwordx4 v[220:221], off
	s_barrier
	s_waitcnt lgkmcnt(0)
	s_setprio 1
	s_waitcnt lgkmcnt(0)
	v_mfma_f32_16x16x32_bf16 v[60:63], v[64:67], v[162:165], v[60:63]
	v_mfma_f32_16x16x32_bf16 v[56:59], v[80:83], v[162:165], v[56:59]
	v_mfma_f32_16x16x32_bf16 v[44:47], v[64:67], v[180:183], v[44:47]
	v_mfma_f32_16x16x32_bf16 v[40:43], v[80:83], v[180:183], v[40:43]
	v_mfma_f32_16x16x32_bf16 v[28:31], v[64:67], v[188:191], v[28:31]
	v_mfma_f32_16x16x32_bf16 v[24:27], v[80:83], v[188:191], v[24:27]
	v_mfma_f32_16x16x32_bf16 v[12:15], v[64:67], v[196:199], v[12:15]
	v_mfma_f32_16x16x32_bf16 v[8:11], v[80:83], v[196:199], v[8:11]
	v_mfma_f32_16x16x32_bf16 v[60:63], v[68:71], v[166:169], v[60:63]
	v_mfma_f32_16x16x32_bf16 v[56:59], v[84:87], v[166:169], v[56:59]
	v_mfma_f32_16x16x32_bf16 v[44:47], v[68:71], v[184:187], v[44:47]
	v_mfma_f32_16x16x32_bf16 v[40:43], v[84:87], v[184:187], v[40:43]
	v_mfma_f32_16x16x32_bf16 v[28:31], v[68:71], v[192:195], v[28:31]
	v_mfma_f32_16x16x32_bf16 v[24:27], v[84:87], v[192:195], v[24:27]
	v_mfma_f32_16x16x32_bf16 v[12:15], v[68:71], v[200:203], v[12:15]
	v_mfma_f32_16x16x32_bf16 v[8:11], v[84:87], v[200:203], v[8:11]
	s_setprio 0
	s_barrier
	s_add_u32 s34, s34, 0x20080
	s_addc_u32 s35, s35, 0
	s_add_i32 s36, s36, s43
	v_lshl_add_u64 v[64:65], s[34:35], 0, v[148:149]
	s_mov_b32 m0, s36
	s_nop 0
	global_load_lds_dwordx4 v[64:65], off
	v_lshl_add_u64 v[64:65], s[34:35], 0, v[144:145]
	s_add_i32 m0, s36, 0x2000
	s_nop 0
	global_load_lds_dwordx4 v[64:65], off
	s_waitcnt vmcnt(10)
	s_barrier
	s_setprio 1
	v_mfma_f32_16x16x32_bf16 v[52:55], v[204:207], v[162:165], v[52:55]
	v_mfma_f32_16x16x32_bf16 v[48:51], v[212:215], v[162:165], v[48:51]
	v_mfma_f32_16x16x32_bf16 v[36:39], v[204:207], v[180:183], v[36:39]
	v_mfma_f32_16x16x32_bf16 v[32:35], v[212:215], v[180:183], v[32:35]
	v_mfma_f32_16x16x32_bf16 v[20:23], v[204:207], v[188:191], v[20:23]
	v_mfma_f32_16x16x32_bf16 v[16:19], v[212:215], v[188:191], v[16:19]
	v_mfma_f32_16x16x32_bf16 v[4:7], v[204:207], v[196:199], v[4:7]
	v_mfma_f32_16x16x32_bf16 v[0:3], v[212:215], v[196:199], v[0:3]
	v_mfma_f32_16x16x32_bf16 v[52:55], v[208:211], v[166:169], v[52:55]
	v_mfma_f32_16x16x32_bf16 v[48:51], v[216:219], v[166:169], v[48:51]
	v_mfma_f32_16x16x32_bf16 v[36:39], v[208:211], v[184:187], v[36:39]
	v_mfma_f32_16x16x32_bf16 v[32:35], v[216:219], v[184:187], v[32:35]
	v_mfma_f32_16x16x32_bf16 v[20:23], v[208:211], v[192:195], v[20:23]
	v_mfma_f32_16x16x32_bf16 v[16:19], v[216:219], v[192:195], v[16:19]
	v_mfma_f32_16x16x32_bf16 v[4:7], v[208:211], v[200:203], v[4:7]
	v_mfma_f32_16x16x32_bf16 v[0:3], v[216:219], v[200:203], v[0:3]
	s_setprio 0
	s_add_i32 s80, s80, 2
	s_add_u32 s30, s30, 0x100
	s_addc_u32 s31, s31, 0
	s_add_u32 s66, s66, 0x100
	s_addc_u32 s67, s67, 0
	s_cmp_gt_u32 s80, 1
	s_barrier
	s_cbranch_scc0 .LBB0_517
	v_lshl_add_u32 v164, s0, 8, v172
	s_lshl_b32 s0, s33, 8
	s_and_b32 s0, s0, 0x300
	v_or_b32_e32 v179, s0, v174
	s_cmp_gt_u32 s33, 3
	s_mov_b64 s[0:1], -1
	s_cbranch_scc0 .LBB0_524
	s_cmp_gt_u32 s33, 7
	s_cbranch_scc0 .LBB0_521
	v_lshlrev_b32_e32 v152, 1, v179
	v_ashrrev_i32_e32 v165, 31, v164
	v_lshl_add_u64 v[70:71], s[10:11], 0, v[152:153]
	v_lshlrev_b64 v[64:65], 11, v[164:165]
	v_pk_add_f32 v[68:69], v[142:143], 0 op_sel_hi:[1,0]
	v_pk_add_f32 v[66:67], v[140:141], 0 op_sel_hi:[1,0]
	v_pk_add_f32 v[80:81], v[138:139], 0 op_sel_hi:[1,0]
	v_pk_add_f32 v[82:83], v[136:137], 0 op_sel_hi:[1,0]
	v_lshl_add_u64 v[64:65], v[70:71], 0, v[64:65]
	v_cvt_pk_bf16_f32 v66, v66, v67
	v_cvt_pk_bf16_f32 v67, v68, v69
	v_cvt_pk_bf16_f32 v68, v82, v83
	v_cvt_pk_bf16_f32 v69, v80, v81
	global_store_dwordx4 v[64:65], v[66:69], off
	v_pk_add_f32 v[80:81], v[130:131], 0 op_sel_hi:[1,0]
	v_pk_add_f32 v[82:83], v[128:129], 0 op_sel_hi:[1,0]
	v_pk_add_f32 v[68:69], v[134:135], 0 op_sel_hi:[1,0]
	v_pk_add_f32 v[66:67], v[132:133], 0 op_sel_hi:[1,0]
	v_pk_add_f32 v[84:85], v[120:121], 0 op_sel_hi:[1,0]
	v_cvt_pk_bf16_f32 v66, v66, v67
	v_cvt_pk_bf16_f32 v67, v68, v69
	v_cvt_pk_bf16_f32 v68, v82, v83
	v_cvt_pk_bf16_f32 v69, v80, v81
	global_store_dwordx4 v[64:65], v[66:69], off offset:256
	v_pk_add_f32 v[82:83], v[122:123], 0 op_sel_hi:[1,0]
	v_lshl_add_u64 v[166:167], v[64:65], 0, s[20:21]
	v_or_b32_e32 v66, 16, v164
	v_ashrrev_i32_e32 v67, 31, v66
	v_lshlrev_b64 v[66:67], 11, v[66:67]
	v_lshl_add_u64 v[80:81], v[70:71], 0, v[66:67]
	v_pk_add_f32 v[68:69], v[126:127], 0 op_sel_hi:[1,0]
	v_pk_add_f32 v[66:67], v[124:125], 0 op_sel_hi:[1,0]
	s_mov_b64 s[0:1], 0
	v_cvt_pk_bf16_f32 v66, v66, v67
	v_cvt_pk_bf16_f32 v67, v68, v69
	v_cvt_pk_bf16_f32 v68, v84, v85
	v_cvt_pk_bf16_f32 v69, v82, v83
	global_store_dwordx4 v[80:81], v[66:69], off
	v_pk_add_f32 v[82:83], v[114:115], 0 op_sel_hi:[1,0]
	v_pk_add_f32 v[84:85], v[112:113], 0 op_sel_hi:[1,0]
	v_pk_add_f32 v[68:69], v[118:119], 0 op_sel_hi:[1,0]
	v_pk_add_f32 v[66:67], v[116:117], 0 op_sel_hi:[1,0]
	s_nop 0
	v_cvt_pk_bf16_f32 v66, v66, v67
	v_cvt_pk_bf16_f32 v67, v68, v69
	v_cvt_pk_bf16_f32 v68, v84, v85
	v_cvt_pk_bf16_f32 v69, v82, v83
	global_store_dwordx4 v[80:81], v[66:69], off offset:256
	v_pk_add_f32 v[82:83], v[106:107], 0 op_sel_hi:[1,0]
	v_pk_add_f32 v[84:85], v[104:105], 0 op_sel_hi:[1,0]
	v_or_b32_e32 v66, 32, v164
	v_ashrrev_i32_e32 v67, 31, v66
	v_lshlrev_b64 v[66:67], 11, v[66:67]
	v_lshl_add_u64 v[80:81], v[70:71], 0, v[66:67]
	v_pk_add_f32 v[68:69], v[110:111], 0 op_sel_hi:[1,0]
	v_pk_add_f32 v[66:67], v[108:109], 0 op_sel_hi:[1,0]
	s_nop 0
	v_cvt_pk_bf16_f32 v66, v66, v67
	v_cvt_pk_bf16_f32 v67, v68, v69
	v_cvt_pk_bf16_f32 v68, v84, v85
	v_cvt_pk_bf16_f32 v69, v82, v83
	global_store_dwordx4 v[80:81], v[66:69], off
	v_pk_add_f32 v[82:83], v[98:99], 0 op_sel_hi:[1,0]
	v_pk_add_f32 v[84:85], v[96:97], 0 op_sel_hi:[1,0]
	v_pk_add_f32 v[68:69], v[102:103], 0 op_sel_hi:[1,0]
	v_pk_add_f32 v[66:67], v[100:101], 0 op_sel_hi:[1,0]
	s_nop 0
	v_cvt_pk_bf16_f32 v66, v66, v67
	v_cvt_pk_bf16_f32 v67, v68, v69
	v_cvt_pk_bf16_f32 v68, v84, v85
	v_cvt_pk_bf16_f32 v69, v82, v83
	global_store_dwordx4 v[80:81], v[66:69], off offset:256
	v_pk_add_f32 v[80:81], v[90:91], 0 op_sel_hi:[1,0]
	v_pk_add_f32 v[82:83], v[88:89], 0 op_sel_hi:[1,0]
	v_or_b32_e32 v66, 48, v164
	v_ashrrev_i32_e32 v67, 31, v66
	v_lshlrev_b64 v[66:67], 11, v[66:67]
	v_lshl_add_u64 v[70:71], v[70:71], 0, v[66:67]
	v_pk_add_f32 v[68:69], v[94:95], 0 op_sel_hi:[1,0]
	v_pk_add_f32 v[66:67], v[92:93], 0 op_sel_hi:[1,0]
	s_nop 0
	v_cvt_pk_bf16_f32 v66, v66, v67
	v_cvt_pk_bf16_f32 v67, v68, v69
	v_cvt_pk_bf16_f32 v68, v82, v83
	v_cvt_pk_bf16_f32 v69, v80, v81
	global_store_dwordx4 v[70:71], v[66:69], off
	v_pk_add_f32 v[80:81], v[74:75], 0 op_sel_hi:[1,0]
	v_pk_add_f32 v[82:83], v[72:73], 0 op_sel_hi:[1,0]
	v_pk_add_f32 v[68:69], v[78:79], 0 op_sel_hi:[1,0]
	v_pk_add_f32 v[66:67], v[76:77], 0 op_sel_hi:[1,0]
	s_nop 0
	v_cvt_pk_bf16_f32 v66, v66, v67
	v_cvt_pk_bf16_f32 v67, v68, v69
	v_cvt_pk_bf16_f32 v68, v82, v83
	v_cvt_pk_bf16_f32 v69, v80, v81
	global_store_dwordx4 v[70:71], v[66:69], off offset:256
	v_pk_add_f32 v[80:81], v[58:59], 0 op_sel_hi:[1,0]
	v_pk_add_f32 v[82:83], v[56:57], 0 op_sel_hi:[1,0]
	v_pk_add_f32 v[68:69], v[62:63], 0 op_sel_hi:[1,0]
	v_pk_add_f32 v[66:67], v[60:61], 0 op_sel_hi:[1,0]
	v_lshl_add_u64 v[70:71], v[64:65], 0, s[14:15]
	v_cvt_pk_bf16_f32 v66, v66, v67
	v_cvt_pk_bf16_f32 v67, v68, v69
	v_cvt_pk_bf16_f32 v69, v80, v81
	v_add_co_u32_e32 v80, vcc, s57, v64
	v_cvt_pk_bf16_f32 v68, v82, v83
	s_nop 0
	v_addc_co_u32_e32 v81, vcc, 0, v65, vcc
	global_store_dwordx4 v[80:81], v[66:69], off
	v_pk_add_f32 v[80:81], v[50:51], 0 op_sel_hi:[1,0]
	v_pk_add_f32 v[82:83], v[48:49], 0 op_sel_hi:[1,0]
	v_pk_add_f32 v[68:69], v[54:55], 0 op_sel_hi:[1,0]
	v_pk_add_f32 v[66:67], v[52:53], 0 op_sel_hi:[1,0]
	s_nop 0
	v_cvt_pk_bf16_f32 v66, v66, v67
	v_cvt_pk_bf16_f32 v67, v68, v69
	v_cvt_pk_bf16_f32 v68, v82, v83
	v_cvt_pk_bf16_f32 v69, v80, v81
	global_store_dwordx4 v[70:71], v[66:69], off offset:256
	v_pk_add_f32 v[80:81], v[42:43], 0 op_sel_hi:[1,0]
	v_pk_add_f32 v[82:83], v[40:41], 0 op_sel_hi:[1,0]
	v_pk_add_f32 v[68:69], v[46:47], 0 op_sel_hi:[1,0]
	v_pk_add_f32 v[66:67], v[44:45], 0 op_sel_hi:[1,0]
	v_lshl_add_u64 v[70:71], v[64:65], 0, s[16:17]
	v_cvt_pk_bf16_f32 v66, v66, v67
	v_cvt_pk_bf16_f32 v67, v68, v69
	v_cvt_pk_bf16_f32 v69, v80, v81
	v_add_co_u32_e32 v80, vcc, s58, v64
	v_cvt_pk_bf16_f32 v68, v82, v83
	s_nop 0
	v_addc_co_u32_e32 v81, vcc, 0, v65, vcc
	global_store_dwordx4 v[80:81], v[66:69], off
	v_pk_add_f32 v[80:81], v[34:35], 0 op_sel_hi:[1,0]
	v_pk_add_f32 v[82:83], v[32:33], 0 op_sel_hi:[1,0]
	v_pk_add_f32 v[68:69], v[38:39], 0 op_sel_hi:[1,0]
	v_pk_add_f32 v[66:67], v[36:37], 0 op_sel_hi:[1,0]
	s_nop 0
	v_cvt_pk_bf16_f32 v66, v66, v67
	v_cvt_pk_bf16_f32 v67, v68, v69
	v_cvt_pk_bf16_f32 v68, v82, v83
	v_cvt_pk_bf16_f32 v69, v80, v81
	global_store_dwordx4 v[70:71], v[66:69], off offset:256
	v_pk_add_f32 v[80:81], v[26:27], 0 op_sel_hi:[1,0]
	v_pk_add_f32 v[82:83], v[24:25], 0 op_sel_hi:[1,0]
	v_pk_add_f32 v[68:69], v[30:31], 0 op_sel_hi:[1,0]
	v_pk_add_f32 v[66:67], v[28:29], 0 op_sel_hi:[1,0]
	v_lshl_add_u64 v[70:71], v[64:65], 0, s[18:19]
	v_cvt_pk_bf16_f32 v66, v66, v67
	v_cvt_pk_bf16_f32 v67, v68, v69
	v_cvt_pk_bf16_f32 v69, v80, v81
	v_add_co_u32_e32 v80, vcc, s59, v64
	v_cvt_pk_bf16_f32 v68, v82, v83
	s_nop 0
	v_addc_co_u32_e32 v81, vcc, 0, v65, vcc
	global_store_dwordx4 v[80:81], v[66:69], off
	v_pk_add_f32 v[80:81], v[18:19], 0 op_sel_hi:[1,0]
	v_pk_add_f32 v[82:83], v[16:17], 0 op_sel_hi:[1,0]
	v_pk_add_f32 v[68:69], v[22:23], 0 op_sel_hi:[1,0]
	v_pk_add_f32 v[66:67], v[20:21], 0 op_sel_hi:[1,0]
	v_add_co_u32_e32 v64, vcc, s60, v64
	v_cvt_pk_bf16_f32 v66, v66, v67
	v_cvt_pk_bf16_f32 v67, v68, v69
	v_cvt_pk_bf16_f32 v68, v82, v83
	v_cvt_pk_bf16_f32 v69, v80, v81
	global_store_dwordx4 v[70:71], v[66:69], off offset:256
	v_pk_add_f32 v[70:71], v[10:11], 0 op_sel_hi:[1,0]
	v_pk_add_f32 v[80:81], v[8:9], 0 op_sel_hi:[1,0]
	v_pk_add_f32 v[68:69], v[14:15], 0 op_sel_hi:[1,0]
	v_pk_add_f32 v[66:67], v[12:13], 0 op_sel_hi:[1,0]
	v_addc_co_u32_e32 v65, vcc, 0, v65, vcc
	v_cvt_pk_bf16_f32 v66, v66, v67
	v_cvt_pk_bf16_f32 v67, v68, v69
	v_cvt_pk_bf16_f32 v68, v80, v81
	v_cvt_pk_bf16_f32 v69, v70, v71
	global_store_dwordx4 v[64:65], v[66:69], off
	v_pk_add_f32 v[64:65], v[4:5], 0 op_sel_hi:[1,0]
	v_pk_add_f32 v[70:71], v[0:1], 0 op_sel_hi:[1,0]
	v_pk_add_f32 v[66:67], v[6:7], 0 op_sel_hi:[1,0]
	v_pk_add_f32 v[68:69], v[2:3], 0 op_sel_hi:[1,0]
	v_cvt_pk_bf16_f32 v64, v64, v65
	v_cvt_pk_bf16_f32 v65, v66, v67
	v_cvt_pk_bf16_f32 v66, v70, v71

.LBB0_952:
	ds_read_b128 v[144:147], v151
	ds_read_b128 v[156:159], v151 offset:1024
	ds_read_b128 v[160:163], v151 offset:2048
	ds_read_b128 v[164:167], v151 offset:3072
	s_add_u32 s26, s24, 0xfff80080
	s_addc_u32 s27, s25, -1
	s_cmp_eq_u32 s49, 28
	s_cselect_b32 s29, s15, s27
	s_cselect_b32 s28, s21, s26
	s_cselect_b32 s27, s13, s48
	s_cselect_b32 s26, s46, s47
	v_lshl_add_u64 v[168:169], s[24:25], 0, v[136:137]
	s_add_i32 m0, s23, 0xc000
	ds_read_b128 v[172:175], v152
	ds_read_b128 v[176:179], v152 offset:1024
	ds_read_b128 v[180:183], v152 offset:2048
	ds_read_b128 v[184:187], v152 offset:3072
	ds_read_b128 v[188:191], v152 offset:4096
	ds_read_b128 v[192:195], v152 offset:5120
	ds_read_b128 v[196:199], v152 offset:6144
	ds_read_b128 v[200:203], v152 offset:7168
	global_load_lds_dwordx4 v[168:169], off
	v_lshl_add_u64 v[168:169], s[24:25], 0, v[138:139]
	s_add_i32 m0, s23, 0xe000
	s_nop 0
	global_load_lds_dwordx4 v[168:169], off
	s_waitcnt vmcnt(10)
	s_waitcnt lgkmcnt(8)
	s_barrier
	s_waitcnt lgkmcnt(0)
	s_setprio 1
	s_waitcnt lgkmcnt(0)
	v_mfma_f32_16x16x32_bf16 v[124:127], v[144:147], v[172:175], v[124:127]
	v_mfma_f32_16x16x32_bf16 v[120:123], v[160:163], v[172:175], v[120:123]
	v_mfma_f32_16x16x32_bf16 v[108:111], v[144:147], v[180:183], v[108:111]
	v_mfma_f32_16x16x32_bf16 v[104:107], v[160:163], v[180:183], v[104:107]
	v_mfma_f32_16x16x32_bf16 v[92:95], v[144:147], v[188:191], v[92:95]
	v_mfma_f32_16x16x32_bf16 v[88:91], v[160:163], v[188:191], v[88:91]
	v_mfma_f32_16x16x32_bf16 v[76:79], v[144:147], v[196:199], v[76:79]
	v_mfma_f32_16x16x32_bf16 v[72:75], v[160:163], v[196:199], v[72:75]
	v_mfma_f32_16x16x32_bf16 v[124:127], v[156:159], v[176:179], v[124:127]
	v_mfma_f32_16x16x32_bf16 v[120:123], v[164:167], v[176:179], v[120:123]
	v_mfma_f32_16x16x32_bf16 v[108:111], v[156:159], v[184:187], v[108:111]
	v_mfma_f32_16x16x32_bf16 v[104:107], v[164:167], v[184:187], v[104:107]
	v_mfma_f32_16x16x32_bf16 v[92:95], v[156:159], v[192:195], v[92:95]
	v_mfma_f32_16x16x32_bf16 v[88:91], v[164:167], v[192:195], v[88:91]
	v_mfma_f32_16x16x32_bf16 v[76:79], v[156:159], v[200:203], v[76:79]
	v_mfma_f32_16x16x32_bf16 v[72:75], v[164:167], v[200:203], v[72:75]
	s_setprio 0
	s_barrier
	s_add_i32 s50, s44, s34
	v_lshl_add_u64 v[168:169], s[26:27], 0, v[130:131]
	s_mov_b32 m0, s50
	ds_read_b128 v[204:207], v153
	ds_read_b128 v[208:211], v153 offset:1024
	ds_read_b128 v[212:215], v153 offset:2048
	ds_read_b128 v[216:219], v153 offset:3072
	global_load_lds_dwordx4 v[168:169], off
	v_lshl_add_u64 v[220:221], s[26:27], 0, v[134:135]
	s_add_i32 m0, s50, 0x2000
	s_nop 0
	global_load_lds_dwordx4 v[220:221], off
	s_waitcnt vmcnt(10)
	s_barrier
	s_waitcnt lgkmcnt(0)
	s_setprio 1
	s_waitcnt lgkmcnt(0)
	v_mfma_f32_16x16x32_bf16 v[116:119], v[204:207], v[172:175], v[116:119]
	v_mfma_f32_16x16x32_bf16 v[112:115], v[212:215], v[172:175], v[112:115]
	v_mfma_f32_16x16x32_bf16 v[100:103], v[204:207], v[180:183], v[100:103]
	v_mfma_f32_16x16x32_bf16 v[96:99], v[212:215], v[180:183], v[96:99]
	v_mfma_f32_16x16x32_bf16 v[84:87], v[204:207], v[188:191], v[84:87]
	v_mfma_f32_16x16x32_bf16 v[80:83], v[212:215], v[188:191], v[80:83]
	v_mfma_f32_16x16x32_bf16 v[68:71], v[204:207], v[196:199], v[68:71]
	v_mfma_f32_16x16x32_bf16 v[64:67], v[212:215], v[196:199], v[64:67]
	v_mfma_f32_16x16x32_bf16 v[116:119], v[208:211], v[176:179], v[116:119]
	v_mfma_f32_16x16x32_bf16 v[112:115], v[216:219], v[176:179], v[112:115]
	v_mfma_f32_16x16x32_bf16 v[100:103], v[208:211], v[184:187], v[100:103]
	v_mfma_f32_16x16x32_bf16 v[96:99], v[216:219], v[184:187], v[96:99]
	v_mfma_f32_16x16x32_bf16 v[84:87], v[208:211], v[192:195], v[84:87]
	v_mfma_f32_16x16x32_bf16 v[80:83], v[216:219], v[192:195], v[80:83]
	v_mfma_f32_16x16x32_bf16 v[68:71], v[208:211], v[200:203], v[68:71]
	v_mfma_f32_16x16x32_bf16 v[64:67], v[216:219], v[200:203], v[64:67]
	s_setprio 0
	s_mov_b32 m0, s23
	v_lshl_add_u64 v[222:223], s[28:29], 0, v[128:129]
	s_barrier
	ds_read_b128 v[172:175], v152 offset:16384
	ds_read_b128 v[176:179], v152 offset:17408
	ds_read_b128 v[180:183], v152 offset:18432
	ds_read_b128 v[184:187], v152 offset:19456
	ds_read_b128 v[188:191], v152 offset:20480
	ds_read_b128 v[192:195], v152 offset:21504
	ds_read_b128 v[196:199], v152 offset:22528
	ds_read_b128 v[200:203], v152 offset:23552
	global_load_lds_dwordx4 v[222:223], off
	v_lshl_add_u64 v[224:225], s[28:29], 0, v[132:133]
	s_mov_b32 m0, s35
	s_nop 0
	global_load_lds_dwordx4 v[224:225], off
	s_barrier
	s_waitcnt lgkmcnt(0)
	s_setprio 1
	s_waitcnt lgkmcnt(0)
	v_mfma_f32_16x16x32_bf16 v[60:63], v[144:147], v[172:175], v[60:63]
	v_mfma_f32_16x16x32_bf16 v[56:59], v[160:163], v[172:175], v[56:59]
	v_mfma_f32_16x16x32_bf16 v[44:47], v[144:147], v[180:183], v[44:47]
	v_mfma_f32_16x16x32_bf16 v[40:43], v[160:163], v[180:183], v[40:43]
	v_mfma_f32_16x16x32_bf16 v[28:31], v[144:147], v[188:191], v[28:31]
	v_mfma_f32_16x16x32_bf16 v[24:27], v[160:163], v[188:191], v[24:27]
	v_mfma_f32_16x16x32_bf16 v[12:15], v[144:147], v[196:199], v[12:15]
	v_mfma_f32_16x16x32_bf16 v[8:11], v[160:163], v[196:199], v[8:11]
	v_mfma_f32_16x16x32_bf16 v[60:63], v[156:159], v[176:179], v[60:63]
	v_mfma_f32_16x16x32_bf16 v[56:59], v[164:167], v[176:179], v[56:59]
	v_mfma_f32_16x16x32_bf16 v[44:47], v[156:159], v[184:187], v[44:47]
	v_mfma_f32_16x16x32_bf16 v[40:43], v[164:167], v[184:187], v[40:43]
	v_mfma_f32_16x16x32_bf16 v[28:31], v[156:159], v[192:195], v[28:31]
	v_mfma_f32_16x16x32_bf16 v[24:27], v[164:167], v[192:195], v[24:27]
	v_mfma_f32_16x16x32_bf16 v[12:15], v[156:159], v[200:203], v[12:15]
	v_mfma_f32_16x16x32_bf16 v[8:11], v[164:167], v[200:203], v[8:11]
	s_setprio 0
	s_barrier
	s_add_u32 s50, s26, 0x80000
	s_addc_u32 s51, s27, 0
	s_add_i32 s52, s45, s34
	v_lshl_add_u64 v[144:145], s[50:51], 0, v[130:131]
	s_mov_b32 m0, s52
	s_nop 0
	global_load_lds_dwordx4 v[144:145], off
	v_lshl_add_u64 v[144:145], s[50:51], 0, v[134:135]
	s_add_i32 m0, s52, 0x2000
	s_nop 0
	global_load_lds_dwordx4 v[144:145], off
	s_waitcnt vmcnt(10)
	s_barrier
	s_setprio 1
	v_mfma_f32_16x16x32_bf16 v[52:55], v[204:207], v[172:175], v[52:55]
	v_mfma_f32_16x16x32_bf16 v[48:51], v[212:215], v[172:175], v[48:51]
	v_mfma_f32_16x16x32_bf16 v[36:39], v[204:207], v[180:183], v[36:39]
	v_mfma_f32_16x16x32_bf16 v[32:35], v[212:215], v[180:183], v[32:35]
	v_mfma_f32_16x16x32_bf16 v[20:23], v[204:207], v[188:191], v[20:23]
	v_mfma_f32_16x16x32_bf16 v[16:19], v[212:215], v[188:191], v[16:19]
	v_mfma_f32_16x16x32_bf16 v[4:7], v[204:207], v[196:199], v[4:7]
	v_mfma_f32_16x16x32_bf16 v[0:3], v[212:215], v[196:199], v[0:3]
	v_mfma_f32_16x16x32_bf16 v[52:55], v[208:211], v[176:179], v[52:55]
	v_mfma_f32_16x16x32_bf16 v[48:51], v[216:219], v[176:179], v[48:51]
	v_mfma_f32_16x16x32_bf16 v[36:39], v[208:211], v[184:187], v[36:39]
	v_mfma_f32_16x16x32_bf16 v[32:35], v[216:219], v[184:187], v[32:35]
	v_mfma_f32_16x16x32_bf16 v[20:23], v[208:211], v[192:195], v[20:23]
	v_mfma_f32_16x16x32_bf16 v[16:19], v[216:219], v[192:195], v[16:19]
	v_mfma_f32_16x16x32_bf16 v[4:7], v[208:211], v[200:203], v[4:7]
	v_mfma_f32_16x16x32_bf16 v[0:3], v[216:219], v[200:203], v[0:3]
	s_setprio 0
	s_add_i32 s50, 0, 0x18000
	v_add_u32_e32 v155, s50, v149
	s_barrier
	ds_read_b128 v[144:147], v155
	ds_read_b128 v[156:159], v155 offset:1024
	ds_read_b128 v[160:163], v155 offset:2048
	ds_read_b128 v[164:167], v155 offset:3072
	s_add_u32 s28, s28, 0x80000
	s_addc_u32 s29, s29, 0
	s_mov_b32 m0, s36
	v_lshl_add_u64 v[204:205], s[28:29], 0, v[128:129]
	ds_read_b128 v[172:175], v152 offset:32768
	ds_read_b128 v[176:179], v152 offset:33792
	ds_read_b128 v[180:183], v152 offset:34816
	ds_read_b128 v[184:187], v152 offset:35840
	ds_read_b128 v[188:191], v152 offset:36864
	ds_read_b128 v[192:195], v152 offset:37888
	ds_read_b128 v[196:199], v152 offset:38912
	ds_read_b128 v[200:203], v152 offset:39936
	global_load_lds_dwordx4 v[204:205], off
	v_lshl_add_u64 v[204:205], s[28:29], 0, v[132:133]
	s_mov_b32 m0, s37
	s_nop 0
	global_load_lds_dwordx4 v[204:205], off
	s_waitcnt vmcnt(10)
	s_waitcnt lgkmcnt(8)
	s_barrier
	s_waitcnt lgkmcnt(0)
	s_setprio 1
	s_waitcnt lgkmcnt(0)
	v_mfma_f32_16x16x32_bf16 v[124:127], v[144:147], v[172:175], v[124:127]
	v_mfma_f32_16x16x32_bf16 v[120:123], v[160:163], v[172:175], v[120:123]
	v_mfma_f32_16x16x32_bf16 v[108:111], v[144:147], v[180:183], v[108:111]
	v_mfma_f32_16x16x32_bf16 v[104:107], v[160:163], v[180:183], v[104:107]
	v_mfma_f32_16x16x32_bf16 v[92:95], v[144:147], v[188:191], v[92:95]
	v_mfma_f32_16x16x32_bf16 v[88:91], v[160:163], v[188:191], v[88:91]
	v_mfma_f32_16x16x32_bf16 v[76:79], v[144:147], v[196:199], v[76:79]
	v_mfma_f32_16x16x32_bf16 v[72:75], v[160:163], v[196:199], v[72:75]
	v_mfma_f32_16x16x32_bf16 v[124:127], v[156:159], v[176:179], v[124:127]
	v_mfma_f32_16x16x32_bf16 v[120:123], v[164:167], v[176:179], v[120:123]
	v_mfma_f32_16x16x32_bf16 v[108:111], v[156:159], v[184:187], v[108:111]
	v_mfma_f32_16x16x32_bf16 v[104:107], v[164:167], v[184:187], v[104:107]
	v_mfma_f32_16x16x32_bf16 v[92:95], v[156:159], v[192:195], v[92:95]
	v_mfma_f32_16x16x32_bf16 v[88:91], v[164:167], v[192:195], v[88:91]
	v_mfma_f32_16x16x32_bf16 v[76:79], v[156:159], v[200:203], v[76:79]
	v_mfma_f32_16x16x32_bf16 v[72:75], v[164:167], v[200:203], v[72:75]
	s_setprio 0
	s_barrier
	s_add_i32 s28, 0, 0x1c000
	s_add_i32 s29, s50, s34
	v_add_u32_e32 v155, s28, v149
	v_lshl_add_u64 v[168:169], v[168:169], 0, s[10:11]
	s_mov_b32 m0, s29
	ds_read_b128 v[204:207], v155
	ds_read_b128 v[208:211], v155 offset:1024
	ds_read_b128 v[212:215], v155 offset:2048
	ds_read_b128 v[216:219], v155 offset:3072
	global_load_lds_dwordx4 v[168:169], off
	v_lshl_add_u64 v[168:169], v[220:221], 0, s[10:11]
	s_add_i32 m0, s29, 0x2000
	s_nop 0
	global_load_lds_dwordx4 v[168:169], off
	s_waitcnt vmcnt(10)
	s_barrier
	s_waitcnt lgkmcnt(0)
	s_setprio 1
	s_waitcnt lgkmcnt(0)
	v_mfma_f32_16x16x32_bf16 v[116:119], v[204:207], v[172:175], v[116:119]
	v_mfma_f32_16x16x32_bf16 v[112:115], v[212:215], v[172:175], v[112:115]
	v_mfma_f32_16x16x32_bf16 v[100:103], v[204:207], v[180:183], v[100:103]
	v_mfma_f32_16x16x32_bf16 v[96:99], v[212:215], v[180:183], v[96:99]
	v_mfma_f32_16x16x32_bf16 v[84:87], v[204:207], v[188:191], v[84:87]
	v_mfma_f32_16x16x32_bf16 v[80:83], v[212:215], v[188:191], v[80:83]
	v_mfma_f32_16x16x32_bf16 v[68:71], v[204:207], v[196:199], v[68:71]
	v_mfma_f32_16x16x32_bf16 v[64:67], v[212:215], v[196:199], v[64:67]
	v_mfma_f32_16x16x32_bf16 v[116:119], v[208:211], v[176:179], v[116:119]
	v_mfma_f32_16x16x32_bf16 v[112:115], v[216:219], v[176:179], v[112:115]
	v_mfma_f32_16x16x32_bf16 v[100:103], v[208:211], v[184:187], v[100:103]
	v_mfma_f32_16x16x32_bf16 v[96:99], v[216:219], v[184:187], v[96:99]
	v_mfma_f32_16x16x32_bf16 v[84:87], v[208:211], v[192:195], v[84:87]
	v_mfma_f32_16x16x32_bf16 v[80:83], v[216:219], v[192:195], v[80:83]
	v_mfma_f32_16x16x32_bf16 v[68:71], v[208:211], v[200:203], v[68:71]
	v_mfma_f32_16x16x32_bf16 v[64:67], v[216:219], v[200:203], v[64:67]
	s_setprio 0
	s_mov_b32 m0, s41
	v_lshl_add_u64 v[168:169], v[222:223], 0, s[10:11]
	s_barrier
	ds_read_b128 v[172:175], v152 offset:49152
	ds_read_b128 v[176:179], v152 offset:50176
	ds_read_b128 v[180:183], v152 offset:51200
	ds_read_b128 v[184:187], v152 offset:52224
	ds_read_b128 v[188:191], v152 offset:53248
	ds_read_b128 v[192:195], v152 offset:54272
	ds_read_b128 v[196:199], v152 offset:55296
	ds_read_b128 v[200:203], v152 offset:56320
	global_load_lds_dwordx4 v[168:169], off
	v_lshl_add_u64 v[168:169], v[224:225], 0, s[10:11]
	s_mov_b32 m0, s42
	s_nop 0
	global_load_lds_dwordx4 v[168:169], off
	s_barrier
	s_waitcnt lgkmcnt(0)
	s_setprio 1
	s_waitcnt lgkmcnt(0)
	v_mfma_f32_16x16x32_bf16 v[60:63], v[144:147], v[172:175], v[60:63]
	v_mfma_f32_16x16x32_bf16 v[56:59], v[160:163], v[172:175], v[56:59]
	v_mfma_f32_16x16x32_bf16 v[44:47], v[144:147], v[180:183], v[44:47]
	v_mfma_f32_16x16x32_bf16 v[40:43], v[160:163], v[180:183], v[40:43]
	v_mfma_f32_16x16x32_bf16 v[28:31], v[144:147], v[188:191], v[28:31]
	v_mfma_f32_16x16x32_bf16 v[24:27], v[160:163], v[188:191], v[24:27]
	v_mfma_f32_16x16x32_bf16 v[12:15], v[144:147], v[196:199], v[12:15]
	v_mfma_f32_16x16x32_bf16 v[8:11], v[160:163], v[196:199], v[8:11]
	v_mfma_f32_16x16x32_bf16 v[60:63], v[156:159], v[176:179], v[60:63]
	v_mfma_f32_16x16x32_bf16 v[56:59], v[164:167], v[176:179], v[56:59]
	v_mfma_f32_16x16x32_bf16 v[44:47], v[156:159], v[184:187], v[44:47]
	v_mfma_f32_16x16x32_bf16 v[40:43], v[164:167], v[184:187], v[40:43]
	v_mfma_f32_16x16x32_bf16 v[28:31], v[156:159], v[192:195], v[28:31]
	v_mfma_f32_16x16x32_bf16 v[24:27], v[164:167], v[192:195], v[24:27]
	v_mfma_f32_16x16x32_bf16 v[12:15], v[156:159], v[200:203], v[12:15]
	v_mfma_f32_16x16x32_bf16 v[8:11], v[164:167], v[200:203], v[8:11]
	s_setprio 0
	s_barrier
	s_add_u32 s26, s26, 0x80080
	s_addc_u32 s27, s27, 0
	s_add_i32 s28, s28, s34
	v_lshl_add_u64 v[144:145], s[26:27], 0, v[130:131]
	s_mov_b32 m0, s28
	s_nop 0
	global_load_lds_dwordx4 v[144:145], off
	v_lshl_add_u64 v[144:145], s[26:27], 0, v[134:135]
	s_add_i32 m0, s28, 0x2000
	s_nop 0
	global_load_lds_dwordx4 v[144:145], off
	s_waitcnt vmcnt(10)
	s_barrier
	s_setprio 1
	v_mfma_f32_16x16x32_bf16 v[52:55], v[204:207], v[172:175], v[52:55]
	v_mfma_f32_16x16x32_bf16 v[48:51], v[212:215], v[172:175], v[48:51]
	v_mfma_f32_16x16x32_bf16 v[36:39], v[204:207], v[180:183], v[36:39]
	v_mfma_f32_16x16x32_bf16 v[32:35], v[212:215], v[180:183], v[32:35]
	v_mfma_f32_16x16x32_bf16 v[20:23], v[204:207], v[188:191], v[20:23]
	v_mfma_f32_16x16x32_bf16 v[16:19], v[212:215], v[188:191], v[16:19]
	v_mfma_f32_16x16x32_bf16 v[4:7], v[204:207], v[196:199], v[4:7]
	v_mfma_f32_16x16x32_bf16 v[0:3], v[212:215], v[196:199], v[0:3]
	v_mfma_f32_16x16x32_bf16 v[52:55], v[208:211], v[176:179], v[52:55]
	v_mfma_f32_16x16x32_bf16 v[48:51], v[216:219], v[176:179], v[48:51]
	v_mfma_f32_16x16x32_bf16 v[36:39], v[208:211], v[184:187], v[36:39]
	v_mfma_f32_16x16x32_bf16 v[32:35], v[216:219], v[184:187], v[32:35]
	v_mfma_f32_16x16x32_bf16 v[20:23], v[208:211], v[192:195], v[20:23]
	v_mfma_f32_16x16x32_bf16 v[16:19], v[216:219], v[192:195], v[16:19]
	v_mfma_f32_16x16x32_bf16 v[4:7], v[208:211], v[200:203], v[4:7]
	v_mfma_f32_16x16x32_bf16 v[0:3], v[216:219], v[200:203], v[0:3]
	s_setprio 0
	s_add_i32 s49, s49, 2
	s_add_u32 s24, s24, 0x100
	s_addc_u32 s25, s25, 0
	s_add_u32 s47, s47, 0x100
	s_addc_u32 s48, s48, 0
	s_cmp_gt_u32 s49, 29
	s_barrier
	s_cbranch_scc0 .LBB0_952
	v_lshl_add_u32 v146, s22, 8, v148
	v_lshl_or_b32 v144, s20, 8, v150
	v_readlane_b32 s98, v235, 6
	v_readlane_b32 s99, v235, 7
	v_lshlrev_b32_e32 v225, 13, v146
	v_lshl_add_u32 v224, v144, 2, v225
	s_nop 4
	s_add_u32 s100, s98, 0x0
	s_addc_u32 s101, s99, 0
	global_load_dwordx4 v[172:175], v224, s[100:101] nt
	global_load_dwordx4 v[176:179], v224, s[100:101] offset:16 nt
	global_load_dwordx4 v[180:183], v224, s[100:101] offset:512 nt
	global_load_dwordx4 v[184:187], v224, s[100:101] offset:528 nt
	s_add_u32 s100, s98, 0x20000
	s_addc_u32 s101, s99, 0
	global_load_dwordx4 v[188:191], v224, s[100:101] nt
	global_load_dwordx4 v[192:195], v224, s[100:101] offset:16 nt
	global_load_dwordx4 v[196:199], v224, s[100:101] offset:512 nt
	global_load_dwordx4 v[200:203], v224, s[100:101] offset:528 nt
	s_add_u32 s100, s98, 0x40000
	s_addc_u32 s101, s99, 0
	global_load_dwordx4 v[204:207], v224, s[100:101] nt
	global_load_dwordx4 v[208:211], v224, s[100:101] offset:16 nt
	global_load_dwordx4 v[212:215], v224, s[100:101] offset:512 nt
	global_load_dwordx4 v[216:219], v224, s[100:101] offset:528 nt
	s_add_u32 s100, s98, 0x60000
	s_addc_u32 s101, s99, 0
	global_load_dwordx4 v[220:223], v224, s[100:101] nt
	global_load_dwordx4 v[236:239], v224, s[100:101] offset:16 nt
	global_load_dwordx4 v[240:243], v224, s[100:101] offset:512 nt
	global_load_dwordx4 v[244:247], v224, s[100:101] offset:528 nt
	v_ashrrev_i32_e32 v147, 31, v146
	v_ashrrev_i32_e32 v145, 31, v144
	v_lshlrev_b64 v[156:157], 11, v[146:147]
	v_readlane_b32 s48, v235, 6
	v_lshl_add_u64 v[164:165], v[156:157], 0, v[144:145]
	v_readlane_b32 s49, v235, 7
	v_xor_b32_e32 v155, 32, v154
	v_readlane_b32 s50, v235, 8
	v_lshl_add_u64 v[166:167], v[164:165], 2, s[48:49]
	v_lshl_add_u64 v[164:165], v[164:165], 1, s[6:7]
	v_readlane_b32 s51, v235, 9
	v_readlane_b32 s52, v235, 10
	v_readlane_b32 s53, v235, 11
	v_readlane_b32 s54, v235, 12
	v_readlane_b32 s55, v235, 13
	v_readlane_b32 s56, v235, 14
	v_readlane_b32 s57, v235, 15
	v_readlane_b32 s58, v235, 16
	v_readlane_b32 s59, v235, 17
	v_readlane_b32 s60, v235, 18
	v_readlane_b32 s61, v235, 19
	v_readlane_b32 s62, v235, 20
	v_readlane_b32 s63, v235, 21
	s_waitcnt vmcnt(14)
	v_pk_add_f32 v[126:127], v[126:127], v[174:175]
	v_pk_add_f32 v[168:169], v[124:125], v[172:173]
	v_pk_add_f32 v[178:179], v[122:123], v[178:179]
	v_pk_add_f32 v[176:177], v[120:121], v[176:177]
	v_cvt_pk_bf16_f32 v120, v168, v169
	v_cvt_pk_bf16_f32 v121, v126, v127
	v_cvt_pk_bf16_f32 v122, v176, v177
	v_cvt_pk_bf16_f32 v123, v178, v179
	global_store_dwordx4 v[164:165], v[120:123], off
	s_nop 0
	v_mul_f32_e32 v166, v169, v169
	v_mul_f32_e32 v127, v127, v127
	v_and_b32_e32 v121, 64, v154
	v_mul_f32_e32 v177, v177, v177
	v_fmac_f32_e32 v166, v168, v168
	v_fmac_f32_e32 v127, v126, v126
	v_xor_b32_e32 v120, 16, v154
	v_add_u32_e32 v121, 64, v121
	v_mul_f32_e32 v179, v179, v179
	v_fmac_f32_e32 v177, v176, v176
	v_add_f32_e32 v126, v166, v127
	v_cmp_lt_i32_e32 vcc, v120, v121
	v_fmac_f32_e32 v179, v178, v178
	v_add_f32_e32 v126, v126, v177
	v_cndmask_b32_e32 v120, v154, v120, vcc
	v_add_f32_e32 v126, v179, v126
	v_lshlrev_b32_e32 v120, 2, v120
	v_cmp_lt_i32_e32 vcc, v155, v121
	s_waitcnt vmcnt(13)
	v_pk_add_f32 v[118:119], v[118:119], v[182:183]
	v_pk_add_f32 v[116:117], v[116:117], v[180:181]
	v_pk_add_f32 v[182:183], v[112:113], v[184:185]
	v_mul_f32_e32 v112, v117, v117
	v_mul_f32_e32 v113, v119, v119
	v_pk_add_f32 v[180:181], v[114:115], v[186:187]
	v_mul_f32_e32 v114, v183, v183
	v_fmac_f32_e32 v112, v116, v116
	v_fmac_f32_e32 v113, v118, v118
	v_mul_f32_e32 v115, v181, v181
	v_fmac_f32_e32 v114, v182, v182
	v_add_f32_e32 v112, v112, v113
	v_add_f32_e32 v112, v112, v114
	v_fmac_f32_e32 v115, v180, v180
	v_add_f32_e32 v112, v115, v112
	v_add_f32_e32 v112, v126, v112
	ds_bpermute_b32 v113, v120, v112
	v_cndmask_b32_e32 v114, v154, v155, vcc
	v_lshlrev_b32_e32 v114, 2, v114
	v_cvt_pk_bf16_f32 v116, v116, v117
	v_cvt_pk_bf16_f32 v117, v118, v119
	s_waitcnt lgkmcnt(0)
	v_add_f32_e32 v112, v112, v113
	ds_bpermute_b32 v113, v114, v112
	v_cvt_pk_bf16_f32 v118, v182, v183
	v_cvt_pk_bf16_f32 v119, v180, v181
	global_store_dwordx4 v[164:165], v[116:119], off offset:256
	s_and_saveexec_b64 s[20:21], s[2:3]
	s_cbranch_execz .LBB0_955
	v_lshl_add_u64 v[116:117], v[146:147], 2, s[8:9]
	s_waitcnt lgkmcnt(0)
	v_add_f32_e32 v112, v112, v113
	global_atomic_add_f32 v[116:117], v112, off

.LBB0_1039:
	ds_read_b128 v[144:147], v151
	ds_read_b128 v[156:159], v151 offset:1024
	ds_read_b128 v[160:163], v151 offset:2048
	ds_read_b128 v[164:167], v151 offset:3072
	s_add_u32 s30, s0, 0xfff80080
	s_addc_u32 s31, s1, -1
	s_cmp_eq_u32 s60, 28
	s_cselect_b32 s35, s23, s31
	s_cselect_b32 s34, s56, s30
	s_cselect_b32 s31, s21, s59
	s_cselect_b32 s30, s57, s58
	v_lshl_add_u64 v[168:169], s[0:1], 0, v[136:137]
	s_add_i32 m0, s29, 0xc000
	ds_read_b128 v[172:175], v152
	ds_read_b128 v[176:179], v152 offset:1024
	ds_read_b128 v[180:183], v152 offset:2048
	ds_read_b128 v[184:187], v152 offset:3072
	ds_read_b128 v[188:191], v152 offset:4096
	ds_read_b128 v[192:195], v152 offset:5120
	ds_read_b128 v[196:199], v152 offset:6144
	ds_read_b128 v[200:203], v152 offset:7168
	global_load_lds_dwordx4 v[168:169], off
	v_lshl_add_u64 v[168:169], s[0:1], 0, v[138:139]
	s_add_i32 m0, s29, 0xe000
	s_nop 0
	global_load_lds_dwordx4 v[168:169], off
	s_waitcnt vmcnt(10)
	s_waitcnt lgkmcnt(8)
	s_barrier
	s_waitcnt lgkmcnt(0)
	s_setprio 1
	s_waitcnt lgkmcnt(0)
	v_mfma_f32_16x16x32_bf16 v[124:127], v[144:147], v[172:175], v[124:127]
	v_mfma_f32_16x16x32_bf16 v[120:123], v[160:163], v[172:175], v[120:123]
	v_mfma_f32_16x16x32_bf16 v[108:111], v[144:147], v[180:183], v[108:111]
	v_mfma_f32_16x16x32_bf16 v[104:107], v[160:163], v[180:183], v[104:107]
	v_mfma_f32_16x16x32_bf16 v[92:95], v[144:147], v[188:191], v[92:95]
	v_mfma_f32_16x16x32_bf16 v[88:91], v[160:163], v[188:191], v[88:91]
	v_mfma_f32_16x16x32_bf16 v[76:79], v[144:147], v[196:199], v[76:79]
	v_mfma_f32_16x16x32_bf16 v[72:75], v[160:163], v[196:199], v[72:75]
	v_mfma_f32_16x16x32_bf16 v[124:127], v[156:159], v[176:179], v[124:127]
	v_mfma_f32_16x16x32_bf16 v[120:123], v[164:167], v[176:179], v[120:123]
	v_mfma_f32_16x16x32_bf16 v[108:111], v[156:159], v[184:187], v[108:111]
	v_mfma_f32_16x16x32_bf16 v[104:107], v[164:167], v[184:187], v[104:107]
	v_mfma_f32_16x16x32_bf16 v[92:95], v[156:159], v[192:195], v[92:95]
	v_mfma_f32_16x16x32_bf16 v[88:91], v[164:167], v[192:195], v[88:91]
	v_mfma_f32_16x16x32_bf16 v[76:79], v[156:159], v[200:203], v[76:79]
	v_mfma_f32_16x16x32_bf16 v[72:75], v[164:167], v[200:203], v[72:75]
	s_setprio 0
	s_barrier
	s_add_i32 s61, s48, s38
	v_lshl_add_u64 v[168:169], s[30:31], 0, v[130:131]
	s_mov_b32 m0, s61
	ds_read_b128 v[204:207], v153
	ds_read_b128 v[208:211], v153 offset:1024
	ds_read_b128 v[212:215], v153 offset:2048
	ds_read_b128 v[216:219], v153 offset:3072
	global_load_lds_dwordx4 v[168:169], off
	v_lshl_add_u64 v[220:221], s[30:31], 0, v[134:135]
	s_add_i32 m0, s61, 0x2000
	s_nop 0
	global_load_lds_dwordx4 v[220:221], off
	s_waitcnt vmcnt(10)
	s_barrier
	s_waitcnt lgkmcnt(0)
	s_setprio 1
	s_waitcnt lgkmcnt(0)
	v_mfma_f32_16x16x32_bf16 v[116:119], v[204:207], v[172:175], v[116:119]
	v_mfma_f32_16x16x32_bf16 v[112:115], v[212:215], v[172:175], v[112:115]
	v_mfma_f32_16x16x32_bf16 v[100:103], v[204:207], v[180:183], v[100:103]
	v_mfma_f32_16x16x32_bf16 v[96:99], v[212:215], v[180:183], v[96:99]
	v_mfma_f32_16x16x32_bf16 v[84:87], v[204:207], v[188:191], v[84:87]
	v_mfma_f32_16x16x32_bf16 v[80:83], v[212:215], v[188:191], v[80:83]
	v_mfma_f32_16x16x32_bf16 v[68:71], v[204:207], v[196:199], v[68:71]
	v_mfma_f32_16x16x32_bf16 v[64:67], v[212:215], v[196:199], v[64:67]
	v_mfma_f32_16x16x32_bf16 v[116:119], v[208:211], v[176:179], v[116:119]
	v_mfma_f32_16x16x32_bf16 v[112:115], v[216:219], v[176:179], v[112:115]
	v_mfma_f32_16x16x32_bf16 v[100:103], v[208:211], v[184:187], v[100:103]
	v_mfma_f32_16x16x32_bf16 v[96:99], v[216:219], v[184:187], v[96:99]
	v_mfma_f32_16x16x32_bf16 v[84:87], v[208:211], v[192:195], v[84:87]
	v_mfma_f32_16x16x32_bf16 v[80:83], v[216:219], v[192:195], v[80:83]
	v_mfma_f32_16x16x32_bf16 v[68:71], v[208:211], v[200:203], v[68:71]
	v_mfma_f32_16x16x32_bf16 v[64:67], v[216:219], v[200:203], v[64:67]
	s_setprio 0
	s_mov_b32 m0, s29
	v_lshl_add_u64 v[222:223], s[34:35], 0, v[128:129]
	s_barrier
	ds_read_b128 v[172:175], v152 offset:16384
	ds_read_b128 v[176:179], v152 offset:17408
	ds_read_b128 v[180:183], v152 offset:18432
	ds_read_b128 v[184:187], v152 offset:19456
	ds_read_b128 v[188:191], v152 offset:20480
	ds_read_b128 v[192:195], v152 offset:21504
	ds_read_b128 v[196:199], v152 offset:22528
	ds_read_b128 v[200:203], v152 offset:23552
	global_load_lds_dwordx4 v[222:223], off
	v_lshl_add_u64 v[224:225], s[34:35], 0, v[132:133]
	s_mov_b32 m0, s40
	s_nop 0
	global_load_lds_dwordx4 v[224:225], off
	s_barrier
	s_waitcnt lgkmcnt(0)
	s_setprio 1
	s_waitcnt lgkmcnt(0)
	v_mfma_f32_16x16x32_bf16 v[60:63], v[144:147], v[172:175], v[60:63]
	v_mfma_f32_16x16x32_bf16 v[56:59], v[160:163], v[172:175], v[56:59]
	v_mfma_f32_16x16x32_bf16 v[44:47], v[144:147], v[180:183], v[44:47]
	v_mfma_f32_16x16x32_bf16 v[40:43], v[160:163], v[180:183], v[40:43]
	v_mfma_f32_16x16x32_bf16 v[28:31], v[144:147], v[188:191], v[28:31]
	v_mfma_f32_16x16x32_bf16 v[24:27], v[160:163], v[188:191], v[24:27]
	v_mfma_f32_16x16x32_bf16 v[12:15], v[144:147], v[196:199], v[12:15]
	v_mfma_f32_16x16x32_bf16 v[8:11], v[160:163], v[196:199], v[8:11]
	v_mfma_f32_16x16x32_bf16 v[60:63], v[156:159], v[176:179], v[60:63]
	v_mfma_f32_16x16x32_bf16 v[56:59], v[164:167], v[176:179], v[56:59]
	v_mfma_f32_16x16x32_bf16 v[44:47], v[156:159], v[184:187], v[44:47]
	v_mfma_f32_16x16x32_bf16 v[40:43], v[164:167], v[184:187], v[40:43]
	v_mfma_f32_16x16x32_bf16 v[28:31], v[156:159], v[192:195], v[28:31]
	v_mfma_f32_16x16x32_bf16 v[24:27], v[164:167], v[192:195], v[24:27]
	v_mfma_f32_16x16x32_bf16 v[12:15], v[156:159], v[200:203], v[12:15]
	v_mfma_f32_16x16x32_bf16 v[8:11], v[164:167], v[200:203], v[8:11]
	s_setprio 0
	s_barrier
	s_add_u32 s62, s30, 0x80000
	s_addc_u32 s63, s31, 0
	s_add_i32 s61, s49, s38
	v_lshl_add_u64 v[144:145], s[62:63], 0, v[130:131]
	s_mov_b32 m0, s61
	s_nop 0
	global_load_lds_dwordx4 v[144:145], off
	v_lshl_add_u64 v[144:145], s[62:63], 0, v[134:135]
	s_add_i32 m0, s61, 0x2000
	s_nop 0
	global_load_lds_dwordx4 v[144:145], off
	s_waitcnt vmcnt(10)
	s_barrier
	s_setprio 1
	v_mfma_f32_16x16x32_bf16 v[52:55], v[204:207], v[172:175], v[52:55]
	v_mfma_f32_16x16x32_bf16 v[48:51], v[212:215], v[172:175], v[48:51]
	v_mfma_f32_16x16x32_bf16 v[36:39], v[204:207], v[180:183], v[36:39]
	v_mfma_f32_16x16x32_bf16 v[32:35], v[212:215], v[180:183], v[32:35]
	v_mfma_f32_16x16x32_bf16 v[20:23], v[204:207], v[188:191], v[20:23]
	v_mfma_f32_16x16x32_bf16 v[16:19], v[212:215], v[188:191], v[16:19]
	v_mfma_f32_16x16x32_bf16 v[4:7], v[204:207], v[196:199], v[4:7]
	v_mfma_f32_16x16x32_bf16 v[0:3], v[212:215], v[196:199], v[0:3]
	v_mfma_f32_16x16x32_bf16 v[52:55], v[208:211], v[176:179], v[52:55]
	v_mfma_f32_16x16x32_bf16 v[48:51], v[216:219], v[176:179], v[48:51]
	v_mfma_f32_16x16x32_bf16 v[36:39], v[208:211], v[184:187], v[36:39]
	v_mfma_f32_16x16x32_bf16 v[32:35], v[216:219], v[184:187], v[32:35]
	v_mfma_f32_16x16x32_bf16 v[20:23], v[208:211], v[192:195], v[20:23]
	v_mfma_f32_16x16x32_bf16 v[16:19], v[216:219], v[192:195], v[16:19]
	v_mfma_f32_16x16x32_bf16 v[4:7], v[208:211], v[200:203], v[4:7]
	v_mfma_f32_16x16x32_bf16 v[0:3], v[216:219], v[200:203], v[0:3]
	s_setprio 0
	s_add_i32 s61, 0, 0x18000
	v_add_u32_e32 v155, s61, v149
	s_barrier
	ds_read_b128 v[144:147], v155
	ds_read_b128 v[156:159], v155 offset:1024
	ds_read_b128 v[160:163], v155 offset:2048
	ds_read_b128 v[164:167], v155 offset:3072
	s_add_u32 s34, s34, 0x80000
	s_addc_u32 s35, s35, 0
	s_mov_b32 m0, s41
	v_lshl_add_u64 v[204:205], s[34:35], 0, v[128:129]
	ds_read_b128 v[172:175], v152 offset:32768
	ds_read_b128 v[176:179], v152 offset:33792
	ds_read_b128 v[180:183], v152 offset:34816
	ds_read_b128 v[184:187], v152 offset:35840
	ds_read_b128 v[188:191], v152 offset:36864
	ds_read_b128 v[192:195], v152 offset:37888
	ds_read_b128 v[196:199], v152 offset:38912
	ds_read_b128 v[200:203], v152 offset:39936
	global_load_lds_dwordx4 v[204:205], off
	v_lshl_add_u64 v[204:205], s[34:35], 0, v[132:133]
	s_mov_b32 m0, s42
	s_nop 0
	global_load_lds_dwordx4 v[204:205], off
	s_waitcnt vmcnt(10)
	s_waitcnt lgkmcnt(8)
	s_barrier
	s_waitcnt lgkmcnt(0)
	s_setprio 1
	s_waitcnt lgkmcnt(0)
	v_mfma_f32_16x16x32_bf16 v[124:127], v[144:147], v[172:175], v[124:127]
	v_mfma_f32_16x16x32_bf16 v[120:123], v[160:163], v[172:175], v[120:123]
	v_mfma_f32_16x16x32_bf16 v[108:111], v[144:147], v[180:183], v[108:111]
	v_mfma_f32_16x16x32_bf16 v[104:107], v[160:163], v[180:183], v[104:107]
	v_mfma_f32_16x16x32_bf16 v[92:95], v[144:147], v[188:191], v[92:95]
	v_mfma_f32_16x16x32_bf16 v[88:91], v[160:163], v[188:191], v[88:91]
	v_mfma_f32_16x16x32_bf16 v[76:79], v[144:147], v[196:199], v[76:79]
	v_mfma_f32_16x16x32_bf16 v[72:75], v[160:163], v[196:199], v[72:75]
	v_mfma_f32_16x16x32_bf16 v[124:127], v[156:159], v[176:179], v[124:127]
	v_mfma_f32_16x16x32_bf16 v[120:123], v[164:167], v[176:179], v[120:123]
	v_mfma_f32_16x16x32_bf16 v[108:111], v[156:159], v[184:187], v[108:111]
	v_mfma_f32_16x16x32_bf16 v[104:107], v[164:167], v[184:187], v[104:107]
	v_mfma_f32_16x16x32_bf16 v[92:95], v[156:159], v[192:195], v[92:95]
	v_mfma_f32_16x16x32_bf16 v[88:91], v[164:167], v[192:195], v[88:91]
	v_mfma_f32_16x16x32_bf16 v[76:79], v[156:159], v[200:203], v[76:79]
	v_mfma_f32_16x16x32_bf16 v[72:75], v[164:167], v[200:203], v[72:75]
	s_setprio 0
	s_barrier
	s_add_i32 s34, 0, 0x1c000
	s_add_i32 s35, s61, s38
	v_add_u32_e32 v155, s34, v149
	v_lshl_add_u64 v[168:169], v[168:169], 0, s[12:13]
	s_mov_b32 m0, s35
	ds_read_b128 v[204:207], v155
	ds_read_b128 v[208:211], v155 offset:1024
	ds_read_b128 v[212:215], v155 offset:2048
	ds_read_b128 v[216:219], v155 offset:3072
	global_load_lds_dwordx4 v[168:169], off
	v_lshl_add_u64 v[168:169], v[220:221], 0, s[12:13]
	s_add_i32 m0, s35, 0x2000
	s_nop 0
	global_load_lds_dwordx4 v[168:169], off
	s_waitcnt vmcnt(10)
	s_barrier
	s_waitcnt lgkmcnt(0)
	s_setprio 1
	s_waitcnt lgkmcnt(0)
	v_mfma_f32_16x16x32_bf16 v[116:119], v[204:207], v[172:175], v[116:119]
	v_mfma_f32_16x16x32_bf16 v[112:115], v[212:215], v[172:175], v[112:115]
	v_mfma_f32_16x16x32_bf16 v[100:103], v[204:207], v[180:183], v[100:103]
	v_mfma_f32_16x16x32_bf16 v[96:99], v[212:215], v[180:183], v[96:99]
	v_mfma_f32_16x16x32_bf16 v[84:87], v[204:207], v[188:191], v[84:87]
	v_mfma_f32_16x16x32_bf16 v[80:83], v[212:215], v[188:191], v[80:83]
	v_mfma_f32_16x16x32_bf16 v[68:71], v[204:207], v[196:199], v[68:71]
	v_mfma_f32_16x16x32_bf16 v[64:67], v[212:215], v[196:199], v[64:67]
	v_mfma_f32_16x16x32_bf16 v[116:119], v[208:211], v[176:179], v[116:119]
	v_mfma_f32_16x16x32_bf16 v[112:115], v[216:219], v[176:179], v[112:115]
	v_mfma_f32_16x16x32_bf16 v[100:103], v[208:211], v[184:187], v[100:103]
	v_mfma_f32_16x16x32_bf16 v[96:99], v[216:219], v[184:187], v[96:99]
	v_mfma_f32_16x16x32_bf16 v[84:87], v[208:211], v[192:195], v[84:87]
	v_mfma_f32_16x16x32_bf16 v[80:83], v[216:219], v[192:195], v[80:83]
	v_mfma_f32_16x16x32_bf16 v[68:71], v[208:211], v[200:203], v[68:71]
	v_mfma_f32_16x16x32_bf16 v[64:67], v[216:219], v[200:203], v[64:67]
	s_setprio 0
	s_mov_b32 m0, s45
	v_lshl_add_u64 v[168:169], v[222:223], 0, s[12:13]
	s_barrier
	ds_read_b128 v[172:175], v152 offset:49152
	ds_read_b128 v[176:179], v152 offset:50176
	ds_read_b128 v[180:183], v152 offset:51200
	ds_read_b128 v[184:187], v152 offset:52224
	ds_read_b128 v[188:191], v152 offset:53248
	ds_read_b128 v[192:195], v152 offset:54272
	ds_read_b128 v[196:199], v152 offset:55296
	ds_read_b128 v[200:203], v152 offset:56320
	global_load_lds_dwordx4 v[168:169], off
	v_lshl_add_u64 v[168:169], v[224:225], 0, s[12:13]
	s_mov_b32 m0, s46
	s_nop 0
	global_load_lds_dwordx4 v[168:169], off
	s_barrier
	s_waitcnt lgkmcnt(0)
	s_setprio 1
	s_waitcnt lgkmcnt(0)
	v_mfma_f32_16x16x32_bf16 v[60:63], v[144:147], v[172:175], v[60:63]
	v_mfma_f32_16x16x32_bf16 v[56:59], v[160:163], v[172:175], v[56:59]
	v_mfma_f32_16x16x32_bf16 v[44:47], v[144:147], v[180:183], v[44:47]
	v_mfma_f32_16x16x32_bf16 v[40:43], v[160:163], v[180:183], v[40:43]
	v_mfma_f32_16x16x32_bf16 v[28:31], v[144:147], v[188:191], v[28:31]
	v_mfma_f32_16x16x32_bf16 v[24:27], v[160:163], v[188:191], v[24:27]
	v_mfma_f32_16x16x32_bf16 v[12:15], v[144:147], v[196:199], v[12:15]
	v_mfma_f32_16x16x32_bf16 v[8:11], v[160:163], v[196:199], v[8:11]
	v_mfma_f32_16x16x32_bf16 v[60:63], v[156:159], v[176:179], v[60:63]
	v_mfma_f32_16x16x32_bf16 v[56:59], v[164:167], v[176:179], v[56:59]
	v_mfma_f32_16x16x32_bf16 v[44:47], v[156:159], v[184:187], v[44:47]
	v_mfma_f32_16x16x32_bf16 v[40:43], v[164:167], v[184:187], v[40:43]
	v_mfma_f32_16x16x32_bf16 v[28:31], v[156:159], v[192:195], v[28:31]
	v_mfma_f32_16x16x32_bf16 v[24:27], v[164:167], v[192:195], v[24:27]
	v_mfma_f32_16x16x32_bf16 v[12:15], v[156:159], v[200:203], v[12:15]
	v_mfma_f32_16x16x32_bf16 v[8:11], v[164:167], v[200:203], v[8:11]
	s_setprio 0
	s_barrier
	s_add_u32 s30, s30, 0x80080
	s_addc_u32 s31, s31, 0
	s_add_i32 s34, s34, s38
	v_lshl_add_u64 v[144:145], s[30:31], 0, v[130:131]
	s_mov_b32 m0, s34
	s_nop 0
	global_load_lds_dwordx4 v[144:145], off
	v_lshl_add_u64 v[144:145], s[30:31], 0, v[134:135]
	s_add_i32 m0, s34, 0x2000
	s_nop 0
	global_load_lds_dwordx4 v[144:145], off
	s_waitcnt vmcnt(10)
	s_barrier
	s_setprio 1
	v_mfma_f32_16x16x32_bf16 v[52:55], v[204:207], v[172:175], v[52:55]
	v_mfma_f32_16x16x32_bf16 v[48:51], v[212:215], v[172:175], v[48:51]
	v_mfma_f32_16x16x32_bf16 v[36:39], v[204:207], v[180:183], v[36:39]
	v_mfma_f32_16x16x32_bf16 v[32:35], v[212:215], v[180:183], v[32:35]
	v_mfma_f32_16x16x32_bf16 v[20:23], v[204:207], v[188:191], v[20:23]
	v_mfma_f32_16x16x32_bf16 v[16:19], v[212:215], v[188:191], v[16:19]
	v_mfma_f32_16x16x32_bf16 v[4:7], v[204:207], v[196:199], v[4:7]
	v_mfma_f32_16x16x32_bf16 v[0:3], v[212:215], v[196:199], v[0:3]
	v_mfma_f32_16x16x32_bf16 v[52:55], v[208:211], v[176:179], v[52:55]
	v_mfma_f32_16x16x32_bf16 v[48:51], v[216:219], v[176:179], v[48:51]
	v_mfma_f32_16x16x32_bf16 v[36:39], v[208:211], v[184:187], v[36:39]
	v_mfma_f32_16x16x32_bf16 v[32:35], v[216:219], v[184:187], v[32:35]
	v_mfma_f32_16x16x32_bf16 v[20:23], v[208:211], v[192:195], v[20:23]
	v_mfma_f32_16x16x32_bf16 v[16:19], v[216:219], v[192:195], v[16:19]
	v_mfma_f32_16x16x32_bf16 v[4:7], v[208:211], v[200:203], v[4:7]
	v_mfma_f32_16x16x32_bf16 v[0:3], v[216:219], v[200:203], v[0:3]
	s_setprio 0
	s_add_i32 s60, s60, 2
	s_add_u32 s0, s0, 0x100
	s_addc_u32 s1, s1, 0
	s_add_u32 s58, s58, 0x100
	s_addc_u32 s59, s59, 0
	s_cmp_gt_u32 s60, 29
	s_barrier
	s_cbranch_scc0 .LBB0_1039
	v_lshl_add_u32 v156, s28, 8, v148
	v_ashrrev_i32_e32 v157, 31, v156
	v_lshl_add_u64 v[144:145], v[156:157], 2, s[8:9]
	v_lshl_or_b32 v146, s55, 8, v150
	v_ashrrev_i32_e32 v147, 31, v146
	v_lshlrev_b64 v[162:163], 1, v[146:147]
	v_lshlrev_b64 v[160:161], 12, v[156:157]
	v_readlane_b32 s0, v234, 9
	v_readlane_b32 s1, v234, 10
	v_or_b32_e32 v158, 16, v156
	v_ashrrev_i32_e32 v159, 31, v158
	s_mov_b32 s55, s20
	s_mov_b32 s28, s22
	s_mov_b64 s[30:31], s[26:27]
	s_mov_b64 s[34:35], s[24:25]
	v_fmamk_f32 v146, v236, 0x3a000000, v154
	v_mul_f32_e32 v147, 0x4b800000, v146
	v_cmp_gt_f32_e32 vcc, s50, v146
	s_nop 1
	v_cndmask_b32_e32 v146, v146, v147, vcc
	v_rsq_f32_e32 v155, v146
	v_lshl_add_u64 v[146:147], s[0:1], 0, v[160:161]
	v_lshl_add_u64 v[146:147], v[146:147], 0, v[162:163]
	v_lshl_add_u64 v[160:161], v[158:159], 2, s[8:9]
	v_mul_f32_e32 v157, 0x45800000, v155
	v_cndmask_b32_e32 v164, v155, v157, vcc
	v_pk_mul_f32 v[126:127], v[126:127], v[164:165] op_sel_hi:[1,0]
	v_pk_mul_f32 v[124:125], v[124:125], v[164:165] op_sel_hi:[1,0]
	v_pk_mul_f32 v[122:123], v[122:123], v[164:165] op_sel_hi:[1,0]
	v_pk_mul_f32 v[120:121], v[120:121], v[164:165] op_sel_hi:[1,0]
	v_pk_mul_f32 v[118:119], v[118:119], v[164:165] op_sel_hi:[1,0]
	v_pk_mul_f32 v[116:117], v[116:117], v[164:165] op_sel_hi:[1,0]
	v_pk_mul_f32 v[166:167], v[114:115], v[164:165] op_sel_hi:[1,0]
	v_pk_mul_f32 v[164:165], v[112:113], v[164:165] op_sel_hi:[1,0]
	v_cvt_pk_bf16_f32 v112, v124, v125
	v_cvt_pk_bf16_f32 v113, v126, v127
	v_cvt_pk_bf16_f32 v114, v120, v121
	v_cvt_pk_bf16_f32 v115, v122, v123
	v_cvt_pk_bf16_f32 v116, v116, v117
	v_cvt_pk_bf16_f32 v117, v118, v119
	v_cvt_pk_bf16_f32 v118, v164, v165
	v_cvt_pk_bf16_f32 v119, v166, v167
	global_store_dwordx4 v[146:147], v[112:115], off
	global_store_dwordx4 v[146:147], v[116:119], off offset:256
	v_lshlrev_b64 v[114:115], 12, v[158:159]
	v_or_b32_e32 v112, 32, v156
	v_lshl_add_u64 v[114:115], s[0:1], 0, v[114:115]
	v_ashrrev_i32_e32 v113, 31, v112
	v_lshl_add_u64 v[114:115], v[114:115], 0, v[162:163]
	v_fmamk_f32 v116, v237, 0x3a000000, v154
	v_mul_f32_e32 v117, 0x4b800000, v116
	v_cmp_gt_f32_e32 vcc, s50, v116
	s_nop 1
	v_cndmask_b32_e32 v116, v116, v117, vcc
	v_rsq_f32_e32 v118, v116
	v_lshl_add_u64 v[116:117], v[112:113], 2, s[8:9]
	v_mul_f32_e32 v119, 0x45800000, v118
	v_cndmask_b32_e32 v118, v118, v119, vcc
	v_pk_mul_f32 v[110:111], v[110:111], v[118:119] op_sel_hi:[1,0]
	v_pk_mul_f32 v[108:109], v[108:109], v[118:119] op_sel_hi:[1,0]
	v_pk_mul_f32 v[106:107], v[106:107], v[118:119] op_sel_hi:[1,0]
	v_pk_mul_f32 v[104:105], v[104:105], v[118:119] op_sel_hi:[1,0]
	v_pk_mul_f32 v[102:103], v[102:103], v[118:119] op_sel_hi:[1,0]
	v_pk_mul_f32 v[100:101], v[100:101], v[118:119] op_sel_hi:[1,0]
	v_pk_mul_f32 v[120:121], v[98:99], v[118:119] op_sel_hi:[1,0]
	v_pk_mul_f32 v[118:119], v[96:97], v[118:119] op_sel_hi:[1,0]
	v_cvt_pk_bf16_f32 v96, v108, v109
	v_cvt_pk_bf16_f32 v97, v110, v111
	v_cvt_pk_bf16_f32 v98, v104, v105
	v_cvt_pk_bf16_f32 v99, v106, v107
	v_cvt_pk_bf16_f32 v100, v100, v101
	v_cvt_pk_bf16_f32 v101, v102, v103
	v_cvt_pk_bf16_f32 v102, v118, v119
	v_cvt_pk_bf16_f32 v103, v120, v121
	global_store_dwordx4 v[114:115], v[96:99], off
	global_store_dwordx4 v[114:115], v[100:103], off offset:256
	v_lshlrev_b64 v[98:99], 12, v[112:113]
	v_or_b32_e32 v96, 48, v156
	v_lshl_add_u64 v[98:99], s[0:1], 0, v[98:99]
	v_ashrrev_i32_e32 v97, 31, v96
	v_lshl_add_u64 v[98:99], v[98:99], 0, v[162:163]
	v_fmamk_f32 v100, v238, 0x3a000000, v154
	v_mul_f32_e32 v101, 0x4b800000, v100
	v_cmp_gt_f32_e32 vcc, s50, v100
	s_nop 1
	v_cndmask_b32_e32 v100, v100, v101, vcc
	v_rsq_f32_e32 v102, v100
	v_lshl_add_u64 v[100:101], v[96:97], 2, s[8:9]
	v_mul_f32_e32 v103, 0x45800000, v102
	v_cndmask_b32_e32 v102, v102, v103, vcc
	v_pk_mul_f32 v[94:95], v[94:95], v[102:103] op_sel_hi:[1,0]
	v_pk_mul_f32 v[92:93], v[92:93], v[102:103] op_sel_hi:[1,0]
	v_pk_mul_f32 v[90:91], v[90:91], v[102:103] op_sel_hi:[1,0]
	v_pk_mul_f32 v[88:89], v[88:89], v[102:103] op_sel_hi:[1,0]
	v_pk_mul_f32 v[86:87], v[86:87], v[102:103] op_sel_hi:[1,0]
	v_pk_mul_f32 v[84:85], v[84:85], v[102:103] op_sel_hi:[1,0]
	v_pk_mul_f32 v[104:105], v[82:83], v[102:103] op_sel_hi:[1,0]
	v_pk_mul_f32 v[102:103], v[80:81], v[102:103] op_sel_hi:[1,0]
	v_cvt_pk_bf16_f32 v80, v92, v93
	v_cvt_pk_bf16_f32 v81, v94, v95
	v_cvt_pk_bf16_f32 v82, v88, v89
	v_cvt_pk_bf16_f32 v83, v90, v91
	v_cvt_pk_bf16_f32 v84, v84, v85
	v_cvt_pk_bf16_f32 v85, v86, v87
	v_cvt_pk_bf16_f32 v86, v102, v103
	v_cvt_pk_bf16_f32 v87, v104, v105
	global_store_dwordx4 v[98:99], v[80:83], off
	global_store_dwordx4 v[98:99], v[84:87], off offset:256
	v_fmamk_f32 v80, v239, 0x3a000000, v154
	v_mul_f32_e32 v81, 0x4b800000, v80
	v_cmp_gt_f32_e32 vcc, s50, v80
	s_nop 1
	v_cndmask_b32_e32 v80, v80, v81, vcc
	v_rsq_f32_e32 v82, v80
	v_lshlrev_b64 v[80:81], 12, v[96:97]
	v_lshl_add_u64 v[80:81], s[0:1], 0, v[80:81]
	v_lshl_add_u64 v[80:81], v[80:81], 0, v[162:163]
	v_mul_f32_e32 v83, 0x45800000, v82
	v_cndmask_b32_e32 v82, v82, v83, vcc
	v_pk_mul_f32 v[78:79], v[78:79], v[82:83] op_sel_hi:[1,0]
	v_pk_mul_f32 v[76:77], v[76:77], v[82:83] op_sel_hi:[1,0]
	v_pk_mul_f32 v[74:75], v[74:75], v[82:83] op_sel_hi:[1,0]
	v_pk_mul_f32 v[72:73], v[72:73], v[82:83] op_sel_hi:[1,0]
	v_pk_mul_f32 v[70:71], v[70:71], v[82:83] op_sel_hi:[1,0]
	v_pk_mul_f32 v[68:69], v[68:69], v[82:83] op_sel_hi:[1,0]
	v_pk_mul_f32 v[84:85], v[66:67], v[82:83] op_sel_hi:[1,0]
	v_pk_mul_f32 v[82:83], v[64:65], v[82:83] op_sel_hi:[1,0]
	v_cvt_pk_bf16_f32 v64, v76, v77
	v_cvt_pk_bf16_f32 v65, v78, v79
	v_cvt_pk_bf16_f32 v66, v72, v73
	v_cvt_pk_bf16_f32 v67, v74, v75
	v_cvt_pk_bf16_f32 v68, v68, v69
	v_cvt_pk_bf16_f32 v69, v70, v71
	v_cvt_pk_bf16_f32 v70, v82, v83
	v_cvt_pk_bf16_f32 v71, v84, v85
	global_store_dwordx4 v[80:81], v[64:67], off
	global_store_dwordx4 v[80:81], v[68:71], off offset:256
	v_lshl_add_u64 v[64:65], v[146:147], 0, s[10:11]
	v_fmamk_f32 v66, v240, 0x3a000000, v154
	v_mul_f32_e32 v67, 0x4b800000, v66
	v_cmp_gt_f32_e32 vcc, s50, v66
	s_nop 1
	v_cndmask_b32_e32 v66, v66, v67, vcc
	v_rsq_f32_e32 v68, v66
	v_add_co_u32_e64 v66, s[0:1], s51, v146
	v_mul_f32_e32 v69, 0x45800000, v68
	v_cndmask_b32_e32 v68, v68, v69, vcc
	v_pk_mul_f32 v[62:63], v[62:63], v[68:69] op_sel_hi:[1,0]
	v_pk_mul_f32 v[60:61], v[60:61], v[68:69] op_sel_hi:[1,0]
	v_pk_mul_f32 v[58:59], v[58:59], v[68:69] op_sel_hi:[1,0]
	v_pk_mul_f32 v[56:57], v[56:57], v[68:69] op_sel_hi:[1,0]
	v_addc_co_u32_e64 v67, s[0:1], 0, v147, s[0:1]
	v_pk_mul_f32 v[54:55], v[54:55], v[68:69] op_sel_hi:[1,0]
	v_pk_mul_f32 v[52:53], v[52:53], v[68:69] op_sel_hi:[1,0]
	v_pk_mul_f32 v[70:71], v[50:51], v[68:69] op_sel_hi:[1,0]
	v_pk_mul_f32 v[68:69], v[48:49], v[68:69] op_sel_hi:[1,0]
	v_cvt_pk_bf16_f32 v48, v60, v61
	v_cvt_pk_bf16_f32 v49, v62, v63
	v_cvt_pk_bf16_f32 v50, v56, v57
	v_cvt_pk_bf16_f32 v51, v58, v59
	v_cvt_pk_bf16_f32 v52, v52, v53
	v_cvt_pk_bf16_f32 v53, v54, v55
	v_cvt_pk_bf16_f32 v54, v68, v69
	v_cvt_pk_bf16_f32 v55, v70, v71
	global_store_dwordx4 v[66:67], v[48:51], off
	global_store_dwordx4 v[64:65], v[52:55], off offset:256
	v_lshl_add_u64 v[48:49], v[146:147], 0, s[14:15]
	v_fmamk_f32 v50, v241, 0x3a000000, v154
	v_mul_f32_e32 v51, 0x4b800000, v50
	v_cmp_gt_f32_e32 vcc, s50, v50
	s_nop 1
	v_cndmask_b32_e32 v50, v50, v51, vcc
	v_rsq_f32_e32 v52, v50
	v_add_co_u32_e64 v50, s[0:1], s52, v146
	v_mul_f32_e32 v53, 0x45800000, v52
	v_cndmask_b32_e32 v52, v52, v53, vcc
	v_pk_mul_f32 v[46:47], v[46:47], v[52:53] op_sel_hi:[1,0]
	v_pk_mul_f32 v[44:45], v[44:45], v[52:53] op_sel_hi:[1,0]
	v_pk_mul_f32 v[42:43], v[42:43], v[52:53] op_sel_hi:[1,0]
	v_pk_mul_f32 v[40:41], v[40:41], v[52:53] op_sel_hi:[1,0]
	v_addc_co_u32_e64 v51, s[0:1], 0, v147, s[0:1]
	v_pk_mul_f32 v[38:39], v[38:39], v[52:53] op_sel_hi:[1,0]
	v_pk_mul_f32 v[36:37], v[36:37], v[52:53] op_sel_hi:[1,0]
	v_pk_mul_f32 v[54:55], v[34:35], v[52:53] op_sel_hi:[1,0]
	v_pk_mul_f32 v[52:53], v[32:33], v[52:53] op_sel_hi:[1,0]
	v_cvt_pk_bf16_f32 v32, v44, v45
	v_cvt_pk_bf16_f32 v33, v46, v47
	v_cvt_pk_bf16_f32 v34, v40, v41
	v_cvt_pk_bf16_f32 v35, v42, v43
	v_cvt_pk_bf16_f32 v36, v36, v37
	v_cvt_pk_bf16_f32 v37, v38, v39
	v_cvt_pk_bf16_f32 v38, v52, v53
	v_cvt_pk_bf16_f32 v39, v54, v55
	global_store_dwordx4 v[50:51], v[32:35], off
	global_store_dwordx4 v[48:49], v[36:39], off offset:256
	v_lshl_add_u64 v[32:33], v[146:147], 0, s[16:17]
	v_fmamk_f32 v34, v242, 0x3a000000, v154
	v_mul_f32_e32 v35, 0x4b800000, v34
	v_cmp_gt_f32_e32 vcc, s50, v34
	s_nop 1
	v_cndmask_b32_e32 v34, v34, v35, vcc
	v_rsq_f32_e32 v36, v34
	v_add_co_u32_e64 v34, s[0:1], s53, v146
	v_mul_f32_e32 v37, 0x45800000, v36
	v_cndmask_b32_e32 v36, v36, v37, vcc
	v_pk_mul_f32 v[30:31], v[30:31], v[36:37] op_sel_hi:[1,0]
	v_pk_mul_f32 v[28:29], v[28:29], v[36:37] op_sel_hi:[1,0]
	v_pk_mul_f32 v[26:27], v[26:27], v[36:37] op_sel_hi:[1,0]
	v_pk_mul_f32 v[24:25], v[24:25], v[36:37] op_sel_hi:[1,0]
	v_addc_co_u32_e64 v35, s[0:1], 0, v147, s[0:1]
	v_pk_mul_f32 v[22:23], v[22:23], v[36:37] op_sel_hi:[1,0]
	v_pk_mul_f32 v[20:21], v[20:21], v[36:37] op_sel_hi:[1,0]
	v_pk_mul_f32 v[38:39], v[18:19], v[36:37] op_sel_hi:[1,0]
	v_pk_mul_f32 v[36:37], v[16:17], v[36:37] op_sel_hi:[1,0]
	v_cvt_pk_bf16_f32 v16, v28, v29
	v_cvt_pk_bf16_f32 v17, v30, v31
	v_cvt_pk_bf16_f32 v18, v24, v25
	v_cvt_pk_bf16_f32 v19, v26, v27
	v_cvt_pk_bf16_f32 v20, v20, v21
	v_cvt_pk_bf16_f32 v21, v22, v23
	v_cvt_pk_bf16_f32 v22, v36, v37
	v_cvt_pk_bf16_f32 v23, v38, v39
	global_store_dwordx4 v[34:35], v[16:19], off
	global_store_dwordx4 v[32:33], v[20:23], off offset:256
	s_and_b64 vcc, exec, s[2:3]
	v_lshl_add_u64 v[16:17], v[146:147], 0, s[18:19]
	v_fmamk_f32 v18, v243, 0x3a000000, v154
	v_mul_f32_e32 v19, 0x4b800000, v18
	v_cmp_gt_f32_e64 s[0:1], s50, v18
	s_nop 1
	v_cndmask_b32_e64 v18, v18, v19, s[0:1]
	v_rsq_f32_e32 v20, v18
	v_add_co_u32_e64 v18, s[2:3], s54, v146
	v_mul_f32_e32 v21, 0x45800000, v20
	v_cndmask_b32_e64 v20, v20, v21, s[0:1]
	v_pk_mul_f32 v[14:15], v[14:15], v[20:21] op_sel_hi:[1,0]
	v_pk_mul_f32 v[12:13], v[12:13], v[20:21] op_sel_hi:[1,0]
	v_pk_mul_f32 v[10:11], v[10:11], v[20:21] op_sel_hi:[1,0]
	v_pk_mul_f32 v[8:9], v[8:9], v[20:21] op_sel_hi:[1,0]
	v_addc_co_u32_e64 v19, s[2:3], 0, v147, s[2:3]
	v_pk_mul_f32 v[6:7], v[6:7], v[20:21] op_sel_hi:[1,0]
	v_pk_mul_f32 v[4:5], v[4:5], v[20:21] op_sel_hi:[1,0]
	v_pk_mul_f32 v[22:23], v[2:3], v[20:21] op_sel_hi:[1,0]
	v_pk_mul_f32 v[20:21], v[0:1], v[20:21] op_sel_hi:[1,0]
	v_cvt_pk_bf16_f32 v0, v12, v13
	v_cvt_pk_bf16_f32 v1, v14, v15
	v_cvt_pk_bf16_f32 v2, v8, v9
	v_cvt_pk_bf16_f32 v3, v10, v11
	v_cvt_pk_bf16_f32 v4, v4, v5
	v_cvt_pk_bf16_f32 v5, v6, v7
	v_cvt_pk_bf16_f32 v6, v20, v21
	v_cvt_pk_bf16_f32 v7, v22, v23
	global_store_dwordx4 v[18:19], v[0:3], off
	global_store_dwordx4 v[16:17], v[4:7], off offset:256
	s_cbranch_vccz .LBB0_1032
	s_waitcnt vmcnt(0)
	s_cmpk_gt_u32 s33, 0xff
	s_cbranch_scc1 .LBB0_1043
	s_barrier

.LBB0_1184:
	ds_read_b128 v[144:147], v151
	ds_read_b128 v[156:159], v151 offset:1024
	ds_read_b128 v[160:163], v151 offset:2048
	ds_read_b128 v[164:167], v151 offset:3072
	s_add_u32 s26, s24, 0xfff80080
	s_addc_u32 s27, s25, -1
	s_cmp_eq_u32 s49, 28
	s_cselect_b32 s29, s15, s27
	s_cselect_b32 s28, s21, s26
	s_cselect_b32 s27, s13, s48
	s_cselect_b32 s26, s46, s47
	v_lshl_add_u64 v[168:169], s[24:25], 0, v[136:137]
	s_add_i32 m0, s23, 0xc000
	ds_read_b128 v[172:175], v152
	ds_read_b128 v[176:179], v152 offset:1024
	ds_read_b128 v[180:183], v152 offset:2048
	ds_read_b128 v[184:187], v152 offset:3072
	ds_read_b128 v[188:191], v152 offset:4096
	ds_read_b128 v[192:195], v152 offset:5120
	ds_read_b128 v[196:199], v152 offset:6144
	ds_read_b128 v[200:203], v152 offset:7168
	global_load_lds_dwordx4 v[168:169], off
	v_lshl_add_u64 v[168:169], s[24:25], 0, v[138:139]
	s_add_i32 m0, s23, 0xe000
	s_nop 0
	global_load_lds_dwordx4 v[168:169], off
	s_waitcnt vmcnt(10)
	s_waitcnt lgkmcnt(8)
	s_barrier
	s_waitcnt lgkmcnt(0)
	s_setprio 1
	s_waitcnt lgkmcnt(0)
	v_mfma_f32_16x16x32_bf16 v[124:127], v[144:147], v[172:175], v[124:127]
	v_mfma_f32_16x16x32_bf16 v[120:123], v[160:163], v[172:175], v[120:123]
	v_mfma_f32_16x16x32_bf16 v[108:111], v[144:147], v[180:183], v[108:111]
	v_mfma_f32_16x16x32_bf16 v[104:107], v[160:163], v[180:183], v[104:107]
	v_mfma_f32_16x16x32_bf16 v[92:95], v[144:147], v[188:191], v[92:95]
	v_mfma_f32_16x16x32_bf16 v[88:91], v[160:163], v[188:191], v[88:91]
	v_mfma_f32_16x16x32_bf16 v[76:79], v[144:147], v[196:199], v[76:79]
	v_mfma_f32_16x16x32_bf16 v[72:75], v[160:163], v[196:199], v[72:75]
	v_mfma_f32_16x16x32_bf16 v[124:127], v[156:159], v[176:179], v[124:127]
	v_mfma_f32_16x16x32_bf16 v[120:123], v[164:167], v[176:179], v[120:123]
	v_mfma_f32_16x16x32_bf16 v[108:111], v[156:159], v[184:187], v[108:111]
	v_mfma_f32_16x16x32_bf16 v[104:107], v[164:167], v[184:187], v[104:107]
	v_mfma_f32_16x16x32_bf16 v[92:95], v[156:159], v[192:195], v[92:95]
	v_mfma_f32_16x16x32_bf16 v[88:91], v[164:167], v[192:195], v[88:91]
	v_mfma_f32_16x16x32_bf16 v[76:79], v[156:159], v[200:203], v[76:79]
	v_mfma_f32_16x16x32_bf16 v[72:75], v[164:167], v[200:203], v[72:75]
	s_setprio 0
	s_barrier
	s_add_i32 s50, s44, s34
	v_lshl_add_u64 v[168:169], s[26:27], 0, v[130:131]
	s_mov_b32 m0, s50
	ds_read_b128 v[204:207], v153
	ds_read_b128 v[208:211], v153 offset:1024
	ds_read_b128 v[212:215], v153 offset:2048
	ds_read_b128 v[216:219], v153 offset:3072
	global_load_lds_dwordx4 v[168:169], off
	v_lshl_add_u64 v[220:221], s[26:27], 0, v[134:135]
	s_add_i32 m0, s50, 0x2000
	s_nop 0
	global_load_lds_dwordx4 v[220:221], off
	s_waitcnt vmcnt(10)
	s_barrier
	s_waitcnt lgkmcnt(0)
	s_setprio 1
	s_waitcnt lgkmcnt(0)
	v_mfma_f32_16x16x32_bf16 v[116:119], v[204:207], v[172:175], v[116:119]
	v_mfma_f32_16x16x32_bf16 v[112:115], v[212:215], v[172:175], v[112:115]
	v_mfma_f32_16x16x32_bf16 v[100:103], v[204:207], v[180:183], v[100:103]
	v_mfma_f32_16x16x32_bf16 v[96:99], v[212:215], v[180:183], v[96:99]
	v_mfma_f32_16x16x32_bf16 v[84:87], v[204:207], v[188:191], v[84:87]
	v_mfma_f32_16x16x32_bf16 v[80:83], v[212:215], v[188:191], v[80:83]
	v_mfma_f32_16x16x32_bf16 v[68:71], v[204:207], v[196:199], v[68:71]
	v_mfma_f32_16x16x32_bf16 v[64:67], v[212:215], v[196:199], v[64:67]
	v_mfma_f32_16x16x32_bf16 v[116:119], v[208:211], v[176:179], v[116:119]
	v_mfma_f32_16x16x32_bf16 v[112:115], v[216:219], v[176:179], v[112:115]
	v_mfma_f32_16x16x32_bf16 v[100:103], v[208:211], v[184:187], v[100:103]
	v_mfma_f32_16x16x32_bf16 v[96:99], v[216:219], v[184:187], v[96:99]
	v_mfma_f32_16x16x32_bf16 v[84:87], v[208:211], v[192:195], v[84:87]
	v_mfma_f32_16x16x32_bf16 v[80:83], v[216:219], v[192:195], v[80:83]
	v_mfma_f32_16x16x32_bf16 v[68:71], v[208:211], v[200:203], v[68:71]
	v_mfma_f32_16x16x32_bf16 v[64:67], v[216:219], v[200:203], v[64:67]
	s_setprio 0
	s_mov_b32 m0, s23
	v_lshl_add_u64 v[222:223], s[28:29], 0, v[128:129]
	s_barrier
	ds_read_b128 v[172:175], v152 offset:16384
	ds_read_b128 v[176:179], v152 offset:17408
	ds_read_b128 v[180:183], v152 offset:18432
	ds_read_b128 v[184:187], v152 offset:19456
	ds_read_b128 v[188:191], v152 offset:20480
	ds_read_b128 v[192:195], v152 offset:21504
	ds_read_b128 v[196:199], v152 offset:22528
	ds_read_b128 v[200:203], v152 offset:23552
	global_load_lds_dwordx4 v[222:223], off
	v_lshl_add_u64 v[224:225], s[28:29], 0, v[132:133]
	s_mov_b32 m0, s35
	s_nop 0
	global_load_lds_dwordx4 v[224:225], off
	s_barrier
	s_waitcnt lgkmcnt(0)
	s_setprio 1
	s_waitcnt lgkmcnt(0)
	v_mfma_f32_16x16x32_bf16 v[60:63], v[144:147], v[172:175], v[60:63]
	v_mfma_f32_16x16x32_bf16 v[56:59], v[160:163], v[172:175], v[56:59]
	v_mfma_f32_16x16x32_bf16 v[44:47], v[144:147], v[180:183], v[44:47]
	v_mfma_f32_16x16x32_bf16 v[40:43], v[160:163], v[180:183], v[40:43]
	v_mfma_f32_16x16x32_bf16 v[28:31], v[144:147], v[188:191], v[28:31]
	v_mfma_f32_16x16x32_bf16 v[24:27], v[160:163], v[188:191], v[24:27]
	v_mfma_f32_16x16x32_bf16 v[12:15], v[144:147], v[196:199], v[12:15]
	v_mfma_f32_16x16x32_bf16 v[8:11], v[160:163], v[196:199], v[8:11]
	v_mfma_f32_16x16x32_bf16 v[60:63], v[156:159], v[176:179], v[60:63]
	v_mfma_f32_16x16x32_bf16 v[56:59], v[164:167], v[176:179], v[56:59]
	v_mfma_f32_16x16x32_bf16 v[44:47], v[156:159], v[184:187], v[44:47]
	v_mfma_f32_16x16x32_bf16 v[40:43], v[164:167], v[184:187], v[40:43]
	v_mfma_f32_16x16x32_bf16 v[28:31], v[156:159], v[192:195], v[28:31]
	v_mfma_f32_16x16x32_bf16 v[24:27], v[164:167], v[192:195], v[24:27]
	v_mfma_f32_16x16x32_bf16 v[12:15], v[156:159], v[200:203], v[12:15]
	v_mfma_f32_16x16x32_bf16 v[8:11], v[164:167], v[200:203], v[8:11]
	s_setprio 0
	s_barrier
	s_add_u32 s50, s26, 0x80000
	s_addc_u32 s51, s27, 0
	s_add_i32 s52, s45, s34
	v_lshl_add_u64 v[144:145], s[50:51], 0, v[130:131]
	s_mov_b32 m0, s52
	s_nop 0
	global_load_lds_dwordx4 v[144:145], off
	v_lshl_add_u64 v[144:145], s[50:51], 0, v[134:135]
	s_add_i32 m0, s52, 0x2000
	s_nop 0
	global_load_lds_dwordx4 v[144:145], off
	s_waitcnt vmcnt(10)
	s_barrier
	s_setprio 1
	v_mfma_f32_16x16x32_bf16 v[52:55], v[204:207], v[172:175], v[52:55]
	v_mfma_f32_16x16x32_bf16 v[48:51], v[212:215], v[172:175], v[48:51]
	v_mfma_f32_16x16x32_bf16 v[36:39], v[204:207], v[180:183], v[36:39]
	v_mfma_f32_16x16x32_bf16 v[32:35], v[212:215], v[180:183], v[32:35]
	v_mfma_f32_16x16x32_bf16 v[20:23], v[204:207], v[188:191], v[20:23]
	v_mfma_f32_16x16x32_bf16 v[16:19], v[212:215], v[188:191], v[16:19]
	v_mfma_f32_16x16x32_bf16 v[4:7], v[204:207], v[196:199], v[4:7]
	v_mfma_f32_16x16x32_bf16 v[0:3], v[212:215], v[196:199], v[0:3]
	v_mfma_f32_16x16x32_bf16 v[52:55], v[208:211], v[176:179], v[52:55]
	v_mfma_f32_16x16x32_bf16 v[48:51], v[216:219], v[176:179], v[48:51]
	v_mfma_f32_16x16x32_bf16 v[36:39], v[208:211], v[184:187], v[36:39]
	v_mfma_f32_16x16x32_bf16 v[32:35], v[216:219], v[184:187], v[32:35]
	v_mfma_f32_16x16x32_bf16 v[20:23], v[208:211], v[192:195], v[20:23]
	v_mfma_f32_16x16x32_bf16 v[16:19], v[216:219], v[192:195], v[16:19]
	v_mfma_f32_16x16x32_bf16 v[4:7], v[208:211], v[200:203], v[4:7]
	v_mfma_f32_16x16x32_bf16 v[0:3], v[216:219], v[200:203], v[0:3]
	s_setprio 0
	s_add_i32 s50, 0, 0x18000
	v_add_u32_e32 v155, s50, v149
	s_barrier
	ds_read_b128 v[144:147], v155
	ds_read_b128 v[156:159], v155 offset:1024
	ds_read_b128 v[160:163], v155 offset:2048
	ds_read_b128 v[164:167], v155 offset:3072
	s_add_u32 s28, s28, 0x80000
	s_addc_u32 s29, s29, 0
	s_mov_b32 m0, s36
	v_lshl_add_u64 v[204:205], s[28:29], 0, v[128:129]
	ds_read_b128 v[172:175], v152 offset:32768
	ds_read_b128 v[176:179], v152 offset:33792
	ds_read_b128 v[180:183], v152 offset:34816
	ds_read_b128 v[184:187], v152 offset:35840
	ds_read_b128 v[188:191], v152 offset:36864
	ds_read_b128 v[192:195], v152 offset:37888
	ds_read_b128 v[196:199], v152 offset:38912
	ds_read_b128 v[200:203], v152 offset:39936
	global_load_lds_dwordx4 v[204:205], off
	v_lshl_add_u64 v[204:205], s[28:29], 0, v[132:133]
	s_mov_b32 m0, s37
	s_nop 0
	global_load_lds_dwordx4 v[204:205], off
	s_waitcnt vmcnt(10)
	s_waitcnt lgkmcnt(8)
	s_barrier
	s_waitcnt lgkmcnt(0)
	s_setprio 1
	s_waitcnt lgkmcnt(0)
	v_mfma_f32_16x16x32_bf16 v[124:127], v[144:147], v[172:175], v[124:127]
	v_mfma_f32_16x16x32_bf16 v[120:123], v[160:163], v[172:175], v[120:123]
	v_mfma_f32_16x16x32_bf16 v[108:111], v[144:147], v[180:183], v[108:111]
	v_mfma_f32_16x16x32_bf16 v[104:107], v[160:163], v[180:183], v[104:107]
	v_mfma_f32_16x16x32_bf16 v[92:95], v[144:147], v[188:191], v[92:95]
	v_mfma_f32_16x16x32_bf16 v[88:91], v[160:163], v[188:191], v[88:91]
	v_mfma_f32_16x16x32_bf16 v[76:79], v[144:147], v[196:199], v[76:79]
	v_mfma_f32_16x16x32_bf16 v[72:75], v[160:163], v[196:199], v[72:75]
	v_mfma_f32_16x16x32_bf16 v[124:127], v[156:159], v[176:179], v[124:127]
	v_mfma_f32_16x16x32_bf16 v[120:123], v[164:167], v[176:179], v[120:123]
	v_mfma_f32_16x16x32_bf16 v[108:111], v[156:159], v[184:187], v[108:111]
	v_mfma_f32_16x16x32_bf16 v[104:107], v[164:167], v[184:187], v[104:107]
	v_mfma_f32_16x16x32_bf16 v[92:95], v[156:159], v[192:195], v[92:95]
	v_mfma_f32_16x16x32_bf16 v[88:91], v[164:167], v[192:195], v[88:91]
	v_mfma_f32_16x16x32_bf16 v[76:79], v[156:159], v[200:203], v[76:79]
	v_mfma_f32_16x16x32_bf16 v[72:75], v[164:167], v[200:203], v[72:75]
	s_setprio 0
	s_barrier
	s_add_i32 s28, 0, 0x1c000
	s_add_i32 s29, s50, s34
	v_add_u32_e32 v155, s28, v149
	v_lshl_add_u64 v[168:169], v[168:169], 0, s[10:11]
	s_mov_b32 m0, s29
	ds_read_b128 v[204:207], v155
	ds_read_b128 v[208:211], v155 offset:1024
	ds_read_b128 v[212:215], v155 offset:2048
	ds_read_b128 v[216:219], v155 offset:3072
	global_load_lds_dwordx4 v[168:169], off
	v_lshl_add_u64 v[168:169], v[220:221], 0, s[10:11]
	s_add_i32 m0, s29, 0x2000
	s_nop 0
	global_load_lds_dwordx4 v[168:169], off
	s_waitcnt vmcnt(10)
	s_barrier
	s_waitcnt lgkmcnt(0)
	s_setprio 1
	s_waitcnt lgkmcnt(0)
	v_mfma_f32_16x16x32_bf16 v[116:119], v[204:207], v[172:175], v[116:119]
	v_mfma_f32_16x16x32_bf16 v[112:115], v[212:215], v[172:175], v[112:115]
	v_mfma_f32_16x16x32_bf16 v[100:103], v[204:207], v[180:183], v[100:103]
	v_mfma_f32_16x16x32_bf16 v[96:99], v[212:215], v[180:183], v[96:99]
	v_mfma_f32_16x16x32_bf16 v[84:87], v[204:207], v[188:191], v[84:87]
	v_mfma_f32_16x16x32_bf16 v[80:83], v[212:215], v[188:191], v[80:83]
	v_mfma_f32_16x16x32_bf16 v[68:71], v[204:207], v[196:199], v[68:71]
	v_mfma_f32_16x16x32_bf16 v[64:67], v[212:215], v[196:199], v[64:67]
	v_mfma_f32_16x16x32_bf16 v[116:119], v[208:211], v[176:179], v[116:119]
	v_mfma_f32_16x16x32_bf16 v[112:115], v[216:219], v[176:179], v[112:115]
	v_mfma_f32_16x16x32_bf16 v[100:103], v[208:211], v[184:187], v[100:103]
	v_mfma_f32_16x16x32_bf16 v[96:99], v[216:219], v[184:187], v[96:99]
	v_mfma_f32_16x16x32_bf16 v[84:87], v[208:211], v[192:195], v[84:87]
	v_mfma_f32_16x16x32_bf16 v[80:83], v[216:219], v[192:195], v[80:83]
	v_mfma_f32_16x16x32_bf16 v[68:71], v[208:211], v[200:203], v[68:71]
	v_mfma_f32_16x16x32_bf16 v[64:67], v[216:219], v[200:203], v[64:67]
	s_setprio 0
	s_mov_b32 m0, s39
	v_lshl_add_u64 v[168:169], v[222:223], 0, s[10:11]
	s_barrier
	ds_read_b128 v[172:175], v152 offset:49152
	ds_read_b128 v[176:179], v152 offset:50176
	ds_read_b128 v[180:183], v152 offset:51200
	ds_read_b128 v[184:187], v152 offset:52224
	ds_read_b128 v[188:191], v152 offset:53248
	ds_read_b128 v[192:195], v152 offset:54272
	ds_read_b128 v[196:199], v152 offset:55296
	ds_read_b128 v[200:203], v152 offset:56320
	global_load_lds_dwordx4 v[168:169], off
	v_lshl_add_u64 v[168:169], v[224:225], 0, s[10:11]
	s_mov_b32 m0, s40
	s_nop 0
	global_load_lds_dwordx4 v[168:169], off
	s_barrier
	s_waitcnt lgkmcnt(0)
	s_setprio 1
	s_waitcnt lgkmcnt(0)
	v_mfma_f32_16x16x32_bf16 v[60:63], v[144:147], v[172:175], v[60:63]
	v_mfma_f32_16x16x32_bf16 v[56:59], v[160:163], v[172:175], v[56:59]
	v_mfma_f32_16x16x32_bf16 v[44:47], v[144:147], v[180:183], v[44:47]
	v_mfma_f32_16x16x32_bf16 v[40:43], v[160:163], v[180:183], v[40:43]
	v_mfma_f32_16x16x32_bf16 v[28:31], v[144:147], v[188:191], v[28:31]
	v_mfma_f32_16x16x32_bf16 v[24:27], v[160:163], v[188:191], v[24:27]
	v_mfma_f32_16x16x32_bf16 v[12:15], v[144:147], v[196:199], v[12:15]
	v_mfma_f32_16x16x32_bf16 v[8:11], v[160:163], v[196:199], v[8:11]
	v_mfma_f32_16x16x32_bf16 v[60:63], v[156:159], v[176:179], v[60:63]
	v_mfma_f32_16x16x32_bf16 v[56:59], v[164:167], v[176:179], v[56:59]
	v_mfma_f32_16x16x32_bf16 v[44:47], v[156:159], v[184:187], v[44:47]
	v_mfma_f32_16x16x32_bf16 v[40:43], v[164:167], v[184:187], v[40:43]
	v_mfma_f32_16x16x32_bf16 v[28:31], v[156:159], v[192:195], v[28:31]
	v_mfma_f32_16x16x32_bf16 v[24:27], v[164:167], v[192:195], v[24:27]
	v_mfma_f32_16x16x32_bf16 v[12:15], v[156:159], v[200:203], v[12:15]
	v_mfma_f32_16x16x32_bf16 v[8:11], v[164:167], v[200:203], v[8:11]
	s_setprio 0
	s_barrier
	s_add_u32 s26, s26, 0x80080
	s_addc_u32 s27, s27, 0
	s_add_i32 s28, s28, s34
	v_lshl_add_u64 v[144:145], s[26:27], 0, v[130:131]
	s_mov_b32 m0, s28
	s_nop 0
	global_load_lds_dwordx4 v[144:145], off
	v_lshl_add_u64 v[144:145], s[26:27], 0, v[134:135]
	s_add_i32 m0, s28, 0x2000
	s_nop 0
	global_load_lds_dwordx4 v[144:145], off
	s_waitcnt vmcnt(10)
	s_barrier
	s_setprio 1
	v_mfma_f32_16x16x32_bf16 v[52:55], v[204:207], v[172:175], v[52:55]
	v_mfma_f32_16x16x32_bf16 v[48:51], v[212:215], v[172:175], v[48:51]
	v_mfma_f32_16x16x32_bf16 v[36:39], v[204:207], v[180:183], v[36:39]
	v_mfma_f32_16x16x32_bf16 v[32:35], v[212:215], v[180:183], v[32:35]
	v_mfma_f32_16x16x32_bf16 v[20:23], v[204:207], v[188:191], v[20:23]
	v_mfma_f32_16x16x32_bf16 v[16:19], v[212:215], v[188:191], v[16:19]
	v_mfma_f32_16x16x32_bf16 v[4:7], v[204:207], v[196:199], v[4:7]
	v_mfma_f32_16x16x32_bf16 v[0:3], v[212:215], v[196:199], v[0:3]
	v_mfma_f32_16x16x32_bf16 v[52:55], v[208:211], v[176:179], v[52:55]
	v_mfma_f32_16x16x32_bf16 v[48:51], v[216:219], v[176:179], v[48:51]
	v_mfma_f32_16x16x32_bf16 v[36:39], v[208:211], v[184:187], v[36:39]
	v_mfma_f32_16x16x32_bf16 v[32:35], v[216:219], v[184:187], v[32:35]
	v_mfma_f32_16x16x32_bf16 v[20:23], v[208:211], v[192:195], v[20:23]
	v_mfma_f32_16x16x32_bf16 v[16:19], v[216:219], v[192:195], v[16:19]
	v_mfma_f32_16x16x32_bf16 v[4:7], v[208:211], v[200:203], v[4:7]
	v_mfma_f32_16x16x32_bf16 v[0:3], v[216:219], v[200:203], v[0:3]
	s_setprio 0
	s_add_i32 s49, s49, 2
	s_add_u32 s24, s24, 0x100
	s_addc_u32 s25, s25, 0
	s_add_u32 s47, s47, 0x100
	s_addc_u32 s48, s48, 0
	s_cmp_gt_u32 s49, 29
	s_barrier
	s_cbranch_scc0 .LBB0_1184
	v_lshl_add_u32 v146, s20, 8, v148
	v_ashrrev_i32_e32 v147, 31, v146
	v_lshl_or_b32 v144, s22, 8, v150
	v_lshlrev_b32_e32 v179, 12, v146
	v_lshl_add_u32 v178, v144, 1, v179
	global_load_dwordx4 v[180:183], v178, s[6:7]
	global_load_dwordx4 v[184:187], v178, s[6:7] offset:256
	s_add_u32 s98, s6, 0x10000
	s_addc_u32 s99, s7, 0
	global_load_dwordx4 v[188:191], v178, s[98:99]
	global_load_dwordx4 v[192:195], v178, s[98:99] offset:256
	s_add_u32 s98, s6, 0x20000
	s_addc_u32 s99, s7, 0
	global_load_dwordx4 v[196:199], v178, s[98:99]
	global_load_dwordx4 v[200:203], v178, s[98:99] offset:256
	s_add_u32 s98, s6, 0x30000
	s_addc_u32 s99, s7, 0
	global_load_dwordx4 v[204:207], v178, s[98:99]
	global_load_dwordx4 v[208:211], v178, s[98:99] offset:256
	s_add_u32 s98, s6, 0x80000
	s_addc_u32 s99, s7, 0
	global_load_dwordx4 v[212:215], v178, s[98:99]
	global_load_dwordx4 v[216:219], v178, s[98:99] offset:256
	s_add_u32 s98, s6, 0x90000
	s_addc_u32 s99, s7, 0
	global_load_dwordx4 v[236:239], v178, s[98:99]
	global_load_dwordx4 v[240:243], v178, s[98:99] offset:256
	s_add_u32 s98, s6, 0xa0000
	s_addc_u32 s99, s7, 0
	global_load_dwordx4 v[244:247], v178, s[98:99]
	global_load_dwordx4 v[248:251], v178, s[98:99] offset:256
	s_add_u32 s98, s6, 0xb0000
	s_addc_u32 s99, s7, 0
	global_load_dwordx4 v[220:223], v178, s[98:99]
	global_load_dwordx4 v[252:255], v178, s[98:99] offset:256
	v_lshlrev_b64 v[156:157], 12, v[146:147]
	v_ashrrev_i32_e32 v145, 31, v144
	v_lshl_add_u64 v[156:157], s[6:7], 0, v[156:157]
	v_lshl_add_u64 v[166:167], v[144:145], 1, v[156:157]
	v_and_b32_e32 v156, 64, v154
	v_xor_b32_e32 v155, 16, v154
	v_add_u32_e32 v156, 64, v156
	v_xor_b32_e32 v157, 32, v154
	v_cmp_lt_i32_e32 vcc, v155, v156
	s_waitcnt vmcnt(14)
	v_lshlrev_b32_e32 v168, 16, v180
	v_and_b32_e32 v169, 0xffff0000, v180
	v_lshlrev_b32_e32 v180, 16, v181
	v_and_b32_e32 v181, 0xffff0000, v181
	v_lshlrev_b32_e32 v174, 16, v184
	v_and_b32_e32 v175, 0xffff0000, v184
	v_lshlrev_b32_e32 v184, 16, v185
	v_and_b32_e32 v185, 0xffff0000, v185
	v_cndmask_b32_e32 v155, v154, v155, vcc
	v_cmp_lt_i32_e32 vcc, v157, v156
	v_lshlrev_b32_e32 v172, 16, v182
	v_and_b32_e32 v173, 0xffff0000, v182
	v_lshlrev_b32_e32 v182, 16, v183
	v_and_b32_e32 v183, 0xffff0000, v183
	v_lshlrev_b32_e32 v176, 16, v186
	v_and_b32_e32 v177, 0xffff0000, v186
	v_lshlrev_b32_e32 v186, 16, v187
	v_and_b32_e32 v187, 0xffff0000, v187
	v_pk_add_f32 v[126:127], v[126:127], v[180:181]
	v_pk_add_f32 v[124:125], v[124:125], v[168:169]
	v_pk_add_f32 v[118:119], v[118:119], v[184:185]
	v_pk_add_f32 v[116:117], v[116:117], v[174:175]
	v_cndmask_b32_e32 v157, v154, v157, vcc
	v_pk_add_f32 v[122:123], v[122:123], v[182:183]
	v_pk_add_f32 v[120:121], v[120:121], v[172:173]
	v_pk_add_f32 v[180:181], v[114:115], v[186:187]
	v_pk_add_f32 v[182:183], v[112:113], v[176:177]
	v_mul_f32_e32 v114, v125, v125
	v_mul_f32_e32 v115, v127, v127
	v_cvt_pk_bf16_f32 v112, v124, v125
	v_cvt_pk_bf16_f32 v113, v126, v127
	v_mul_f32_e32 v125, v117, v117
	v_mul_f32_e32 v127, v119, v119
	v_lshlrev_b32_e32 v156, 2, v155
	v_lshlrev_b32_e32 v155, 2, v157
	v_mul_f32_e32 v157, v121, v121
	v_mul_f32_e32 v185, v183, v183
	v_fmac_f32_e32 v114, v124, v124
	v_fmac_f32_e32 v115, v126, v126
	v_fmac_f32_e32 v125, v116, v116
	v_fmac_f32_e32 v127, v118, v118
	v_mul_f32_e32 v184, v123, v123
	v_mul_f32_e32 v186, v181, v181
	v_fmac_f32_e32 v157, v120, v120
	v_fmac_f32_e32 v185, v182, v182
	v_add_f32_e32 v114, v114, v115
	v_add_f32_e32 v115, v125, v127
	v_fmac_f32_e32 v184, v122, v122
	v_fmac_f32_e32 v186, v180, v180
	v_add_f32_e32 v114, v157, v114
	v_add_f32_e32 v115, v185, v115
	v_add_f32_e32 v114, v184, v114
	v_add_f32_e32 v115, v186, v115
	v_add_f32_e32 v124, v114, v115
	ds_bpermute_b32 v125, v156, v124
	v_cvt_pk_bf16_f32 v114, v120, v121
	v_cvt_pk_bf16_f32 v115, v122, v123
	global_store_dwordx4 v[166:167], v[112:115], off
	s_waitcnt lgkmcnt(0)
	s_nop 0
	v_add_f32_e32 v112, v124, v125
	ds_bpermute_b32 v113, v155, v112
	v_cvt_pk_bf16_f32 v114, v116, v117
	v_cvt_pk_bf16_f32 v115, v118, v119
	v_cvt_pk_bf16_f32 v116, v182, v183
	v_cvt_pk_bf16_f32 v117, v180, v181
	global_store_dwordx4 v[166:167], v[114:117], off offset:256
	s_and_saveexec_b64 s[20:21], s[2:3]
	s_cbranch_execz .LBB0_1187
	v_lshl_add_u64 v[114:115], v[146:147], 2, s[8:9]
	s_waitcnt lgkmcnt(0)
	v_add_f32_e32 v112, v112, v113
	global_atomic_add_f32 v[114:115], v112, off

.LBB0_1271:
	ds_read_b128 v[144:147], v155
	ds_read_b128 v[148:151], v155 offset:1024
	ds_read_b128 v[160:163], v155 offset:2048
	ds_read_b128 v[164:167], v155 offset:3072
	s_add_u32 s30, s0, 0xfff80080
	s_addc_u32 s31, s1, -1
	s_cmp_eq_u32 s60, 28
	s_cselect_b32 s35, s23, s31
	s_cselect_b32 s34, s56, s30
	s_cselect_b32 s31, s21, s59
	s_cselect_b32 s30, s57, s58
	v_lshl_add_u64 v[168:169], s[0:1], 0, v[136:137]
	s_add_i32 m0, s29, 0xc000
	ds_read_b128 v[172:175], v156
	ds_read_b128 v[176:179], v156 offset:1024
	ds_read_b128 v[180:183], v156 offset:2048
	ds_read_b128 v[184:187], v156 offset:3072
	ds_read_b128 v[188:191], v156 offset:4096
	ds_read_b128 v[192:195], v156 offset:5120
	ds_read_b128 v[196:199], v156 offset:6144
	ds_read_b128 v[200:203], v156 offset:7168
	global_load_lds_dwordx4 v[168:169], off
	v_lshl_add_u64 v[168:169], s[0:1], 0, v[138:139]
	s_add_i32 m0, s29, 0xe000
	s_nop 0
	global_load_lds_dwordx4 v[168:169], off
	s_waitcnt vmcnt(10)
	s_waitcnt lgkmcnt(8)
	s_barrier
	s_waitcnt lgkmcnt(0)
	s_setprio 1
	s_waitcnt lgkmcnt(0)
	v_mfma_f32_16x16x32_bf16 v[124:127], v[144:147], v[172:175], v[124:127]
	v_mfma_f32_16x16x32_bf16 v[120:123], v[160:163], v[172:175], v[120:123]
	v_mfma_f32_16x16x32_bf16 v[108:111], v[144:147], v[180:183], v[108:111]
	v_mfma_f32_16x16x32_bf16 v[104:107], v[160:163], v[180:183], v[104:107]
	v_mfma_f32_16x16x32_bf16 v[92:95], v[144:147], v[188:191], v[92:95]
	v_mfma_f32_16x16x32_bf16 v[88:91], v[160:163], v[188:191], v[88:91]
	v_mfma_f32_16x16x32_bf16 v[76:79], v[144:147], v[196:199], v[76:79]
	v_mfma_f32_16x16x32_bf16 v[72:75], v[160:163], v[196:199], v[72:75]
	v_mfma_f32_16x16x32_bf16 v[124:127], v[148:151], v[176:179], v[124:127]
	v_mfma_f32_16x16x32_bf16 v[120:123], v[164:167], v[176:179], v[120:123]
	v_mfma_f32_16x16x32_bf16 v[108:111], v[148:151], v[184:187], v[108:111]
	v_mfma_f32_16x16x32_bf16 v[104:107], v[164:167], v[184:187], v[104:107]
	v_mfma_f32_16x16x32_bf16 v[92:95], v[148:151], v[192:195], v[92:95]
	v_mfma_f32_16x16x32_bf16 v[88:91], v[164:167], v[192:195], v[88:91]
	v_mfma_f32_16x16x32_bf16 v[76:79], v[148:151], v[200:203], v[76:79]
	v_mfma_f32_16x16x32_bf16 v[72:75], v[164:167], v[200:203], v[72:75]
	s_setprio 0
	s_barrier
	s_add_i32 s61, s48, s38
	v_lshl_add_u64 v[168:169], s[30:31], 0, v[130:131]
	s_mov_b32 m0, s61
	ds_read_b128 v[204:207], v157
	ds_read_b128 v[208:211], v157 offset:1024
	ds_read_b128 v[212:215], v157 offset:2048
	ds_read_b128 v[216:219], v157 offset:3072
	global_load_lds_dwordx4 v[168:169], off
	v_lshl_add_u64 v[220:221], s[30:31], 0, v[134:135]
	s_add_i32 m0, s61, 0x2000
	s_nop 0
	global_load_lds_dwordx4 v[220:221], off
	s_waitcnt vmcnt(10)
	s_barrier
	s_waitcnt lgkmcnt(0)
	s_setprio 1
	s_waitcnt lgkmcnt(0)
	v_mfma_f32_16x16x32_bf16 v[116:119], v[204:207], v[172:175], v[116:119]
	v_mfma_f32_16x16x32_bf16 v[112:115], v[212:215], v[172:175], v[112:115]
	v_mfma_f32_16x16x32_bf16 v[100:103], v[204:207], v[180:183], v[100:103]
	v_mfma_f32_16x16x32_bf16 v[96:99], v[212:215], v[180:183], v[96:99]
	v_mfma_f32_16x16x32_bf16 v[84:87], v[204:207], v[188:191], v[84:87]
	v_mfma_f32_16x16x32_bf16 v[80:83], v[212:215], v[188:191], v[80:83]
	v_mfma_f32_16x16x32_bf16 v[68:71], v[204:207], v[196:199], v[68:71]
	v_mfma_f32_16x16x32_bf16 v[64:67], v[212:215], v[196:199], v[64:67]
	v_mfma_f32_16x16x32_bf16 v[116:119], v[208:211], v[176:179], v[116:119]
	v_mfma_f32_16x16x32_bf16 v[112:115], v[216:219], v[176:179], v[112:115]
	v_mfma_f32_16x16x32_bf16 v[100:103], v[208:211], v[184:187], v[100:103]
	v_mfma_f32_16x16x32_bf16 v[96:99], v[216:219], v[184:187], v[96:99]
	v_mfma_f32_16x16x32_bf16 v[84:87], v[208:211], v[192:195], v[84:87]
	v_mfma_f32_16x16x32_bf16 v[80:83], v[216:219], v[192:195], v[80:83]
	v_mfma_f32_16x16x32_bf16 v[68:71], v[208:211], v[200:203], v[68:71]
	v_mfma_f32_16x16x32_bf16 v[64:67], v[216:219], v[200:203], v[64:67]
	s_setprio 0
	s_mov_b32 m0, s29
	v_lshl_add_u64 v[222:223], s[34:35], 0, v[128:129]
	s_barrier
	ds_read_b128 v[172:175], v156 offset:16384
	ds_read_b128 v[176:179], v156 offset:17408
	ds_read_b128 v[180:183], v156 offset:18432
	ds_read_b128 v[184:187], v156 offset:19456
	ds_read_b128 v[188:191], v156 offset:20480
	ds_read_b128 v[192:195], v156 offset:21504
	ds_read_b128 v[196:199], v156 offset:22528
	ds_read_b128 v[200:203], v156 offset:23552
	global_load_lds_dwordx4 v[222:223], off
	v_lshl_add_u64 v[224:225], s[34:35], 0, v[132:133]
	s_mov_b32 m0, s40
	s_nop 0
	global_load_lds_dwordx4 v[224:225], off
	s_barrier
	s_waitcnt lgkmcnt(0)
	s_setprio 1
	s_waitcnt lgkmcnt(0)
	v_mfma_f32_16x16x32_bf16 v[60:63], v[144:147], v[172:175], v[60:63]
	v_mfma_f32_16x16x32_bf16 v[56:59], v[160:163], v[172:175], v[56:59]
	v_mfma_f32_16x16x32_bf16 v[44:47], v[144:147], v[180:183], v[44:47]
	v_mfma_f32_16x16x32_bf16 v[40:43], v[160:163], v[180:183], v[40:43]
	v_mfma_f32_16x16x32_bf16 v[28:31], v[144:147], v[188:191], v[28:31]
	v_mfma_f32_16x16x32_bf16 v[24:27], v[160:163], v[188:191], v[24:27]
	v_mfma_f32_16x16x32_bf16 v[12:15], v[144:147], v[196:199], v[12:15]
	v_mfma_f32_16x16x32_bf16 v[8:11], v[160:163], v[196:199], v[8:11]
	v_mfma_f32_16x16x32_bf16 v[60:63], v[148:151], v[176:179], v[60:63]
	v_mfma_f32_16x16x32_bf16 v[56:59], v[164:167], v[176:179], v[56:59]
	v_mfma_f32_16x16x32_bf16 v[44:47], v[148:151], v[184:187], v[44:47]
	v_mfma_f32_16x16x32_bf16 v[40:43], v[164:167], v[184:187], v[40:43]
	v_mfma_f32_16x16x32_bf16 v[28:31], v[148:151], v[192:195], v[28:31]
	v_mfma_f32_16x16x32_bf16 v[24:27], v[164:167], v[192:195], v[24:27]
	v_mfma_f32_16x16x32_bf16 v[12:15], v[148:151], v[200:203], v[12:15]
	v_mfma_f32_16x16x32_bf16 v[8:11], v[164:167], v[200:203], v[8:11]
	s_setprio 0
	s_barrier
	s_add_u32 s62, s30, 0x80000
	s_addc_u32 s63, s31, 0
	s_add_i32 s61, s49, s38
	v_lshl_add_u64 v[144:145], s[62:63], 0, v[130:131]
	s_mov_b32 m0, s61
	s_nop 0
	global_load_lds_dwordx4 v[144:145], off
	v_lshl_add_u64 v[144:145], s[62:63], 0, v[134:135]
	s_add_i32 m0, s61, 0x2000
	s_nop 0
	global_load_lds_dwordx4 v[144:145], off
	s_waitcnt vmcnt(10)
	s_barrier
	s_setprio 1
	v_mfma_f32_16x16x32_bf16 v[52:55], v[204:207], v[172:175], v[52:55]
	v_mfma_f32_16x16x32_bf16 v[48:51], v[212:215], v[172:175], v[48:51]
	v_mfma_f32_16x16x32_bf16 v[36:39], v[204:207], v[180:183], v[36:39]
	v_mfma_f32_16x16x32_bf16 v[32:35], v[212:215], v[180:183], v[32:35]
	v_mfma_f32_16x16x32_bf16 v[20:23], v[204:207], v[188:191], v[20:23]
	v_mfma_f32_16x16x32_bf16 v[16:19], v[212:215], v[188:191], v[16:19]
	v_mfma_f32_16x16x32_bf16 v[4:7], v[204:207], v[196:199], v[4:7]
	v_mfma_f32_16x16x32_bf16 v[0:3], v[212:215], v[196:199], v[0:3]
	v_mfma_f32_16x16x32_bf16 v[52:55], v[208:211], v[176:179], v[52:55]
	v_mfma_f32_16x16x32_bf16 v[48:51], v[216:219], v[176:179], v[48:51]
	v_mfma_f32_16x16x32_bf16 v[36:39], v[208:211], v[184:187], v[36:39]
	v_mfma_f32_16x16x32_bf16 v[32:35], v[216:219], v[184:187], v[32:35]
	v_mfma_f32_16x16x32_bf16 v[20:23], v[208:211], v[192:195], v[20:23]
	v_mfma_f32_16x16x32_bf16 v[16:19], v[216:219], v[192:195], v[16:19]
	v_mfma_f32_16x16x32_bf16 v[4:7], v[208:211], v[200:203], v[4:7]
	v_mfma_f32_16x16x32_bf16 v[0:3], v[216:219], v[200:203], v[0:3]
	s_setprio 0
	s_add_i32 s61, 0, 0x18000
	v_add_u32_e32 v159, s61, v153
	s_barrier
	ds_read_b128 v[144:147], v159
	ds_read_b128 v[148:151], v159 offset:1024
	ds_read_b128 v[160:163], v159 offset:2048
	ds_read_b128 v[164:167], v159 offset:3072
	s_add_u32 s34, s34, 0x80000
	s_addc_u32 s35, s35, 0
	s_mov_b32 m0, s41
	v_lshl_add_u64 v[204:205], s[34:35], 0, v[128:129]
	ds_read_b128 v[172:175], v156 offset:32768
	ds_read_b128 v[176:179], v156 offset:33792
	ds_read_b128 v[180:183], v156 offset:34816
	ds_read_b128 v[184:187], v156 offset:35840
	ds_read_b128 v[188:191], v156 offset:36864
	ds_read_b128 v[192:195], v156 offset:37888
	ds_read_b128 v[196:199], v156 offset:38912
	ds_read_b128 v[200:203], v156 offset:39936
	global_load_lds_dwordx4 v[204:205], off
	v_lshl_add_u64 v[204:205], s[34:35], 0, v[132:133]
	s_mov_b32 m0, s42
	s_nop 0
	global_load_lds_dwordx4 v[204:205], off
	s_waitcnt vmcnt(10)
	s_waitcnt lgkmcnt(8)
	s_barrier
	s_waitcnt lgkmcnt(0)
	s_setprio 1
	s_waitcnt lgkmcnt(0)
	v_mfma_f32_16x16x32_bf16 v[124:127], v[144:147], v[172:175], v[124:127]
	v_mfma_f32_16x16x32_bf16 v[120:123], v[160:163], v[172:175], v[120:123]
	v_mfma_f32_16x16x32_bf16 v[108:111], v[144:147], v[180:183], v[108:111]
	v_mfma_f32_16x16x32_bf16 v[104:107], v[160:163], v[180:183], v[104:107]
	v_mfma_f32_16x16x32_bf16 v[92:95], v[144:147], v[188:191], v[92:95]
	v_mfma_f32_16x16x32_bf16 v[88:91], v[160:163], v[188:191], v[88:91]
	v_mfma_f32_16x16x32_bf16 v[76:79], v[144:147], v[196:199], v[76:79]
	v_mfma_f32_16x16x32_bf16 v[72:75], v[160:163], v[196:199], v[72:75]
	v_mfma_f32_16x16x32_bf16 v[124:127], v[148:151], v[176:179], v[124:127]
	v_mfma_f32_16x16x32_bf16 v[120:123], v[164:167], v[176:179], v[120:123]
	v_mfma_f32_16x16x32_bf16 v[108:111], v[148:151], v[184:187], v[108:111]
	v_mfma_f32_16x16x32_bf16 v[104:107], v[164:167], v[184:187], v[104:107]
	v_mfma_f32_16x16x32_bf16 v[92:95], v[148:151], v[192:195], v[92:95]
	v_mfma_f32_16x16x32_bf16 v[88:91], v[164:167], v[192:195], v[88:91]
	v_mfma_f32_16x16x32_bf16 v[76:79], v[148:151], v[200:203], v[76:79]
	v_mfma_f32_16x16x32_bf16 v[72:75], v[164:167], v[200:203], v[72:75]
	s_setprio 0
	s_barrier
	s_add_i32 s34, 0, 0x1c000
	s_add_i32 s35, s61, s38
	v_add_u32_e32 v159, s34, v153
	v_lshl_add_u64 v[168:169], v[168:169], 0, s[10:11]
	s_mov_b32 m0, s35
	ds_read_b128 v[204:207], v159
	ds_read_b128 v[208:211], v159 offset:1024
	ds_read_b128 v[212:215], v159 offset:2048
	ds_read_b128 v[216:219], v159 offset:3072
	global_load_lds_dwordx4 v[168:169], off
	v_lshl_add_u64 v[168:169], v[220:221], 0, s[10:11]
	s_add_i32 m0, s35, 0x2000
	s_nop 0
	global_load_lds_dwordx4 v[168:169], off
	s_waitcnt vmcnt(10)
	s_barrier
	s_waitcnt lgkmcnt(0)
	s_setprio 1
	s_waitcnt lgkmcnt(0)
	v_mfma_f32_16x16x32_bf16 v[116:119], v[204:207], v[172:175], v[116:119]
	v_mfma_f32_16x16x32_bf16 v[112:115], v[212:215], v[172:175], v[112:115]
	v_mfma_f32_16x16x32_bf16 v[100:103], v[204:207], v[180:183], v[100:103]
	v_mfma_f32_16x16x32_bf16 v[96:99], v[212:215], v[180:183], v[96:99]
	v_mfma_f32_16x16x32_bf16 v[84:87], v[204:207], v[188:191], v[84:87]
	v_mfma_f32_16x16x32_bf16 v[80:83], v[212:215], v[188:191], v[80:83]
	v_mfma_f32_16x16x32_bf16 v[68:71], v[204:207], v[196:199], v[68:71]
	v_mfma_f32_16x16x32_bf16 v[64:67], v[212:215], v[196:199], v[64:67]
	v_mfma_f32_16x16x32_bf16 v[116:119], v[208:211], v[176:179], v[116:119]
	v_mfma_f32_16x16x32_bf16 v[112:115], v[216:219], v[176:179], v[112:115]
	v_mfma_f32_16x16x32_bf16 v[100:103], v[208:211], v[184:187], v[100:103]
	v_mfma_f32_16x16x32_bf16 v[96:99], v[216:219], v[184:187], v[96:99]
	v_mfma_f32_16x16x32_bf16 v[84:87], v[208:211], v[192:195], v[84:87]
	v_mfma_f32_16x16x32_bf16 v[80:83], v[216:219], v[192:195], v[80:83]
	v_mfma_f32_16x16x32_bf16 v[68:71], v[208:211], v[200:203], v[68:71]
	v_mfma_f32_16x16x32_bf16 v[64:67], v[216:219], v[200:203], v[64:67]
	s_setprio 0
	s_mov_b32 m0, s45
	v_lshl_add_u64 v[168:169], v[222:223], 0, s[10:11]
	s_barrier
	ds_read_b128 v[172:175], v156 offset:49152
	ds_read_b128 v[176:179], v156 offset:50176
	ds_read_b128 v[180:183], v156 offset:51200
	ds_read_b128 v[184:187], v156 offset:52224
	ds_read_b128 v[188:191], v156 offset:53248
	ds_read_b128 v[192:195], v156 offset:54272
	ds_read_b128 v[196:199], v156 offset:55296
	ds_read_b128 v[200:203], v156 offset:56320
	global_load_lds_dwordx4 v[168:169], off
	v_lshl_add_u64 v[168:169], v[224:225], 0, s[10:11]
	s_mov_b32 m0, s46
	s_nop 0
	global_load_lds_dwordx4 v[168:169], off
	s_barrier
	s_waitcnt lgkmcnt(0)
	s_setprio 1
	s_waitcnt lgkmcnt(0)
	v_mfma_f32_16x16x32_bf16 v[60:63], v[144:147], v[172:175], v[60:63]
	v_mfma_f32_16x16x32_bf16 v[56:59], v[160:163], v[172:175], v[56:59]
	v_mfma_f32_16x16x32_bf16 v[44:47], v[144:147], v[180:183], v[44:47]
	v_mfma_f32_16x16x32_bf16 v[40:43], v[160:163], v[180:183], v[40:43]
	v_mfma_f32_16x16x32_bf16 v[28:31], v[144:147], v[188:191], v[28:31]
	v_mfma_f32_16x16x32_bf16 v[24:27], v[160:163], v[188:191], v[24:27]
	v_mfma_f32_16x16x32_bf16 v[12:15], v[144:147], v[196:199], v[12:15]
	v_mfma_f32_16x16x32_bf16 v[8:11], v[160:163], v[196:199], v[8:11]
	v_mfma_f32_16x16x32_bf16 v[60:63], v[148:151], v[176:179], v[60:63]
	v_mfma_f32_16x16x32_bf16 v[56:59], v[164:167], v[176:179], v[56:59]
	v_mfma_f32_16x16x32_bf16 v[44:47], v[148:151], v[184:187], v[44:47]
	v_mfma_f32_16x16x32_bf16 v[40:43], v[164:167], v[184:187], v[40:43]
	v_mfma_f32_16x16x32_bf16 v[28:31], v[148:151], v[192:195], v[28:31]
	v_mfma_f32_16x16x32_bf16 v[24:27], v[164:167], v[192:195], v[24:27]
	v_mfma_f32_16x16x32_bf16 v[12:15], v[148:151], v[200:203], v[12:15]
	v_mfma_f32_16x16x32_bf16 v[8:11], v[164:167], v[200:203], v[8:11]
	s_setprio 0
	s_barrier
	s_add_u32 s30, s30, 0x80080
	s_addc_u32 s31, s31, 0
	s_add_i32 s34, s34, s38
	v_lshl_add_u64 v[144:145], s[30:31], 0, v[130:131]
	s_mov_b32 m0, s34
	s_nop 0
	global_load_lds_dwordx4 v[144:145], off
	v_lshl_add_u64 v[144:145], s[30:31], 0, v[134:135]
	s_add_i32 m0, s34, 0x2000
	s_nop 0
	global_load_lds_dwordx4 v[144:145], off
	s_waitcnt vmcnt(10)
	s_barrier
	s_setprio 1
	v_mfma_f32_16x16x32_bf16 v[52:55], v[204:207], v[172:175], v[52:55]
	v_mfma_f32_16x16x32_bf16 v[48:51], v[212:215], v[172:175], v[48:51]
	v_mfma_f32_16x16x32_bf16 v[36:39], v[204:207], v[180:183], v[36:39]
	v_mfma_f32_16x16x32_bf16 v[32:35], v[212:215], v[180:183], v[32:35]
	v_mfma_f32_16x16x32_bf16 v[20:23], v[204:207], v[188:191], v[20:23]
	v_mfma_f32_16x16x32_bf16 v[16:19], v[212:215], v[188:191], v[16:19]
	v_mfma_f32_16x16x32_bf16 v[4:7], v[204:207], v[196:199], v[4:7]
	v_mfma_f32_16x16x32_bf16 v[0:3], v[212:215], v[196:199], v[0:3]
	v_mfma_f32_16x16x32_bf16 v[52:55], v[208:211], v[176:179], v[52:55]
	v_mfma_f32_16x16x32_bf16 v[48:51], v[216:219], v[176:179], v[48:51]
	v_mfma_f32_16x16x32_bf16 v[36:39], v[208:211], v[184:187], v[36:39]
	v_mfma_f32_16x16x32_bf16 v[32:35], v[216:219], v[184:187], v[32:35]
	v_mfma_f32_16x16x32_bf16 v[20:23], v[208:211], v[192:195], v[20:23]
	v_mfma_f32_16x16x32_bf16 v[16:19], v[216:219], v[192:195], v[16:19]
	v_mfma_f32_16x16x32_bf16 v[4:7], v[208:211], v[200:203], v[4:7]
	v_mfma_f32_16x16x32_bf16 v[0:3], v[216:219], v[200:203], v[0:3]
	s_setprio 0
	s_add_i32 s60, s60, 2
	s_add_u32 s0, s0, 0x100
	s_addc_u32 s1, s1, 0
	s_add_u32 s58, s58, 0x100
	s_addc_u32 s59, s59, 0
	s_cmp_gt_u32 s60, 29
	s_barrier
	s_cbranch_scc0 .LBB0_1271
	v_lshl_add_u32 v148, s28, 8, v152
	v_ashrrev_i32_e32 v149, 31, v148
	v_lshl_add_u64 v[146:147], v[148:149], 2, s[8:9]
	v_lshl_or_b32 v144, s55, 8, v154
	v_ashrrev_i32_e32 v145, 31, v144
	v_lshlrev_b64 v[150:151], 1, v[144:145]
	v_lshlrev_b64 v[162:163], 14, v[148:149]
	v_or_b32_e32 v160, 16, v148
	v_ashrrev_i32_e32 v161, 31, v160
	s_mov_b32 s55, s20
	s_mov_b32 s28, s22
	s_mov_b64 s[30:31], s[26:27]
	s_mov_b64 s[34:35], s[24:25]
	v_fmamk_f32 v144, v236, 0x3a000000, v158
	v_mul_f32_e32 v145, 0x4b800000, v144
	v_cmp_gt_f32_e32 vcc, s50, v144
	s_nop 1
	v_cndmask_b32_e32 v144, v144, v145, vcc
	v_rsq_f32_e32 v149, v144
	v_lshl_add_u64 v[144:145], s[68:69], 0, v[162:163]
	v_lshl_add_u64 v[144:145], v[144:145], 0, v[150:151]
	v_lshl_add_u64 v[162:163], v[160:161], 2, s[8:9]
	v_mul_f32_e32 v159, 0x45800000, v149
	v_cndmask_b32_e32 v164, v149, v159, vcc
	v_pk_mul_f32 v[126:127], v[126:127], v[164:165] op_sel_hi:[1,0]
	v_pk_mul_f32 v[124:125], v[124:125], v[164:165] op_sel_hi:[1,0]
	v_pk_mul_f32 v[122:123], v[122:123], v[164:165] op_sel_hi:[1,0]
	v_pk_mul_f32 v[120:121], v[120:121], v[164:165] op_sel_hi:[1,0]
	v_pk_mul_f32 v[118:119], v[118:119], v[164:165] op_sel_hi:[1,0]
	v_pk_mul_f32 v[116:117], v[116:117], v[164:165] op_sel_hi:[1,0]
	v_pk_mul_f32 v[114:115], v[114:115], v[164:165] op_sel_hi:[1,0]
	v_pk_mul_f32 v[112:113], v[112:113], v[164:165] op_sel_hi:[1,0]
	v_max_f32_e32 v124, 0, v124
	v_max_f32_e32 v120, 0, v120
	v_max_f32_e32 v125, 0, v125
	v_max_f32_e32 v121, 0, v121
	v_max_f32_e32 v126, 0, v126
	v_max_f32_e32 v122, 0, v122
	v_max_f32_e32 v127, 0, v127
	v_max_f32_e32 v123, 0, v123
	v_max_f32_e32 v116, 0, v116
	v_max_f32_e32 v112, 0, v112
	v_max_f32_e32 v117, 0, v117
	v_max_f32_e32 v113, 0, v113
	v_max_f32_e32 v118, 0, v118
	v_max_f32_e32 v114, 0, v114
	v_max_f32_e32 v119, 0, v119
	v_max_f32_e32 v115, 0, v115
	v_mul_f32_e32 v124, v124, v124
	v_mul_f32_e32 v120, v120, v120
	v_mul_f32_e32 v125, v125, v125
	v_mul_f32_e32 v121, v121, v121
	v_mul_f32_e32 v126, v126, v126
	v_mul_f32_e32 v122, v122, v122
	v_mul_f32_e32 v127, v127, v127
	v_mul_f32_e32 v123, v123, v123
	v_mul_f32_e32 v116, v116, v116
	v_mul_f32_e32 v149, v112, v112
	v_mul_f32_e32 v117, v117, v117
	v_mul_f32_e32 v159, v113, v113
	v_mul_f32_e32 v118, v118, v118
	v_mul_f32_e32 v164, v114, v114
	v_mul_f32_e32 v119, v119, v119
	v_mul_f32_e32 v165, v115, v115
	v_cvt_pk_bf16_f32 v112, v124, v125
	v_cvt_pk_bf16_f32 v113, v126, v127
	v_cvt_pk_bf16_f32 v114, v120, v121
	v_cvt_pk_bf16_f32 v115, v122, v123
	v_cvt_pk_bf16_f32 v116, v116, v117
	v_cvt_pk_bf16_f32 v117, v118, v119
	v_cvt_pk_bf16_f32 v118, v149, v159
	v_cvt_pk_bf16_f32 v119, v164, v165
	global_store_dwordx4 v[144:145], v[112:115], off
	global_store_dwordx4 v[144:145], v[116:119], off offset:256
	v_lshlrev_b64 v[114:115], 14, v[160:161]
	v_or_b32_e32 v112, 32, v148
	v_lshl_add_u64 v[114:115], s[68:69], 0, v[114:115]
	v_ashrrev_i32_e32 v113, 31, v112
	v_lshl_add_u64 v[114:115], v[114:115], 0, v[150:151]
	v_fmamk_f32 v116, v237, 0x3a000000, v158
	v_mul_f32_e32 v117, 0x4b800000, v116
	v_cmp_gt_f32_e32 vcc, s50, v116
	s_nop 1
	v_cndmask_b32_e32 v116, v116, v117, vcc
	v_rsq_f32_e32 v118, v116
	v_lshl_add_u64 v[116:117], v[112:113], 2, s[8:9]
	v_mul_f32_e32 v119, 0x45800000, v118
	v_cndmask_b32_e32 v118, v118, v119, vcc
	v_pk_mul_f32 v[110:111], v[110:111], v[118:119] op_sel_hi:[1,0]
	v_pk_mul_f32 v[108:109], v[108:109], v[118:119] op_sel_hi:[1,0]
	v_pk_mul_f32 v[106:107], v[106:107], v[118:119] op_sel_hi:[1,0]
	v_pk_mul_f32 v[104:105], v[104:105], v[118:119] op_sel_hi:[1,0]
	v_pk_mul_f32 v[102:103], v[102:103], v[118:119] op_sel_hi:[1,0]
	v_pk_mul_f32 v[100:101], v[100:101], v[118:119] op_sel_hi:[1,0]
	v_pk_mul_f32 v[98:99], v[98:99], v[118:119] op_sel_hi:[1,0]
	v_pk_mul_f32 v[96:97], v[96:97], v[118:119] op_sel_hi:[1,0]
	v_max_f32_e32 v108, 0, v108
	v_max_f32_e32 v104, 0, v104
	v_max_f32_e32 v109, 0, v109
	v_max_f32_e32 v105, 0, v105
	v_max_f32_e32 v110, 0, v110
	v_max_f32_e32 v106, 0, v106
	v_max_f32_e32 v111, 0, v111
	v_max_f32_e32 v107, 0, v107
	v_max_f32_e32 v100, 0, v100
	v_max_f32_e32 v96, 0, v96
	v_max_f32_e32 v101, 0, v101
	v_max_f32_e32 v97, 0, v97
	v_max_f32_e32 v102, 0, v102
	v_max_f32_e32 v98, 0, v98
	v_max_f32_e32 v103, 0, v103
	v_max_f32_e32 v99, 0, v99
	v_mul_f32_e32 v108, v108, v108
	v_mul_f32_e32 v104, v104, v104
	v_mul_f32_e32 v109, v109, v109
	v_mul_f32_e32 v105, v105, v105
	v_mul_f32_e32 v110, v110, v110
	v_mul_f32_e32 v106, v106, v106
	v_mul_f32_e32 v111, v111, v111
	v_mul_f32_e32 v107, v107, v107
	v_mul_f32_e32 v100, v100, v100
	v_mul_f32_e32 v118, v96, v96
	v_mul_f32_e32 v101, v101, v101
	v_mul_f32_e32 v119, v97, v97
	v_mul_f32_e32 v102, v102, v102
	v_mul_f32_e32 v120, v98, v98
	v_mul_f32_e32 v103, v103, v103
	v_mul_f32_e32 v121, v99, v99
	v_cvt_pk_bf16_f32 v96, v108, v109
	v_cvt_pk_bf16_f32 v97, v110, v111
	v_cvt_pk_bf16_f32 v98, v104, v105
	v_cvt_pk_bf16_f32 v99, v106, v107
	v_cvt_pk_bf16_f32 v100, v100, v101
	v_cvt_pk_bf16_f32 v101, v102, v103
	v_cvt_pk_bf16_f32 v102, v118, v119
	v_cvt_pk_bf16_f32 v103, v120, v121
	global_store_dwordx4 v[114:115], v[96:99], off
	global_store_dwordx4 v[114:115], v[100:103], off offset:256
	v_lshlrev_b64 v[98:99], 14, v[112:113]
	v_or_b32_e32 v96, 48, v148
	v_lshl_add_u64 v[98:99], s[68:69], 0, v[98:99]
	v_ashrrev_i32_e32 v97, 31, v96
	v_lshl_add_u64 v[98:99], v[98:99], 0, v[150:151]
	v_fmamk_f32 v100, v238, 0x3a000000, v158
	v_mul_f32_e32 v101, 0x4b800000, v100
	v_cmp_gt_f32_e32 vcc, s50, v100
	s_nop 1
	v_cndmask_b32_e32 v100, v100, v101, vcc
	v_rsq_f32_e32 v102, v100
	v_lshl_add_u64 v[100:101], v[96:97], 2, s[8:9]
	v_mul_f32_e32 v103, 0x45800000, v102
	v_cndmask_b32_e32 v102, v102, v103, vcc
	v_pk_mul_f32 v[94:95], v[94:95], v[102:103] op_sel_hi:[1,0]
	v_pk_mul_f32 v[92:93], v[92:93], v[102:103] op_sel_hi:[1,0]
	v_pk_mul_f32 v[90:91], v[90:91], v[102:103] op_sel_hi:[1,0]
	v_pk_mul_f32 v[88:89], v[88:89], v[102:103] op_sel_hi:[1,0]
	v_pk_mul_f32 v[86:87], v[86:87], v[102:103] op_sel_hi:[1,0]
	v_pk_mul_f32 v[84:85], v[84:85], v[102:103] op_sel_hi:[1,0]
	v_pk_mul_f32 v[82:83], v[82:83], v[102:103] op_sel_hi:[1,0]
	v_pk_mul_f32 v[80:81], v[80:81], v[102:103] op_sel_hi:[1,0]
	v_max_f32_e32 v92, 0, v92
	v_max_f32_e32 v88, 0, v88
	v_max_f32_e32 v93, 0, v93
	v_max_f32_e32 v89, 0, v89
	v_max_f32_e32 v94, 0, v94
	v_max_f32_e32 v90, 0, v90
	v_max_f32_e32 v95, 0, v95
	v_max_f32_e32 v91, 0, v91
	v_max_f32_e32 v84, 0, v84
	v_max_f32_e32 v80, 0, v80
	v_max_f32_e32 v85, 0, v85
	v_max_f32_e32 v81, 0, v81
	v_max_f32_e32 v86, 0, v86
	v_max_f32_e32 v82, 0, v82
	v_max_f32_e32 v87, 0, v87
	v_max_f32_e32 v83, 0, v83
	v_mul_f32_e32 v92, v92, v92
	v_mul_f32_e32 v88, v88, v88
	v_mul_f32_e32 v93, v93, v93
	v_mul_f32_e32 v89, v89, v89
	v_mul_f32_e32 v94, v94, v94
	v_mul_f32_e32 v90, v90, v90
	v_mul_f32_e32 v95, v95, v95
	v_mul_f32_e32 v91, v91, v91
	v_mul_f32_e32 v84, v84, v84
	v_mul_f32_e32 v102, v80, v80
	v_mul_f32_e32 v85, v85, v85
	v_mul_f32_e32 v103, v81, v81
	v_mul_f32_e32 v86, v86, v86
	v_mul_f32_e32 v104, v82, v82
	v_mul_f32_e32 v87, v87, v87
	v_mul_f32_e32 v105, v83, v83
	v_cvt_pk_bf16_f32 v80, v92, v93
	v_cvt_pk_bf16_f32 v81, v94, v95
	v_cvt_pk_bf16_f32 v82, v88, v89
	v_cvt_pk_bf16_f32 v83, v90, v91
	v_cvt_pk_bf16_f32 v84, v84, v85
	v_cvt_pk_bf16_f32 v85, v86, v87
	v_cvt_pk_bf16_f32 v86, v102, v103
	v_cvt_pk_bf16_f32 v87, v104, v105
	global_store_dwordx4 v[98:99], v[80:83], off
	global_store_dwordx4 v[98:99], v[84:87], off offset:256
	v_fmamk_f32 v80, v239, 0x3a000000, v158
	v_mul_f32_e32 v81, 0x4b800000, v80
	v_cmp_gt_f32_e32 vcc, s50, v80
	s_nop 1
	v_cndmask_b32_e32 v80, v80, v81, vcc
	v_rsq_f32_e32 v82, v80
	v_lshlrev_b64 v[80:81], 14, v[96:97]
	v_lshl_add_u64 v[80:81], s[68:69], 0, v[80:81]
	v_lshl_add_u64 v[80:81], v[80:81], 0, v[150:151]
	v_mul_f32_e32 v83, 0x45800000, v82
	v_cndmask_b32_e32 v82, v82, v83, vcc
	v_pk_mul_f32 v[78:79], v[78:79], v[82:83] op_sel_hi:[1,0]
	v_pk_mul_f32 v[76:77], v[76:77], v[82:83] op_sel_hi:[1,0]
	v_pk_mul_f32 v[74:75], v[74:75], v[82:83] op_sel_hi:[1,0]
	v_pk_mul_f32 v[72:73], v[72:73], v[82:83] op_sel_hi:[1,0]
	v_pk_mul_f32 v[70:71], v[70:71], v[82:83] op_sel_hi:[1,0]
	v_pk_mul_f32 v[68:69], v[68:69], v[82:83] op_sel_hi:[1,0]
	v_pk_mul_f32 v[66:67], v[66:67], v[82:83] op_sel_hi:[1,0]
	v_pk_mul_f32 v[64:65], v[64:65], v[82:83] op_sel_hi:[1,0]
	v_max_f32_e32 v76, 0, v76
	v_max_f32_e32 v72, 0, v72
	v_max_f32_e32 v77, 0, v77
	v_max_f32_e32 v73, 0, v73
	v_max_f32_e32 v78, 0, v78
	v_max_f32_e32 v74, 0, v74
	v_max_f32_e32 v79, 0, v79
	v_max_f32_e32 v75, 0, v75
	v_max_f32_e32 v68, 0, v68
	v_max_f32_e32 v64, 0, v64
	v_max_f32_e32 v69, 0, v69
	v_max_f32_e32 v65, 0, v65
	v_max_f32_e32 v70, 0, v70
	v_max_f32_e32 v66, 0, v66
	v_max_f32_e32 v71, 0, v71
	v_max_f32_e32 v67, 0, v67
	v_mul_f32_e32 v76, v76, v76
	v_mul_f32_e32 v72, v72, v72
	v_mul_f32_e32 v77, v77, v77
	v_mul_f32_e32 v73, v73, v73
	v_mul_f32_e32 v78, v78, v78
	v_mul_f32_e32 v74, v74, v74
	v_mul_f32_e32 v79, v79, v79
	v_mul_f32_e32 v75, v75, v75
	v_mul_f32_e32 v68, v68, v68
	v_mul_f32_e32 v82, v64, v64
	v_mul_f32_e32 v69, v69, v69
	v_mul_f32_e32 v83, v65, v65
	v_mul_f32_e32 v70, v70, v70
	v_mul_f32_e32 v84, v66, v66
	v_mul_f32_e32 v71, v71, v71
	v_mul_f32_e32 v85, v67, v67
	v_cvt_pk_bf16_f32 v64, v76, v77
	v_cvt_pk_bf16_f32 v65, v78, v79
	v_cvt_pk_bf16_f32 v66, v72, v73
	v_cvt_pk_bf16_f32 v67, v74, v75
	v_cvt_pk_bf16_f32 v68, v68, v69
	v_cvt_pk_bf16_f32 v69, v70, v71
	v_cvt_pk_bf16_f32 v70, v82, v83
	v_cvt_pk_bf16_f32 v71, v84, v85
	global_store_dwordx4 v[80:81], v[64:67], off
	global_store_dwordx4 v[80:81], v[68:71], off offset:256
	v_lshl_add_u64 v[64:65], v[144:145], 0, s[12:13]
	v_fmamk_f32 v66, v240, 0x3a000000, v158
	v_mul_f32_e32 v67, 0x4b800000, v66
	v_cmp_gt_f32_e32 vcc, s50, v66
	s_nop 1
	v_cndmask_b32_e32 v66, v66, v67, vcc
	v_rsq_f32_e32 v68, v66
	v_add_co_u32_e64 v66, s[0:1], s51, v144
	v_mul_f32_e32 v69, 0x45800000, v68
	v_cndmask_b32_e32 v68, v68, v69, vcc
	v_pk_mul_f32 v[62:63], v[62:63], v[68:69] op_sel_hi:[1,0]
	v_pk_mul_f32 v[60:61], v[60:61], v[68:69] op_sel_hi:[1,0]
	v_pk_mul_f32 v[58:59], v[58:59], v[68:69] op_sel_hi:[1,0]
	v_pk_mul_f32 v[56:57], v[56:57], v[68:69] op_sel_hi:[1,0]
	v_pk_mul_f32 v[54:55], v[54:55], v[68:69] op_sel_hi:[1,0]
	v_pk_mul_f32 v[52:53], v[52:53], v[68:69] op_sel_hi:[1,0]
	v_pk_mul_f32 v[50:51], v[50:51], v[68:69] op_sel_hi:[1,0]
	v_pk_mul_f32 v[48:49], v[48:49], v[68:69] op_sel_hi:[1,0]
	v_max_f32_e32 v60, 0, v60
	v_max_f32_e32 v56, 0, v56
	v_max_f32_e32 v61, 0, v61
	v_max_f32_e32 v57, 0, v57
	v_max_f32_e32 v62, 0, v62
	v_max_f32_e32 v58, 0, v58
	v_max_f32_e32 v63, 0, v63
	v_max_f32_e32 v59, 0, v59
	v_max_f32_e32 v52, 0, v52
	v_max_f32_e32 v48, 0, v48
	v_max_f32_e32 v53, 0, v53
	v_max_f32_e32 v49, 0, v49
	v_max_f32_e32 v54, 0, v54
	v_max_f32_e32 v50, 0, v50
	v_max_f32_e32 v55, 0, v55
	v_max_f32_e32 v51, 0, v51
	v_mul_f32_e32 v60, v60, v60
	v_mul_f32_e32 v56, v56, v56
	v_mul_f32_e32 v61, v61, v61
	v_mul_f32_e32 v57, v57, v57
	v_mul_f32_e32 v62, v62, v62
	v_mul_f32_e32 v58, v58, v58
	v_mul_f32_e32 v63, v63, v63
	v_mul_f32_e32 v59, v59, v59
	v_addc_co_u32_e64 v67, s[0:1], 0, v145, s[0:1]
	v_mul_f32_e32 v52, v52, v52
	v_mul_f32_e32 v68, v48, v48
	v_mul_f32_e32 v53, v53, v53
	v_mul_f32_e32 v69, v49, v49
	v_mul_f32_e32 v54, v54, v54
	v_mul_f32_e32 v70, v50, v50
	v_mul_f32_e32 v55, v55, v55
	v_mul_f32_e32 v71, v51, v51
	v_cvt_pk_bf16_f32 v48, v60, v61
	v_cvt_pk_bf16_f32 v49, v62, v63
	v_cvt_pk_bf16_f32 v50, v56, v57
	v_cvt_pk_bf16_f32 v51, v58, v59
	v_cvt_pk_bf16_f32 v52, v52, v53
	v_cvt_pk_bf16_f32 v53, v54, v55
	v_cvt_pk_bf16_f32 v54, v68, v69
	v_cvt_pk_bf16_f32 v55, v70, v71
	global_store_dwordx4 v[66:67], v[48:51], off
	global_store_dwordx4 v[64:65], v[52:55], off offset:256
	v_lshl_add_u64 v[48:49], v[144:145], 0, s[14:15]
	v_fmamk_f32 v50, v241, 0x3a000000, v158
	v_mul_f32_e32 v51, 0x4b800000, v50
	v_cmp_gt_f32_e32 vcc, s50, v50
	s_nop 1
	v_cndmask_b32_e32 v50, v50, v51, vcc
	v_rsq_f32_e32 v52, v50
	v_add_co_u32_e64 v50, s[0:1], s52, v144
	v_mul_f32_e32 v53, 0x45800000, v52
	v_cndmask_b32_e32 v52, v52, v53, vcc
	v_pk_mul_f32 v[46:47], v[46:47], v[52:53] op_sel_hi:[1,0]
	v_pk_mul_f32 v[44:45], v[44:45], v[52:53] op_sel_hi:[1,0]
	v_pk_mul_f32 v[42:43], v[42:43], v[52:53] op_sel_hi:[1,0]
	v_pk_mul_f32 v[40:41], v[40:41], v[52:53] op_sel_hi:[1,0]
	v_pk_mul_f32 v[38:39], v[38:39], v[52:53] op_sel_hi:[1,0]
	v_pk_mul_f32 v[36:37], v[36:37], v[52:53] op_sel_hi:[1,0]
	v_pk_mul_f32 v[34:35], v[34:35], v[52:53] op_sel_hi:[1,0]
	v_pk_mul_f32 v[32:33], v[32:33], v[52:53] op_sel_hi:[1,0]
	v_max_f32_e32 v44, 0, v44
	v_max_f32_e32 v40, 0, v40
	v_max_f32_e32 v45, 0, v45
	v_max_f32_e32 v41, 0, v41
	v_max_f32_e32 v46, 0, v46
	v_max_f32_e32 v42, 0, v42
	v_max_f32_e32 v47, 0, v47
	v_max_f32_e32 v43, 0, v43
	v_max_f32_e32 v36, 0, v36
	v_max_f32_e32 v32, 0, v32
	v_max_f32_e32 v37, 0, v37
	v_max_f32_e32 v33, 0, v33
	v_max_f32_e32 v38, 0, v38
	v_max_f32_e32 v34, 0, v34
	v_max_f32_e32 v39, 0, v39
	v_max_f32_e32 v35, 0, v35
	v_mul_f32_e32 v44, v44, v44
	v_mul_f32_e32 v40, v40, v40
	v_mul_f32_e32 v45, v45, v45
	v_mul_f32_e32 v41, v41, v41
	v_mul_f32_e32 v46, v46, v46
	v_mul_f32_e32 v42, v42, v42
	v_mul_f32_e32 v47, v47, v47
	v_mul_f32_e32 v43, v43, v43
	v_addc_co_u32_e64 v51, s[0:1], 0, v145, s[0:1]
	v_mul_f32_e32 v36, v36, v36
	v_mul_f32_e32 v52, v32, v32
	v_mul_f32_e32 v37, v37, v37
	v_mul_f32_e32 v53, v33, v33
	v_mul_f32_e32 v38, v38, v38
	v_mul_f32_e32 v54, v34, v34
	v_mul_f32_e32 v39, v39, v39
	v_mul_f32_e32 v55, v35, v35
	v_cvt_pk_bf16_f32 v32, v44, v45
	v_cvt_pk_bf16_f32 v33, v46, v47
	v_cvt_pk_bf16_f32 v34, v40, v41
	v_cvt_pk_bf16_f32 v35, v42, v43
	v_cvt_pk_bf16_f32 v36, v36, v37
	v_cvt_pk_bf16_f32 v37, v38, v39
	v_cvt_pk_bf16_f32 v38, v52, v53
	v_cvt_pk_bf16_f32 v39, v54, v55
	global_store_dwordx4 v[50:51], v[32:35], off
	global_store_dwordx4 v[48:49], v[36:39], off offset:256
	v_lshl_add_u64 v[32:33], v[144:145], 0, s[16:17]
	v_fmamk_f32 v34, v242, 0x3a000000, v158
	v_mul_f32_e32 v35, 0x4b800000, v34
	v_cmp_gt_f32_e32 vcc, s50, v34
	s_nop 1
	v_cndmask_b32_e32 v34, v34, v35, vcc
	v_rsq_f32_e32 v36, v34
	v_add_co_u32_e64 v34, s[0:1], s53, v144
	v_mul_f32_e32 v37, 0x45800000, v36
	v_cndmask_b32_e32 v36, v36, v37, vcc
	v_pk_mul_f32 v[30:31], v[30:31], v[36:37] op_sel_hi:[1,0]
	v_pk_mul_f32 v[28:29], v[28:29], v[36:37] op_sel_hi:[1,0]
	v_pk_mul_f32 v[26:27], v[26:27], v[36:37] op_sel_hi:[1,0]
	v_pk_mul_f32 v[24:25], v[24:25], v[36:37] op_sel_hi:[1,0]
	v_pk_mul_f32 v[22:23], v[22:23], v[36:37] op_sel_hi:[1,0]
	v_pk_mul_f32 v[20:21], v[20:21], v[36:37] op_sel_hi:[1,0]
	v_pk_mul_f32 v[18:19], v[18:19], v[36:37] op_sel_hi:[1,0]
	v_pk_mul_f32 v[16:17], v[16:17], v[36:37] op_sel_hi:[1,0]
	v_max_f32_e32 v28, 0, v28
	v_max_f32_e32 v24, 0, v24
	v_max_f32_e32 v29, 0, v29
	v_max_f32_e32 v25, 0, v25
	v_max_f32_e32 v30, 0, v30
	v_max_f32_e32 v26, 0, v26
	v_max_f32_e32 v31, 0, v31
	v_max_f32_e32 v27, 0, v27
	v_max_f32_e32 v20, 0, v20
	v_max_f32_e32 v16, 0, v16
	v_max_f32_e32 v21, 0, v21
	v_max_f32_e32 v17, 0, v17
	v_max_f32_e32 v22, 0, v22
	v_max_f32_e32 v18, 0, v18
	v_max_f32_e32 v23, 0, v23
	v_max_f32_e32 v19, 0, v19
	v_mul_f32_e32 v28, v28, v28
	v_mul_f32_e32 v24, v24, v24
	v_mul_f32_e32 v29, v29, v29
	v_mul_f32_e32 v25, v25, v25
	v_mul_f32_e32 v30, v30, v30
	v_mul_f32_e32 v26, v26, v26
	v_mul_f32_e32 v31, v31, v31
	v_mul_f32_e32 v27, v27, v27
	v_addc_co_u32_e64 v35, s[0:1], 0, v145, s[0:1]
	v_mul_f32_e32 v20, v20, v20
	v_mul_f32_e32 v36, v16, v16
	v_mul_f32_e32 v21, v21, v21
	v_mul_f32_e32 v37, v17, v17
	v_mul_f32_e32 v22, v22, v22
	v_mul_f32_e32 v38, v18, v18
	v_mul_f32_e32 v23, v23, v23
	v_mul_f32_e32 v39, v19, v19
	v_cvt_pk_bf16_f32 v16, v28, v29
	v_cvt_pk_bf16_f32 v17, v30, v31
	v_cvt_pk_bf16_f32 v18, v24, v25
	v_cvt_pk_bf16_f32 v19, v26, v27
	v_cvt_pk_bf16_f32 v20, v20, v21
	v_cvt_pk_bf16_f32 v21, v22, v23
	v_cvt_pk_bf16_f32 v22, v36, v37
	v_cvt_pk_bf16_f32 v23, v38, v39
	global_store_dwordx4 v[34:35], v[16:19], off
	global_store_dwordx4 v[32:33], v[20:23], off offset:256
	s_and_b64 vcc, exec, s[2:3]
	v_lshl_add_u64 v[16:17], v[144:145], 0, s[18:19]
	v_fmamk_f32 v18, v243, 0x3a000000, v158
	v_mul_f32_e32 v19, 0x4b800000, v18
	v_cmp_gt_f32_e64 s[0:1], s50, v18
	s_nop 1
	v_cndmask_b32_e64 v18, v18, v19, s[0:1]
	v_rsq_f32_e32 v20, v18
	v_add_co_u32_e64 v18, s[2:3], s54, v144
	v_mul_f32_e32 v21, 0x45800000, v20
	v_cndmask_b32_e64 v20, v20, v21, s[0:1]
	v_pk_mul_f32 v[14:15], v[14:15], v[20:21] op_sel_hi:[1,0]
	v_pk_mul_f32 v[12:13], v[12:13], v[20:21] op_sel_hi:[1,0]
	v_pk_mul_f32 v[10:11], v[10:11], v[20:21] op_sel_hi:[1,0]
	v_pk_mul_f32 v[8:9], v[8:9], v[20:21] op_sel_hi:[1,0]
	v_pk_mul_f32 v[6:7], v[6:7], v[20:21] op_sel_hi:[1,0]
	v_pk_mul_f32 v[4:5], v[4:5], v[20:21] op_sel_hi:[1,0]
	v_pk_mul_f32 v[2:3], v[2:3], v[20:21] op_sel_hi:[1,0]
	v_pk_mul_f32 v[0:1], v[0:1], v[20:21] op_sel_hi:[1,0]
	v_max_f32_e32 v12, 0, v12
	v_max_f32_e32 v8, 0, v8
	v_max_f32_e32 v13, 0, v13
	v_max_f32_e32 v9, 0, v9
	v_max_f32_e32 v14, 0, v14
	v_max_f32_e32 v10, 0, v10
	v_max_f32_e32 v15, 0, v15
	v_max_f32_e32 v11, 0, v11
	v_max_f32_e32 v4, 0, v4
	v_max_f32_e32 v0, 0, v0
	v_max_f32_e32 v5, 0, v5
	v_max_f32_e32 v1, 0, v1
	v_max_f32_e32 v6, 0, v6
	v_max_f32_e32 v2, 0, v2
	v_max_f32_e32 v7, 0, v7
	v_max_f32_e32 v3, 0, v3
	v_mul_f32_e32 v12, v12, v12
	v_mul_f32_e32 v8, v8, v8
	v_mul_f32_e32 v13, v13, v13
	v_mul_f32_e32 v9, v9, v9
	v_mul_f32_e32 v14, v14, v14
	v_mul_f32_e32 v10, v10, v10
	v_mul_f32_e32 v15, v15, v15
	v_mul_f32_e32 v11, v11, v11
	v_addc_co_u32_e64 v19, s[2:3], 0, v145, s[2:3]
	v_mul_f32_e32 v4, v4, v4
	v_mul_f32_e32 v20, v0, v0
	v_mul_f32_e32 v5, v5, v5
	v_mul_f32_e32 v21, v1, v1
	v_mul_f32_e32 v6, v6, v6
	v_mul_f32_e32 v22, v2, v2
	v_mul_f32_e32 v7, v7, v7
	v_mul_f32_e32 v23, v3, v3
	v_cvt_pk_bf16_f32 v0, v12, v13
	v_cvt_pk_bf16_f32 v1, v14, v15
	v_cvt_pk_bf16_f32 v2, v8, v9
	v_cvt_pk_bf16_f32 v3, v10, v11
	v_cvt_pk_bf16_f32 v4, v4, v5
	v_cvt_pk_bf16_f32 v5, v6, v7
	v_cvt_pk_bf16_f32 v6, v20, v21
	v_cvt_pk_bf16_f32 v7, v22, v23
	global_store_dwordx4 v[18:19], v[0:3], off
	global_store_dwordx4 v[16:17], v[4:7], off offset:256
	s_cbranch_vccz .LBB0_1264
	s_waitcnt vmcnt(0)
	s_cmpk_gt_u32 s33, 0xff
	s_cbranch_scc1 .LBB0_1275
	s_barrier

.LBB0_1350:
	ds_read_b128 v[144:147], v151
	ds_read_b128 v[156:159], v151 offset:1024
	ds_read_b128 v[160:163], v151 offset:2048
	ds_read_b128 v[164:167], v151 offset:3072
	s_add_u32 s26, s24, 0xffe00080
	s_addc_u32 s27, s25, -1
	s_cmpk_eq_i32 s49, 0x7c
	s_cselect_b32 s29, s15, s27
	s_cselect_b32 s28, s21, s26
	s_cselect_b32 s27, s13, s48
	s_cselect_b32 s26, s46, s47
	v_lshl_add_u64 v[168:169], s[24:25], 0, v[136:137]
	s_add_i32 m0, s23, 0xc000
	ds_read_b128 v[172:175], v152
	ds_read_b128 v[176:179], v152 offset:1024
	ds_read_b128 v[180:183], v152 offset:2048
	ds_read_b128 v[184:187], v152 offset:3072
	ds_read_b128 v[188:191], v152 offset:4096
	ds_read_b128 v[192:195], v152 offset:5120
	ds_read_b128 v[196:199], v152 offset:6144
	ds_read_b128 v[200:203], v152 offset:7168
	global_load_lds_dwordx4 v[168:169], off
	v_lshl_add_u64 v[168:169], s[24:25], 0, v[138:139]
	s_add_i32 m0, s23, 0xe000
	s_nop 0
	global_load_lds_dwordx4 v[168:169], off
	s_waitcnt vmcnt(10)
	s_waitcnt lgkmcnt(8)
	s_barrier
	s_waitcnt lgkmcnt(0)
	s_setprio 1
	s_waitcnt lgkmcnt(0)
	v_mfma_f32_16x16x32_bf16 v[124:127], v[144:147], v[172:175], v[124:127]
	v_mfma_f32_16x16x32_bf16 v[120:123], v[160:163], v[172:175], v[120:123]
	v_mfma_f32_16x16x32_bf16 v[108:111], v[144:147], v[180:183], v[108:111]
	v_mfma_f32_16x16x32_bf16 v[104:107], v[160:163], v[180:183], v[104:107]
	v_mfma_f32_16x16x32_bf16 v[92:95], v[144:147], v[188:191], v[92:95]
	v_mfma_f32_16x16x32_bf16 v[88:91], v[160:163], v[188:191], v[88:91]
	v_mfma_f32_16x16x32_bf16 v[76:79], v[144:147], v[196:199], v[76:79]
	v_mfma_f32_16x16x32_bf16 v[72:75], v[160:163], v[196:199], v[72:75]
	v_mfma_f32_16x16x32_bf16 v[124:127], v[156:159], v[176:179], v[124:127]
	v_mfma_f32_16x16x32_bf16 v[120:123], v[164:167], v[176:179], v[120:123]
	v_mfma_f32_16x16x32_bf16 v[108:111], v[156:159], v[184:187], v[108:111]
	v_mfma_f32_16x16x32_bf16 v[104:107], v[164:167], v[184:187], v[104:107]
	v_mfma_f32_16x16x32_bf16 v[92:95], v[156:159], v[192:195], v[92:95]
	v_mfma_f32_16x16x32_bf16 v[88:91], v[164:167], v[192:195], v[88:91]
	v_mfma_f32_16x16x32_bf16 v[76:79], v[156:159], v[200:203], v[76:79]
	v_mfma_f32_16x16x32_bf16 v[72:75], v[164:167], v[200:203], v[72:75]
	s_setprio 0
	s_barrier
	s_add_i32 s50, s44, s34
	v_lshl_add_u64 v[168:169], s[26:27], 0, v[130:131]
	s_mov_b32 m0, s50
	ds_read_b128 v[204:207], v153
	ds_read_b128 v[208:211], v153 offset:1024
	ds_read_b128 v[212:215], v153 offset:2048
	ds_read_b128 v[216:219], v153 offset:3072
	global_load_lds_dwordx4 v[168:169], off
	v_lshl_add_u64 v[220:221], s[26:27], 0, v[134:135]
	s_add_i32 m0, s50, 0x2000
	s_nop 0
	global_load_lds_dwordx4 v[220:221], off
	s_waitcnt vmcnt(10)
	s_barrier
	s_waitcnt lgkmcnt(0)
	s_setprio 1
	s_waitcnt lgkmcnt(0)
	v_mfma_f32_16x16x32_bf16 v[116:119], v[204:207], v[172:175], v[116:119]
	v_mfma_f32_16x16x32_bf16 v[112:115], v[212:215], v[172:175], v[112:115]
	v_mfma_f32_16x16x32_bf16 v[100:103], v[204:207], v[180:183], v[100:103]
	v_mfma_f32_16x16x32_bf16 v[96:99], v[212:215], v[180:183], v[96:99]
	v_mfma_f32_16x16x32_bf16 v[84:87], v[204:207], v[188:191], v[84:87]
	v_mfma_f32_16x16x32_bf16 v[80:83], v[212:215], v[188:191], v[80:83]
	v_mfma_f32_16x16x32_bf16 v[68:71], v[204:207], v[196:199], v[68:71]
	v_mfma_f32_16x16x32_bf16 v[64:67], v[212:215], v[196:199], v[64:67]
	v_mfma_f32_16x16x32_bf16 v[116:119], v[208:211], v[176:179], v[116:119]
	v_mfma_f32_16x16x32_bf16 v[112:115], v[216:219], v[176:179], v[112:115]
	v_mfma_f32_16x16x32_bf16 v[100:103], v[208:211], v[184:187], v[100:103]
	v_mfma_f32_16x16x32_bf16 v[96:99], v[216:219], v[184:187], v[96:99]
	v_mfma_f32_16x16x32_bf16 v[84:87], v[208:211], v[192:195], v[84:87]
	v_mfma_f32_16x16x32_bf16 v[80:83], v[216:219], v[192:195], v[80:83]
	v_mfma_f32_16x16x32_bf16 v[68:71], v[208:211], v[200:203], v[68:71]
	v_mfma_f32_16x16x32_bf16 v[64:67], v[216:219], v[200:203], v[64:67]
	s_setprio 0
	s_mov_b32 m0, s23
	v_lshl_add_u64 v[222:223], s[28:29], 0, v[128:129]
	s_barrier
	ds_read_b128 v[172:175], v152 offset:16384
	ds_read_b128 v[176:179], v152 offset:17408
	ds_read_b128 v[180:183], v152 offset:18432
	ds_read_b128 v[184:187], v152 offset:19456
	ds_read_b128 v[188:191], v152 offset:20480
	ds_read_b128 v[192:195], v152 offset:21504
	ds_read_b128 v[196:199], v152 offset:22528
	ds_read_b128 v[200:203], v152 offset:23552
	global_load_lds_dwordx4 v[222:223], off
	v_lshl_add_u64 v[224:225], s[28:29], 0, v[132:133]
	s_mov_b32 m0, s35
	s_nop 0
	global_load_lds_dwordx4 v[224:225], off
	s_barrier
	s_waitcnt lgkmcnt(0)
	s_setprio 1
	s_waitcnt lgkmcnt(0)
	v_mfma_f32_16x16x32_bf16 v[60:63], v[144:147], v[172:175], v[60:63]
	v_mfma_f32_16x16x32_bf16 v[56:59], v[160:163], v[172:175], v[56:59]
	v_mfma_f32_16x16x32_bf16 v[44:47], v[144:147], v[180:183], v[44:47]
	v_mfma_f32_16x16x32_bf16 v[40:43], v[160:163], v[180:183], v[40:43]
	v_mfma_f32_16x16x32_bf16 v[28:31], v[144:147], v[188:191], v[28:31]
	v_mfma_f32_16x16x32_bf16 v[24:27], v[160:163], v[188:191], v[24:27]
	v_mfma_f32_16x16x32_bf16 v[12:15], v[144:147], v[196:199], v[12:15]
	v_mfma_f32_16x16x32_bf16 v[8:11], v[160:163], v[196:199], v[8:11]
	v_mfma_f32_16x16x32_bf16 v[60:63], v[156:159], v[176:179], v[60:63]
	v_mfma_f32_16x16x32_bf16 v[56:59], v[164:167], v[176:179], v[56:59]
	v_mfma_f32_16x16x32_bf16 v[44:47], v[156:159], v[184:187], v[44:47]
	v_mfma_f32_16x16x32_bf16 v[40:43], v[164:167], v[184:187], v[40:43]
	v_mfma_f32_16x16x32_bf16 v[28:31], v[156:159], v[192:195], v[28:31]
	v_mfma_f32_16x16x32_bf16 v[24:27], v[164:167], v[192:195], v[24:27]
	v_mfma_f32_16x16x32_bf16 v[12:15], v[156:159], v[200:203], v[12:15]
	v_mfma_f32_16x16x32_bf16 v[8:11], v[164:167], v[200:203], v[8:11]
	s_setprio 0
	s_barrier
	s_add_u32 s50, s26, 0x200000
	s_addc_u32 s51, s27, 0
	s_add_i32 s52, s45, s34
	v_lshl_add_u64 v[144:145], s[50:51], 0, v[130:131]
	s_mov_b32 m0, s52
	s_nop 0
	global_load_lds_dwordx4 v[144:145], off
	v_lshl_add_u64 v[144:145], s[50:51], 0, v[134:135]
	s_add_i32 m0, s52, 0x2000
	s_nop 0
	global_load_lds_dwordx4 v[144:145], off
	s_waitcnt vmcnt(10)
	s_barrier
	s_setprio 1
	v_mfma_f32_16x16x32_bf16 v[52:55], v[204:207], v[172:175], v[52:55]
	v_mfma_f32_16x16x32_bf16 v[48:51], v[212:215], v[172:175], v[48:51]
	v_mfma_f32_16x16x32_bf16 v[36:39], v[204:207], v[180:183], v[36:39]
	v_mfma_f32_16x16x32_bf16 v[32:35], v[212:215], v[180:183], v[32:35]
	v_mfma_f32_16x16x32_bf16 v[20:23], v[204:207], v[188:191], v[20:23]
	v_mfma_f32_16x16x32_bf16 v[16:19], v[212:215], v[188:191], v[16:19]
	v_mfma_f32_16x16x32_bf16 v[4:7], v[204:207], v[196:199], v[4:7]
	v_mfma_f32_16x16x32_bf16 v[0:3], v[212:215], v[196:199], v[0:3]
	v_mfma_f32_16x16x32_bf16 v[52:55], v[208:211], v[176:179], v[52:55]
	v_mfma_f32_16x16x32_bf16 v[48:51], v[216:219], v[176:179], v[48:51]
	v_mfma_f32_16x16x32_bf16 v[36:39], v[208:211], v[184:187], v[36:39]
	v_mfma_f32_16x16x32_bf16 v[32:35], v[216:219], v[184:187], v[32:35]
	v_mfma_f32_16x16x32_bf16 v[20:23], v[208:211], v[192:195], v[20:23]
	v_mfma_f32_16x16x32_bf16 v[16:19], v[216:219], v[192:195], v[16:19]
	v_mfma_f32_16x16x32_bf16 v[4:7], v[208:211], v[200:203], v[4:7]
	v_mfma_f32_16x16x32_bf16 v[0:3], v[216:219], v[200:203], v[0:3]
	s_setprio 0
	s_add_i32 s50, 0, 0x18000
	v_add_u32_e32 v155, s50, v149
	s_barrier
	ds_read_b128 v[144:147], v155
	ds_read_b128 v[156:159], v155 offset:1024
	ds_read_b128 v[160:163], v155 offset:2048
	ds_read_b128 v[164:167], v155 offset:3072
	s_add_u32 s28, s28, 0x200000
	s_addc_u32 s29, s29, 0
	s_mov_b32 m0, s36
	v_lshl_add_u64 v[204:205], s[28:29], 0, v[128:129]
	ds_read_b128 v[172:175], v152 offset:32768
	ds_read_b128 v[176:179], v152 offset:33792
	ds_read_b128 v[180:183], v152 offset:34816
	ds_read_b128 v[184:187], v152 offset:35840
	ds_read_b128 v[188:191], v152 offset:36864
	ds_read_b128 v[192:195], v152 offset:37888
	ds_read_b128 v[196:199], v152 offset:38912
	ds_read_b128 v[200:203], v152 offset:39936
	global_load_lds_dwordx4 v[204:205], off
	v_lshl_add_u64 v[204:205], s[28:29], 0, v[132:133]
	s_mov_b32 m0, s37
	s_nop 0
	global_load_lds_dwordx4 v[204:205], off
	s_waitcnt vmcnt(10)
	s_waitcnt lgkmcnt(8)
	s_barrier
	s_waitcnt lgkmcnt(0)
	s_setprio 1
	s_waitcnt lgkmcnt(0)
	v_mfma_f32_16x16x32_bf16 v[124:127], v[144:147], v[172:175], v[124:127]
	v_mfma_f32_16x16x32_bf16 v[120:123], v[160:163], v[172:175], v[120:123]
	v_mfma_f32_16x16x32_bf16 v[108:111], v[144:147], v[180:183], v[108:111]
	v_mfma_f32_16x16x32_bf16 v[104:107], v[160:163], v[180:183], v[104:107]
	v_mfma_f32_16x16x32_bf16 v[92:95], v[144:147], v[188:191], v[92:95]
	v_mfma_f32_16x16x32_bf16 v[88:91], v[160:163], v[188:191], v[88:91]
	v_mfma_f32_16x16x32_bf16 v[76:79], v[144:147], v[196:199], v[76:79]
	v_mfma_f32_16x16x32_bf16 v[72:75], v[160:163], v[196:199], v[72:75]
	v_mfma_f32_16x16x32_bf16 v[124:127], v[156:159], v[176:179], v[124:127]
	v_mfma_f32_16x16x32_bf16 v[120:123], v[164:167], v[176:179], v[120:123]
	v_mfma_f32_16x16x32_bf16 v[108:111], v[156:159], v[184:187], v[108:111]
	v_mfma_f32_16x16x32_bf16 v[104:107], v[164:167], v[184:187], v[104:107]
	v_mfma_f32_16x16x32_bf16 v[92:95], v[156:159], v[192:195], v[92:95]
	v_mfma_f32_16x16x32_bf16 v[88:91], v[164:167], v[192:195], v[88:91]
	v_mfma_f32_16x16x32_bf16 v[76:79], v[156:159], v[200:203], v[76:79]
	v_mfma_f32_16x16x32_bf16 v[72:75], v[164:167], v[200:203], v[72:75]
	s_setprio 0
	s_barrier
	s_add_i32 s28, 0, 0x1c000
	s_add_i32 s29, s50, s34
	v_add_u32_e32 v155, s28, v149
	v_lshl_add_u64 v[168:169], v[168:169], 0, s[10:11]
	s_mov_b32 m0, s29
	ds_read_b128 v[204:207], v155
	ds_read_b128 v[208:211], v155 offset:1024
	ds_read_b128 v[212:215], v155 offset:2048
	ds_read_b128 v[216:219], v155 offset:3072
	global_load_lds_dwordx4 v[168:169], off
	v_lshl_add_u64 v[168:169], v[220:221], 0, s[10:11]
	s_add_i32 m0, s29, 0x2000
	s_nop 0
	global_load_lds_dwordx4 v[168:169], off
	s_waitcnt vmcnt(10)
	s_barrier
	s_waitcnt lgkmcnt(0)
	s_setprio 1
	s_waitcnt lgkmcnt(0)
	v_mfma_f32_16x16x32_bf16 v[116:119], v[204:207], v[172:175], v[116:119]
	v_mfma_f32_16x16x32_bf16 v[112:115], v[212:215], v[172:175], v[112:115]
	v_mfma_f32_16x16x32_bf16 v[100:103], v[204:207], v[180:183], v[100:103]
	v_mfma_f32_16x16x32_bf16 v[96:99], v[212:215], v[180:183], v[96:99]
	v_mfma_f32_16x16x32_bf16 v[84:87], v[204:207], v[188:191], v[84:87]
	v_mfma_f32_16x16x32_bf16 v[80:83], v[212:215], v[188:191], v[80:83]
	v_mfma_f32_16x16x32_bf16 v[68:71], v[204:207], v[196:199], v[68:71]
	v_mfma_f32_16x16x32_bf16 v[64:67], v[212:215], v[196:199], v[64:67]
	v_mfma_f32_16x16x32_bf16 v[116:119], v[208:211], v[176:179], v[116:119]
	v_mfma_f32_16x16x32_bf16 v[112:115], v[216:219], v[176:179], v[112:115]
	v_mfma_f32_16x16x32_bf16 v[100:103], v[208:211], v[184:187], v[100:103]
	v_mfma_f32_16x16x32_bf16 v[96:99], v[216:219], v[184:187], v[96:99]
	v_mfma_f32_16x16x32_bf16 v[84:87], v[208:211], v[192:195], v[84:87]
	v_mfma_f32_16x16x32_bf16 v[80:83], v[216:219], v[192:195], v[80:83]
	v_mfma_f32_16x16x32_bf16 v[68:71], v[208:211], v[200:203], v[68:71]
	v_mfma_f32_16x16x32_bf16 v[64:67], v[216:219], v[200:203], v[64:67]
	s_setprio 0
	s_mov_b32 m0, s39
	v_lshl_add_u64 v[168:169], v[222:223], 0, s[10:11]
	s_barrier
	ds_read_b128 v[172:175], v152 offset:49152
	ds_read_b128 v[176:179], v152 offset:50176
	ds_read_b128 v[180:183], v152 offset:51200
	ds_read_b128 v[184:187], v152 offset:52224
	ds_read_b128 v[188:191], v152 offset:53248
	ds_read_b128 v[192:195], v152 offset:54272
	ds_read_b128 v[196:199], v152 offset:55296
	ds_read_b128 v[200:203], v152 offset:56320
	global_load_lds_dwordx4 v[168:169], off
	v_lshl_add_u64 v[168:169], v[224:225], 0, s[10:11]
	s_mov_b32 m0, s40
	s_nop 0
	global_load_lds_dwordx4 v[168:169], off
	s_barrier
	s_waitcnt lgkmcnt(0)
	s_setprio 1
	s_waitcnt lgkmcnt(0)
	v_mfma_f32_16x16x32_bf16 v[60:63], v[144:147], v[172:175], v[60:63]
	v_mfma_f32_16x16x32_bf16 v[56:59], v[160:163], v[172:175], v[56:59]
	v_mfma_f32_16x16x32_bf16 v[44:47], v[144:147], v[180:183], v[44:47]
	v_mfma_f32_16x16x32_bf16 v[40:43], v[160:163], v[180:183], v[40:43]
	v_mfma_f32_16x16x32_bf16 v[28:31], v[144:147], v[188:191], v[28:31]
	v_mfma_f32_16x16x32_bf16 v[24:27], v[160:163], v[188:191], v[24:27]
	v_mfma_f32_16x16x32_bf16 v[12:15], v[144:147], v[196:199], v[12:15]
	v_mfma_f32_16x16x32_bf16 v[8:11], v[160:163], v[196:199], v[8:11]
	v_mfma_f32_16x16x32_bf16 v[60:63], v[156:159], v[176:179], v[60:63]
	v_mfma_f32_16x16x32_bf16 v[56:59], v[164:167], v[176:179], v[56:59]
	v_mfma_f32_16x16x32_bf16 v[44:47], v[156:159], v[184:187], v[44:47]
	v_mfma_f32_16x16x32_bf16 v[40:43], v[164:167], v[184:187], v[40:43]
	v_mfma_f32_16x16x32_bf16 v[28:31], v[156:159], v[192:195], v[28:31]
	v_mfma_f32_16x16x32_bf16 v[24:27], v[164:167], v[192:195], v[24:27]
	v_mfma_f32_16x16x32_bf16 v[12:15], v[156:159], v[200:203], v[12:15]
	v_mfma_f32_16x16x32_bf16 v[8:11], v[164:167], v[200:203], v[8:11]
	s_setprio 0
	s_barrier
	s_add_u32 s26, s26, 0x200080
	s_addc_u32 s27, s27, 0
	s_add_i32 s28, s28, s34
	v_lshl_add_u64 v[144:145], s[26:27], 0, v[130:131]
	s_mov_b32 m0, s28
	s_nop 0
	global_load_lds_dwordx4 v[144:145], off
	v_lshl_add_u64 v[144:145], s[26:27], 0, v[134:135]
	s_add_i32 m0, s28, 0x2000
	s_nop 0
	global_load_lds_dwordx4 v[144:145], off
	s_waitcnt vmcnt(10)
	s_barrier
	s_setprio 1
	v_mfma_f32_16x16x32_bf16 v[52:55], v[204:207], v[172:175], v[52:55]
	v_mfma_f32_16x16x32_bf16 v[48:51], v[212:215], v[172:175], v[48:51]
	v_mfma_f32_16x16x32_bf16 v[36:39], v[204:207], v[180:183], v[36:39]
	v_mfma_f32_16x16x32_bf16 v[32:35], v[212:215], v[180:183], v[32:35]
	v_mfma_f32_16x16x32_bf16 v[20:23], v[204:207], v[188:191], v[20:23]
	v_mfma_f32_16x16x32_bf16 v[16:19], v[212:215], v[188:191], v[16:19]
	v_mfma_f32_16x16x32_bf16 v[4:7], v[204:207], v[196:199], v[4:7]
	v_mfma_f32_16x16x32_bf16 v[0:3], v[212:215], v[196:199], v[0:3]
	v_mfma_f32_16x16x32_bf16 v[52:55], v[208:211], v[176:179], v[52:55]
	v_mfma_f32_16x16x32_bf16 v[48:51], v[216:219], v[176:179], v[48:51]
	v_mfma_f32_16x16x32_bf16 v[36:39], v[208:211], v[184:187], v[36:39]
	v_mfma_f32_16x16x32_bf16 v[32:35], v[216:219], v[184:187], v[32:35]
	v_mfma_f32_16x16x32_bf16 v[20:23], v[208:211], v[192:195], v[20:23]
	v_mfma_f32_16x16x32_bf16 v[16:19], v[216:219], v[192:195], v[16:19]
	v_mfma_f32_16x16x32_bf16 v[4:7], v[208:211], v[200:203], v[4:7]
	v_mfma_f32_16x16x32_bf16 v[0:3], v[216:219], v[200:203], v[0:3]
	s_setprio 0
	s_add_i32 s49, s49, 2
	s_add_u32 s24, s24, 0x100
	s_addc_u32 s25, s25, 0
	s_add_u32 s47, s47, 0x100
	s_addc_u32 s48, s48, 0
	s_cmpk_gt_u32 s49, 0x7d
	s_barrier
	s_cbranch_scc0 .LBB0_1350
	v_lshl_add_u32 v146, s20, 8, v148
	v_ashrrev_i32_e32 v147, 31, v146
	v_lshl_or_b32 v144, s22, 8, v150
	v_lshlrev_b32_e32 v179, 12, v146
	v_lshl_add_u32 v178, v144, 1, v179
	global_load_dwordx4 v[180:183], v178, s[6:7]
	global_load_dwordx4 v[184:187], v178, s[6:7] offset:256
	s_add_u32 s98, s6, 0x10000
	s_addc_u32 s99, s7, 0
	global_load_dwordx4 v[188:191], v178, s[98:99]
	global_load_dwordx4 v[192:195], v178, s[98:99] offset:256
	s_add_u32 s98, s6, 0x20000
	s_addc_u32 s99, s7, 0
	global_load_dwordx4 v[196:199], v178, s[98:99]
	global_load_dwordx4 v[200:203], v178, s[98:99] offset:256
	s_add_u32 s98, s6, 0x30000
	s_addc_u32 s99, s7, 0
	global_load_dwordx4 v[204:207], v178, s[98:99]
	global_load_dwordx4 v[208:211], v178, s[98:99] offset:256
	s_add_u32 s98, s6, 0x80000
	s_addc_u32 s99, s7, 0
	global_load_dwordx4 v[212:215], v178, s[98:99]
	global_load_dwordx4 v[216:219], v178, s[98:99] offset:256
	s_add_u32 s98, s6, 0x90000
	s_addc_u32 s99, s7, 0
	global_load_dwordx4 v[236:239], v178, s[98:99]
	global_load_dwordx4 v[240:243], v178, s[98:99] offset:256
	s_add_u32 s98, s6, 0xa0000
	s_addc_u32 s99, s7, 0
	global_load_dwordx4 v[244:247], v178, s[98:99]
	global_load_dwordx4 v[248:251], v178, s[98:99] offset:256
	s_add_u32 s98, s6, 0xb0000
	s_addc_u32 s99, s7, 0
	global_load_dwordx4 v[220:223], v178, s[98:99]
	global_load_dwordx4 v[252:255], v178, s[98:99] offset:256
	v_lshlrev_b64 v[156:157], 12, v[146:147]
	v_ashrrev_i32_e32 v145, 31, v144
	v_lshl_add_u64 v[156:157], s[6:7], 0, v[156:157]
	v_lshl_add_u64 v[166:167], v[144:145], 1, v[156:157]
	v_and_b32_e32 v156, 64, v154
	v_xor_b32_e32 v155, 16, v154
	v_add_u32_e32 v156, 64, v156
	v_xor_b32_e32 v157, 32, v154
	v_cmp_lt_i32_e32 vcc, v155, v156
	s_waitcnt vmcnt(14)
	v_lshlrev_b32_e32 v168, 16, v180
	v_and_b32_e32 v169, 0xffff0000, v180
	v_lshlrev_b32_e32 v180, 16, v181
	v_and_b32_e32 v181, 0xffff0000, v181
	v_lshlrev_b32_e32 v174, 16, v184
	v_and_b32_e32 v175, 0xffff0000, v184
	v_lshlrev_b32_e32 v184, 16, v185
	v_and_b32_e32 v185, 0xffff0000, v185
	v_cndmask_b32_e32 v155, v154, v155, vcc
	v_cmp_lt_i32_e32 vcc, v157, v156
	v_lshlrev_b32_e32 v172, 16, v182
	v_and_b32_e32 v173, 0xffff0000, v182
	v_lshlrev_b32_e32 v182, 16, v183
	v_and_b32_e32 v183, 0xffff0000, v183
	v_lshlrev_b32_e32 v176, 16, v186
	v_and_b32_e32 v177, 0xffff0000, v186
	v_lshlrev_b32_e32 v186, 16, v187
	v_and_b32_e32 v187, 0xffff0000, v187
	v_pk_add_f32 v[126:127], v[126:127], v[180:181]
	v_pk_add_f32 v[124:125], v[124:125], v[168:169]
	v_pk_add_f32 v[118:119], v[118:119], v[184:185]
	v_pk_add_f32 v[116:117], v[116:117], v[174:175]
	v_cndmask_b32_e32 v157, v154, v157, vcc
	v_pk_add_f32 v[122:123], v[122:123], v[182:183]
	v_pk_add_f32 v[120:121], v[120:121], v[172:173]
	v_pk_add_f32 v[180:181], v[114:115], v[186:187]
	v_pk_add_f32 v[182:183], v[112:113], v[176:177]
	v_mul_f32_e32 v114, v125, v125
	v_mul_f32_e32 v115, v127, v127
	v_cvt_pk_bf16_f32 v112, v124, v125
	v_cvt_pk_bf16_f32 v113, v126, v127
	v_mul_f32_e32 v125, v117, v117
	v_mul_f32_e32 v127, v119, v119
	v_lshlrev_b32_e32 v156, 2, v155
	v_lshlrev_b32_e32 v155, 2, v157
	v_mul_f32_e32 v157, v121, v121
	v_mul_f32_e32 v185, v183, v183
	v_fmac_f32_e32 v114, v124, v124
	v_fmac_f32_e32 v115, v126, v126
	v_fmac_f32_e32 v125, v116, v116
	v_fmac_f32_e32 v127, v118, v118
	v_mul_f32_e32 v184, v123, v123
	v_mul_f32_e32 v186, v181, v181
	v_fmac_f32_e32 v157, v120, v120
	v_fmac_f32_e32 v185, v182, v182
	v_add_f32_e32 v114, v114, v115
	v_add_f32_e32 v115, v125, v127
	v_fmac_f32_e32 v184, v122, v122
	v_fmac_f32_e32 v186, v180, v180
	v_add_f32_e32 v114, v157, v114
	v_add_f32_e32 v115, v185, v115
	v_add_f32_e32 v114, v184, v114
	v_add_f32_e32 v115, v186, v115
	v_add_f32_e32 v124, v114, v115
	ds_bpermute_b32 v125, v156, v124
	v_cvt_pk_bf16_f32 v114, v120, v121
	v_cvt_pk_bf16_f32 v115, v122, v123
	global_store_dwordx4 v[166:167], v[112:115], off
	s_waitcnt lgkmcnt(0)
	s_nop 0
	v_add_f32_e32 v112, v124, v125
	ds_bpermute_b32 v113, v155, v112
	v_cvt_pk_bf16_f32 v114, v116, v117
	v_cvt_pk_bf16_f32 v115, v118, v119
	v_cvt_pk_bf16_f32 v116, v182, v183
	v_cvt_pk_bf16_f32 v117, v180, v181
	global_store_dwordx4 v[166:167], v[114:117], off offset:256
	s_and_saveexec_b64 s[20:21], s[2:3]
	s_cbranch_execz .LBB0_1353
	v_lshl_add_u64 v[114:115], v[146:147], 2, s[8:9]
	s_waitcnt lgkmcnt(0)
	v_add_f32_e32 v112, v112, v113
	global_atomic_add_f32 v[114:115], v112, off
